# v49: + norm_final_w hoisted out of the v-side token loop (removes 7 serialized store/load/wait round trips per token)
# speedup vs baseline: 1.1440x; 1.0222x over previous
; __device__ void phase_gather(const Params& p) {
;   const int tid = threadIdx.x, lane = tid & 63, wid = tid >> 6;
;   unsigned char* ws = p.ws;
;   const unsigned char* ub = ws + OFF_XB;
;   const unsigned char* vb = ws + OFF_XB + 16 * MIB;
;   const float* scales = (const float*)(ws + OFF_SCALES);
;   const int* idxg = (const int*)(ws + OFF_IDX);
;   const float* gg = (const float*)(ws + OFF_G);
;   const float* ssq2 = (const float*)(ws + OFF_SSQ2);
;   const bool b5 = (lane & 32) != 0, b4 = (lane & 16) != 0, b3 = (lane & 8) != 0;
;   const int srcl = ((lane & 1) << 3) | (((lane >> 1) & 1) << 4) | (((lane >> 2) & 1) << 5);
;   for (int t = blockIdx.x * 8 + wid; t < T_TOK; t += gridDim.x * 8) {
;     const int id0 = idxg[(size_t)t * 128 + lane], id1 = idxg[(size_t)t * 128 + 64 + lane];
;     const float g0 = gg[(size_t)t * 128 + lane], g1 = gg[(size_t)t * 128 + 64 + lane];
;     const float su0 = scales[id0], su1 = scales[id1], sv0 = scales[16384 + id0], sv1 = scales[16384 + id1];
;     float* orow = p.out + (size_t)t * DM + lane * 32;
;     const float sx = ((const float*)(ws + OFF_WBUF + 8 * MIB))[t];
;     float sq = (lane < 32) ? ssq2[(size_t)t * 32 + lane] : 0.f;
;     ...
; #pragma unroll
;     for (int q = 0; q < 8; ++q) {
;       f32x4 wf = *(const f32x4*)(p.norm_final_w + lane * 32 + q * 4);
.LBB0_1316:
	s_waitcnt vmcnt(0)
	s_and_saveexec_b64 s[2:3], s[0:1]
	s_cbranch_execz .LBB0_1323
	s_add_u32 s0, s34, 0x1dc90000
	s_addc_u32 s1, s35, 0
	v_writelane_b32 v250, s0, 20
	v_lshlrev_b32_e32 v0, 2, v138
	v_mov_b32_e32 v1, 0
	v_writelane_b32 v250, s1, 21
	s_add_u32 s0, s34, 0xc800000
	s_addc_u32 s1, s35, 0
	v_writelane_b32 v250, s0, 22
	v_cmp_lt_i32_e32 vcc, v89, v84
	v_lshl_add_u64 v[2:3], s[34:35], 0, v[0:1]
	v_writelane_b32 v250, s1, 23
	s_add_u32 s0, s34, 0x17c00000
	s_addc_u32 s1, s35, 0
	v_cndmask_b32_e32 v0, v83, v89, vcc
	v_cmp_lt_i32_e32 vcc, v90, v84
	v_writelane_b32 v250, s0, 24
	v_lshlrev_b32_e32 v126, 2, v0
	v_cndmask_b32_e32 v0, v83, v90, vcc
	v_cmp_lt_i32_e32 vcc, v88, v84
	v_writelane_b32 v250, s1, 25
	v_cmp_gt_u32_e64 s[0:1], 32, v138
	v_lshlrev_b32_e32 v127, 2, v0
	v_cndmask_b32_e32 v0, v83, v88, vcc
	v_cmp_lt_i32_e32 vcc, v87, v84
	v_writelane_b32 v250, s0, 26
	v_lshlrev_b32_e32 v128, 2, v0
	v_cndmask_b32_e32 v0, v83, v87, vcc
	v_cmp_lt_i32_e32 vcc, v86, v84
	v_writelane_b32 v250, s1, 27
	v_lshlrev_b32_e32 v129, 2, v0
	v_cndmask_b32_e32 v0, v83, v86, vcc
	v_cmp_lt_i32_e32 vcc, v85, v84
	s_mov_b64 s[0:1], 0x1da90000
	v_lshlrev_b32_e32 v130, 2, v0
	v_cndmask_b32_e32 v0, v83, v85, vcc
	v_writelane_b32 v250, s68, 28
	v_lshl_add_u64 v[114:115], v[2:3], 0, s[0:1]
	v_lshlrev_b32_e32 v131, 2, v0
	s_mov_b64 s[0:1], 0x1000000
	v_lshlrev_b32_e32 v0, 7, v138
	v_writelane_b32 v250, s69, 29
	v_and_b32_e32 v132, 24, v82
	v_lshl_add_u64 v[116:117], v[72:73], 0, s[0:1]
	v_lshl_add_u64 v[118:119], s[30:31], 0, v[0:1]
	v_lshl_add_u64 v[120:121], s[28:29], 0, v[0:1]
	global_load_dwordx4 v[188:191], v[120:121], off offset:16
	global_load_dwordx4 v[192:195], v[120:121], off offset:32
	global_load_dwordx4 v[196:199], v[120:121], off offset:48
	global_load_dwordx4 v[200:203], v[120:121], off offset:64
	global_load_dwordx4 v[204:207], v[120:121], off offset:80
	global_load_dwordx4 v[208:211], v[120:121], off offset:96
	global_load_dwordx4 v[212:215], v[120:121], off offset:112
	s_mov_b64 s[0:1], 0
	v_mov_b32_e32 v133, 0x358637bd
	s_mov_b32 s55, 0x800000
	s_mov_b32 s33, 0x5010400
	s_mov_b32 s52, 0x7030602
	s_mov_b32 s53, 0x5040100
	s_mov_b32 s54, 0x7060302
	v_writelane_b32 v250, s70, 30
	s_nop 1
	v_writelane_b32 v250, s71, 31

; __device__ void phase_gather(const Params& p) {
;     ...
;       const int idv = half ? id1 : id0;
;       const int pkv = half ? pk1 : pk0;
;       u32x4 rr[3][GROWS];
; #pragma unroll
;       for (int k = 0; k < GROWS; ++k) {
;         const int e = __builtin_amdgcn_readlane(idv, k);
;         rr[0][k] = *(const u32x4*)(vb + (size_t)e * 1024 + lane * 16);
;         const int e2 = __builtin_amdgcn_readlane(idv, GROWS + k);
;         rr[1][k] = *(const u32x4*)(vb + (size_t)e2 * 1024 + lane * 16);
;       }
.LBB0_1321:
	v_cndmask_b32_e64 v1, v124, v122, s[0:1]
	v_cndmask_b32_e64 v0, 0, 1, s[0:1]
	v_readlane_b32 s56, v1, 24
	s_ashr_i32 s57, s56, 31
	s_lshl_b64 s[84:85], s[56:57], 10
	v_readlane_b32 s56, v1, 25
	s_ashr_i32 s57, s56, 31
	s_lshl_b64 s[82:83], s[56:57], 10
	v_readlane_b32 s56, v1, 26
	s_ashr_i32 s57, s56, 31
	s_lshl_b64 s[86:87], s[56:57], 10
	v_readlane_b32 s56, v1, 27
	s_ashr_i32 s57, s56, 31
	s_lshl_b64 s[88:89], s[56:57], 10
	v_readlane_b32 s56, v1, 28
	s_ashr_i32 s57, s56, 31
	s_lshl_b64 s[90:91], s[56:57], 10
	v_readlane_b32 s56, v1, 29
	s_ashr_i32 s57, s56, 31
	s_lshl_b64 s[92:93], s[56:57], 10
	v_readlane_b32 s56, v1, 30
	s_ashr_i32 s57, s56, 31
	s_lshl_b64 s[94:95], s[56:57], 10
	v_readlane_b32 s56, v1, 31
	s_ashr_i32 s57, s56, 31
	s_lshl_b64 s[96:97], s[56:57], 10
	v_readlane_b32 s56, v1, 32
	s_ashr_i32 s57, s56, 31
	s_lshl_b64 s[66:67], s[56:57], 10
	v_readlane_b32 s56, v1, 33
	s_ashr_i32 s57, s56, 31
	s_lshl_b64 s[68:69], s[56:57], 10
	v_readlane_b32 s56, v1, 34
	s_ashr_i32 s57, s56, 31
	s_lshl_b64 s[70:71], s[56:57], 10
	v_readlane_b32 s56, v1, 35
	s_ashr_i32 s57, s56, 31
	s_lshl_b64 s[72:73], s[56:57], 10
	v_readlane_b32 s56, v1, 36
	s_ashr_i32 s57, s56, 31
	s_lshl_b64 s[74:75], s[56:57], 10
	v_readlane_b32 s56, v1, 37
	s_ashr_i32 s57, s56, 31
	s_lshl_b64 s[76:77], s[56:57], 10
	v_readlane_b32 s56, v1, 38
	s_ashr_i32 s57, s56, 31
	s_lshl_b64 s[78:79], s[56:57], 10
	v_readlane_b32 s56, v1, 39
	s_ashr_i32 s57, s56, 31
	s_lshl_b64 s[80:81], s[56:57], 10
	v_readlane_b32 s56, v1, 40
	s_ashr_i32 s57, s56, 31
	s_lshl_b64 s[56:57], s[56:57], 10
	v_writelane_b32 v250, s56, 34
	v_readlane_b32 vcc_lo, v1, 48
	s_ashr_i32 vcc_hi, vcc_lo, 31
	v_writelane_b32 v250, s57, 35
	v_readlane_b32 s56, v1, 41
	s_ashr_i32 s57, s56, 31
	s_lshl_b64 s[56:57], s[56:57], 10
	v_writelane_b32 v250, s56, 36
	s_lshl_b64 vcc, vcc, 10
	v_readlane_b32 s2, v1, 0
	v_writelane_b32 v250, s57, 37
	v_readlane_b32 s56, v1, 42
	s_ashr_i32 s57, s56, 31
	s_lshl_b64 s[56:57], s[56:57], 10
	v_writelane_b32 v250, s56, 38
	s_ashr_i32 s3, s2, 31
	s_lshl_b64 s[50:51], s[2:3], 10
	v_writelane_b32 v250, s57, 39
	v_writelane_b32 v250, vcc_lo, 40
	v_readlane_b32 s2, v1, 8
	s_ashr_i32 s3, s2, 31
	v_writelane_b32 v250, vcc_hi, 41
	v_readlane_b32 vcc_lo, v1, 49
	s_ashr_i32 vcc_hi, vcc_lo, 31
	s_lshl_b64 vcc, vcc, 10
	v_writelane_b32 v250, vcc_lo, 42
	s_lshl_b64 s[48:49], s[2:3], 10
	v_readlane_b32 s2, v1, 1
	v_writelane_b32 v250, vcc_hi, 43
	v_readlane_b32 vcc_lo, v1, 50
	s_ashr_i32 vcc_hi, vcc_lo, 31
	s_lshl_b64 vcc, vcc, 10
	v_writelane_b32 v250, vcc_lo, 44
	s_ashr_i32 s3, s2, 31
	s_lshl_b64 s[46:47], s[2:3], 10
	v_writelane_b32 v250, vcc_hi, 45
	v_readlane_b32 vcc_lo, v1, 51
	s_ashr_i32 vcc_hi, vcc_lo, 31
	s_lshl_b64 vcc, vcc, 10
	v_writelane_b32 v250, vcc_lo, 46
	v_readlane_b32 s2, v1, 9
	s_ashr_i32 s3, s2, 31
	v_writelane_b32 v250, vcc_hi, 47
	v_readlane_b32 vcc_lo, v1, 52
	s_ashr_i32 vcc_hi, vcc_lo, 31
	s_lshl_b64 vcc, vcc, 10
	v_writelane_b32 v250, vcc_lo, 48
	s_lshl_b64 s[44:45], s[2:3], 10
	v_readlane_b32 s2, v1, 2
	v_writelane_b32 v250, vcc_hi, 49
	v_readlane_b32 vcc_lo, v1, 53
	s_ashr_i32 vcc_hi, vcc_lo, 31
	s_lshl_b64 vcc, vcc, 10
	v_writelane_b32 v250, vcc_lo, 50
	s_ashr_i32 s3, s2, 31
	s_lshl_b64 s[42:43], s[2:3], 10
	v_writelane_b32 v250, vcc_hi, 51
	v_readlane_b32 vcc_lo, v1, 54
	s_ashr_i32 vcc_hi, vcc_lo, 31
	s_lshl_b64 vcc, vcc, 10
	v_writelane_b32 v250, vcc_lo, 52
	v_readlane_b32 s2, v1, 10
	s_ashr_i32 s3, s2, 31
	v_writelane_b32 v250, vcc_hi, 53
	v_readlane_b32 vcc_lo, v1, 55
	s_ashr_i32 vcc_hi, vcc_lo, 31
	s_lshl_b64 s[40:41], s[2:3], 10
	v_readlane_b32 s2, v1, 3
	s_lshl_b64 vcc, vcc, 10
	s_ashr_i32 s3, s2, 31
	v_writelane_b32 v250, vcc_lo, 54
	s_lshl_b64 s[38:39], s[2:3], 10
	v_readlane_b32 s2, v1, 11
	v_writelane_b32 v250, vcc_hi, 55
	v_readlane_b32 vcc_lo, v1, 56
	s_ashr_i32 s3, s2, 31
	s_ashr_i32 vcc_hi, vcc_lo, 31
	s_lshl_b64 s[36:37], s[2:3], 10
	v_readlane_b32 s2, v1, 4
	s_lshl_b64 vcc, vcc, 10
	s_ashr_i32 s3, s2, 31
	v_writelane_b32 v250, vcc_lo, 6
	s_lshl_b64 s[34:35], s[2:3], 10
	v_readlane_b32 s2, v1, 12
	v_writelane_b32 v250, vcc_hi, 7
	v_readlane_b32 vcc_lo, v1, 57
	s_ashr_i32 s3, s2, 31
	s_ashr_i32 vcc_hi, vcc_lo, 31
	s_lshl_b64 s[30:31], s[2:3], 10
	v_readlane_b32 s2, v1, 5
	s_lshl_b64 vcc, vcc, 10
	s_ashr_i32 s3, s2, 31
	v_writelane_b32 v250, vcc_lo, 4
	s_lshl_b64 s[28:29], s[2:3], 10
	v_readlane_b32 s2, v1, 13
	v_writelane_b32 v250, vcc_hi, 5
	v_readlane_b32 vcc_lo, v1, 58
	s_ashr_i32 s3, s2, 31
	s_ashr_i32 vcc_hi, vcc_lo, 31
	s_lshl_b64 s[26:27], s[2:3], 10
	v_readlane_b32 s2, v1, 6
	s_lshl_b64 vcc, vcc, 10
	s_ashr_i32 s3, s2, 31
	v_writelane_b32 v250, vcc_lo, 14
	s_lshl_b64 s[24:25], s[2:3], 10
	v_readlane_b32 s2, v1, 14
	v_writelane_b32 v250, vcc_hi, 15
	v_readlane_b32 vcc_lo, v1, 59
	s_ashr_i32 s3, s2, 31
	s_ashr_i32 vcc_hi, vcc_lo, 31
	s_lshl_b64 s[22:23], s[2:3], 10
	v_readlane_b32 s2, v1, 7
	s_lshl_b64 vcc, vcc, 10
	s_ashr_i32 s3, s2, 31
	v_writelane_b32 v250, vcc_lo, 10
	s_lshl_b64 s[20:21], s[2:3], 10
	v_readlane_b32 s2, v1, 15
	v_writelane_b32 v250, vcc_hi, 11
	v_readlane_b32 vcc_lo, v1, 60
	s_ashr_i32 s3, s2, 31
	s_ashr_i32 vcc_hi, vcc_lo, 31
	s_lshl_b64 s[18:19], s[2:3], 10
	v_readlane_b32 s2, v1, 16
	s_lshl_b64 vcc, vcc, 10
	s_ashr_i32 s3, s2, 31
	v_writelane_b32 v250, vcc_lo, 12
	s_lshl_b64 s[16:17], s[2:3], 10
	v_readlane_b32 s2, v1, 17
	v_writelane_b32 v250, vcc_hi, 13
	v_readlane_b32 vcc_lo, v1, 61
	s_ashr_i32 s3, s2, 31
	s_ashr_i32 vcc_hi, vcc_lo, 31
	s_lshl_b64 s[14:15], s[2:3], 10
	v_readlane_b32 s2, v1, 18
	s_lshl_b64 vcc, vcc, 10
	s_ashr_i32 s3, s2, 31
	v_writelane_b32 v250, vcc_lo, 2
	s_lshl_b64 s[12:13], s[2:3], 10
; __device__ void phase_gather(const Params& p) {
;     ...
;       u32x4 rr[3][GROWS];
; #pragma unroll
;       for (int k = 0; k < GROWS; ++k) {
;         const int e = __builtin_amdgcn_readlane(idv, k);
;         rr[0][k] = *(const u32x4*)(vb + (size_t)e * 1024 + lane * 16);
;         const int e2 = __builtin_amdgcn_readlane(idv, GROWS + k);
;         rr[1][k] = *(const u32x4*)(vb + (size_t)e2 * 1024 + lane * 16);
;       }
; #pragma unroll
;       for (int gi = 0; gi < 64 / GROWS; ++gi) {
;         const int j0 = gi * GROWS;
;         if (gi + 2 < 64 / GROWS) {
; #pragma unroll
;           for (int k = 0; k < GROWS; ++k) {
;             const int e = __builtin_amdgcn_readlane(idv, j0 + 2 * GROWS + k);
;             rr[(gi + 2) % 3][k] = *(const u32x4*)(vb + (size_t)e * 1024 + lane * 16);
;           }
;         }
; #pragma unroll
;         for (int sub = 0; sub < GROWS / 4; ++sub) {
;           const int W4 = __builtin_amdgcn_readlane(pkv, j0 + 4 * sub);
; #pragma unroll
;           for (int m = 0; m < 4; ++m) {
;             unsigned lo[4], hi[4];
; #pragma unroll
;             for (int k = 0; k < 4; ++k) {
;               const unsigned w = rr[gi % 3][sub * 4 + k][m];
;               lo[k] = w & 0x0f0f0f0fu;
;               hi[k] = (w >> 4) & 0x0f0f0f0fu;
;             }
;             {
;               const unsigned p01l = __builtin_amdgcn_perm(lo[1], lo[0], 0x05010400u), p01h = __builtin_amdgcn_perm(lo[1], lo[0], 0x07030602u);
;               const unsigned p23l = __builtin_amdgcn_perm(lo[3], lo[2], 0x05010400u), p23h = __builtin_amdgcn_perm(lo[3], lo[2], 0x07030602u);
;               acc[m * 8 + 0] = __builtin_amdgcn_sdot4((int)__builtin_amdgcn_perm(p23l, p01l, 0x05040100u), W4, acc[m * 8 + 0], false);
;               acc[m * 8 + 1] = __builtin_amdgcn_sdot4((int)__builtin_amdgcn_perm(p23l, p01l, 0x07060302u), W4, acc[m * 8 + 1], false);
;               acc[m * 8 + 2] = __builtin_amdgcn_sdot4((int)__builtin_amdgcn_perm(p23h, p01h, 0x05040100u), W4, acc[m * 8 + 2], false);
;               acc[m * 8 + 3] = __builtin_amdgcn_sdot4((int)__builtin_amdgcn_perm(p23h, p01h, 0x07060302u), W4, acc[m * 8 + 3], false);
;             }
;             {
;               const unsigned p01l = __builtin_amdgcn_perm(hi[1], hi[0], 0x05010400u), p01h = __builtin_amdgcn_perm(hi[1], hi[0], 0x07030602u);
	v_readlane_b32 s2, v1, 19
	v_writelane_b32 v250, vcc_hi, 3
	v_readlane_b32 vcc_lo, v1, 62
	s_ashr_i32 s3, s2, 31
	s_ashr_i32 vcc_hi, vcc_lo, 31
	s_lshl_b64 s[10:11], s[2:3], 10
	v_readlane_b32 s2, v1, 20
	s_lshl_b64 vcc, vcc, 10
	s_ashr_i32 s3, s2, 31
	v_writelane_b32 v250, vcc_lo, 0
	s_lshl_b64 s[8:9], s[2:3], 10
	v_readlane_b32 s2, v1, 21
	v_writelane_b32 v250, vcc_hi, 1
	v_readlane_b32 vcc_lo, v1, 63
	s_ashr_i32 s3, s2, 31
	s_ashr_i32 vcc_hi, vcc_lo, 31
	s_lshl_b64 s[6:7], s[2:3], 10
	v_readlane_b32 s2, v1, 22
	s_lshl_b64 vcc, vcc, 10
	s_ashr_i32 s3, s2, 31
	v_writelane_b32 v250, vcc_lo, 16
	s_lshl_b64 s[4:5], s[2:3], 10
	v_readlane_b32 s2, v1, 23
	v_readlane_b32 s56, v1, 43
	v_readlane_b32 s58, v1, 44
	v_readlane_b32 s60, v1, 45
	v_readlane_b32 s62, v1, 46
	v_readlane_b32 s64, v1, 47
	v_writelane_b32 v250, vcc_hi, 17
	v_cmp_ne_u32_e32 vcc, 1, v0
	v_lshl_add_u64 v[0:1], v[116:117], 0, s[50:51]
	global_load_dwordx4 v[64:67], v[0:1], off
	v_lshl_add_u64 v[0:1], v[116:117], 0, s[48:49]
	global_load_dwordx4 v[80:83], v[0:1], off
	v_lshl_add_u64 v[0:1], v[116:117], 0, s[46:47]
	global_load_dwordx4 v[68:71], v[0:1], off
	v_lshl_add_u64 v[0:1], v[116:117], 0, s[44:45]
	global_load_dwordx4 v[84:87], v[0:1], off
	v_lshl_add_u64 v[0:1], v[116:117], 0, s[42:43]
	global_load_dwordx4 v[72:75], v[0:1], off
	v_lshl_add_u64 v[0:1], v[116:117], 0, s[40:41]
	global_load_dwordx4 v[88:91], v[0:1], off
	v_lshl_add_u64 v[0:1], v[116:117], 0, s[38:39]
	global_load_dwordx4 v[76:79], v[0:1], off
	v_lshl_add_u64 v[0:1], v[116:117], 0, s[36:37]
	global_load_dwordx4 v[92:95], v[0:1], off
	v_lshl_add_u64 v[0:1], v[116:117], 0, s[34:35]
	global_load_dwordx4 v[48:51], v[0:1], off
	v_lshl_add_u64 v[0:1], v[116:117], 0, s[30:31]
	global_load_dwordx4 v[32:35], v[0:1], off
	v_lshl_add_u64 v[0:1], v[116:117], 0, s[28:29]
	global_load_dwordx4 v[52:55], v[0:1], off
	v_lshl_add_u64 v[0:1], v[116:117], 0, s[26:27]
	global_load_dwordx4 v[36:39], v[0:1], off
	v_lshl_add_u64 v[0:1], v[116:117], 0, s[24:25]
	global_load_dwordx4 v[56:59], v[0:1], off
	v_lshl_add_u64 v[0:1], v[116:117], 0, s[22:23]
	global_load_dwordx4 v[40:43], v[0:1], off
	v_lshl_add_u64 v[0:1], v[116:117], 0, s[20:21]
	global_load_dwordx4 v[60:63], v[0:1], off
	v_cndmask_b32_e64 v170, v169, v168, s[0:1]
	v_lshl_add_u64 v[0:1], v[116:117], 0, s[18:19]
	v_readlane_b32 s0, v170, 0
	global_load_dwordx4 v[44:47], v[0:1], off
	s_ashr_i32 s63, s62, 31
	s_lshl_b64 s[62:63], s[62:63], 10
	s_ashr_i32 s65, s64, 31
	s_lshl_b64 s[64:65], s[64:65], 10
	s_ashr_i32 s3, s2, 31
	s_lshl_b64 s[2:3], s[2:3], 10
	s_ashr_i32 s57, s56, 31
	s_lshl_b64 s[56:57], s[56:57], 10
	s_ashr_i32 s59, s58, 31
	s_ashr_i32 s61, s60, 31
	s_lshl_b64 s[58:59], s[58:59], 10
	s_lshl_b64 s[60:61], s[60:61], 10
	s_and_b64 vcc, exec, vcc
	s_waitcnt vmcnt(15)
	v_and_b32_e32 v96, 0xf0f0f0f, v64
	v_lshrrev_b32_e32 v64, 4, v64
	v_and_b32_e32 v64, 0xf0f0f0f, v64
	s_waitcnt vmcnt(13)
	v_and_b32_e32 v97, 0xf0f0f0f, v68
	v_perm_b32 v100, v97, v96, s33
	v_perm_b32 v96, v97, v96, s52
	v_lshrrev_b32_e32 v68, 4, v68
	s_waitcnt vmcnt(11)
	v_and_b32_e32 v98, 0xf0f0f0f, v72
	v_lshrrev_b32_e32 v72, 4, v72
	v_and_b32_e32 v68, 0xf0f0f0f, v68
	v_and_b32_e32 v72, 0xf0f0f0f, v72
	s_waitcnt vmcnt(9)
	v_and_b32_e32 v99, 0xf0f0f0f, v76
	v_perm_b32 v97, v99, v98, s33
	v_lshrrev_b32_e32 v76, 4, v76
	v_perm_b32 v98, v99, v98, s52
	v_perm_b32 v99, v97, v100, s53
	v_perm_b32 v97, v97, v100, s54
	v_and_b32_e32 v76, 0xf0f0f0f, v76
	v_dot4c_i32_i8_e32 v164, s0, v97
	v_perm_b32 v97, v98, v96, s53
	v_perm_b32 v96, v98, v96, s54
	v_dot4c_i32_i8_e32 v162, s0, v96
	v_perm_b32 v96, v68, v64, s33
	v_perm_b32 v64, v68, v64, s52
	v_perm_b32 v68, v76, v72, s33
	v_perm_b32 v72, v76, v72, s52
	v_perm_b32 v76, v68, v96, s53
	v_perm_b32 v68, v68, v96, s54
	v_dot4c_i32_i8_e32 v160, s0, v68
	v_perm_b32 v68, v72, v64, s53
	v_perm_b32 v64, v72, v64, s54
	v_dot4c_i32_i8_e32 v159, s0, v76
	v_dot4c_i32_i8_e32 v157, s0, v68
	v_dot4c_i32_i8_e32 v158, s0, v64
	v_and_b32_e32 v64, 0xf0f0f0f, v65
	v_and_b32_e32 v68, 0xf0f0f0f, v69
	v_and_b32_e32 v72, 0xf0f0f0f, v73
	v_and_b32_e32 v76, 0xf0f0f0f, v77
	v_perm_b32 v96, v68, v64, s33
	v_perm_b32 v64, v68, v64, s52
	v_perm_b32 v68, v76, v72, s33
	v_lshrrev_b32_e32 v65, 4, v65
	v_lshrrev_b32_e32 v69, 4, v69
	v_lshrrev_b32_e32 v73, 4, v73
	v_lshrrev_b32_e32 v77, 4, v77
	v_perm_b32 v72, v76, v72, s52
	v_perm_b32 v76, v68, v96, s53
	v_perm_b32 v68, v68, v96, s54
	v_and_b32_e32 v65, 0xf0f0f0f, v65
	v_and_b32_e32 v69, 0xf0f0f0f, v69
	v_and_b32_e32 v73, 0xf0f0f0f, v73
	v_and_b32_e32 v77, 0xf0f0f0f, v77
	v_dot4c_i32_i8_e32 v154, s0, v68
	v_perm_b32 v68, v72, v64, s53
	v_perm_b32 v64, v72, v64, s54
	v_dot4c_i32_i8_e32 v149, s0, v68
	v_dot4c_i32_i8_e32 v150, s0, v64
	v_perm_b32 v64, v69, v65, s33
	v_perm_b32 v68, v77, v73, s33
	v_perm_b32 v65, v69, v65, s52
	v_perm_b32 v69, v77, v73, s52
	v_perm_b32 v72, v68, v64, s53
	v_perm_b32 v64, v68, v64, s54
	v_dot4c_i32_i8_e32 v146, s0, v64
	v_perm_b32 v64, v69, v65, s53
	v_dot4c_i32_i8_e32 v155, s0, v64
	v_perm_b32 v64, v69, v65, s54
	v_dot4c_i32_i8_e32 v144, s0, v72
	v_dot4c_i32_i8_e32 v156, s0, v64
	v_and_b32_e32 v64, 0xf0f0f0f, v66
	v_lshrrev_b32_e32 v65, 4, v66
	v_and_b32_e32 v66, 0xf0f0f0f, v70
	v_and_b32_e32 v69, 0xf0f0f0f, v74
	v_and_b32_e32 v72, 0xf0f0f0f, v78
	v_lshrrev_b32_e32 v68, 4, v70
	v_lshrrev_b32_e32 v70, 4, v74
	v_perm_b32 v74, v66, v64, s33
	v_perm_b32 v64, v66, v64, s52
	v_perm_b32 v66, v72, v69, s33
	v_lshrrev_b32_e32 v73, 4, v78
	v_perm_b32 v69, v72, v69, s52
	v_perm_b32 v72, v66, v74, s53
	v_perm_b32 v66, v66, v74, s54
	v_and_b32_e32 v65, 0xf0f0f0f, v65
	v_and_b32_e32 v68, 0xf0f0f0f, v68
	v_and_b32_e32 v70, 0xf0f0f0f, v70
; __device__ void phase_gather(const Params& p) {
;     ...
;         for (int sub = 0; sub < GROWS / 4; ++sub) {
;           const int W4 = __builtin_amdgcn_readlane(pkv, j0 + 4 * sub);
; #pragma unroll
;           for (int m = 0; m < 4; ++m) {
;             unsigned lo[4], hi[4];
; #pragma unroll
;             for (int k = 0; k < 4; ++k) {
;               const unsigned w = rr[gi % 3][sub * 4 + k][m];
;               lo[k] = w & 0x0f0f0f0fu;
;               hi[k] = (w >> 4) & 0x0f0f0f0fu;
;             }
;             {
;               const unsigned p01l = __builtin_amdgcn_perm(lo[1], lo[0], 0x05010400u), p01h = __builtin_amdgcn_perm(lo[1], lo[0], 0x07030602u);
;               const unsigned p23l = __builtin_amdgcn_perm(lo[3], lo[2], 0x05010400u), p23h = __builtin_amdgcn_perm(lo[3], lo[2], 0x07030602u);
;               acc[m * 8 + 0] = __builtin_amdgcn_sdot4((int)__builtin_amdgcn_perm(p23l, p01l, 0x05040100u), W4, acc[m * 8 + 0], false);
;               acc[m * 8 + 1] = __builtin_amdgcn_sdot4((int)__builtin_amdgcn_perm(p23l, p01l, 0x07060302u), W4, acc[m * 8 + 1], false);
;               acc[m * 8 + 2] = __builtin_amdgcn_sdot4((int)__builtin_amdgcn_perm(p23h, p01h, 0x05040100u), W4, acc[m * 8 + 2], false);
;               acc[m * 8 + 3] = __builtin_amdgcn_sdot4((int)__builtin_amdgcn_perm(p23h, p01h, 0x07060302u), W4, acc[m * 8 + 3], false);
;             }
;             {
;               const unsigned p01l = __builtin_amdgcn_perm(hi[1], hi[0], 0x05010400u), p01h = __builtin_amdgcn_perm(hi[1], hi[0], 0x07030602u);
;               const unsigned p23l = __builtin_amdgcn_perm(hi[3], hi[2], 0x05010400u), p23h = __builtin_amdgcn_perm(hi[3], hi[2], 0x07030602u);
;               acc[m * 8 + 4] = __builtin_amdgcn_sdot4((int)__builtin_amdgcn_perm(p23l, p01l, 0x05040100u), W4, acc[m * 8 + 4], false);
;               acc[m * 8 + 5] = __builtin_amdgcn_sdot4((int)__builtin_amdgcn_perm(p23l, p01l, 0x07060302u), W4, acc[m * 8 + 5], false);
;               acc[m * 8 + 6] = __builtin_amdgcn_sdot4((int)__builtin_amdgcn_perm(p23h, p01h, 0x05040100u), W4, acc[m * 8 + 6], false);
;               acc[m * 8 + 7] = __builtin_amdgcn_sdot4((int)__builtin_amdgcn_perm(p23h, p01h, 0x07060302u), W4, acc[m * 8 + 7], false);
;             }
	v_and_b32_e32 v73, 0xf0f0f0f, v73
	v_dot4c_i32_i8_e32 v153, s0, v66
	v_perm_b32 v66, v69, v64, s53
	v_perm_b32 v64, v69, v64, s54
	v_dot4c_i32_i8_e32 v147, s0, v66
	v_dot4c_i32_i8_e32 v148, s0, v64
	v_perm_b32 v64, v68, v65, s33
	v_perm_b32 v66, v73, v70, s33
	v_perm_b32 v65, v68, v65, s52
	v_perm_b32 v68, v73, v70, s52
	v_perm_b32 v69, v66, v64, s53
	v_perm_b32 v64, v66, v64, s54
	v_dot4c_i32_i8_e32 v145, s0, v64
	v_perm_b32 v64, v68, v65, s53
	v_dot4c_i32_i8_e32 v141, s0, v64
	v_perm_b32 v64, v68, v65, s54
	v_dot4c_i32_i8_e32 v142, s0, v64
	v_and_b32_e32 v64, 0xf0f0f0f, v67
	v_and_b32_e32 v66, 0xf0f0f0f, v71
	v_and_b32_e32 v68, 0xf0f0f0f, v75
	v_and_b32_e32 v70, 0xf0f0f0f, v79
	v_dot4c_i32_i8_e32 v151, s0, v72
	v_perm_b32 v72, v66, v64, s33
	v_perm_b32 v64, v66, v64, s52
	v_perm_b32 v66, v70, v68, s33
	v_dot4c_i32_i8_e32 v143, s0, v69
	v_lshrrev_b32_e32 v65, 4, v67
	v_lshrrev_b32_e32 v67, 4, v71
	v_lshrrev_b32_e32 v69, 4, v75
	v_lshrrev_b32_e32 v71, 4, v79
	v_perm_b32 v68, v70, v68, s52
	v_perm_b32 v70, v66, v72, s53
	v_perm_b32 v66, v66, v72, s54
	v_and_b32_e32 v65, 0xf0f0f0f, v65
	v_and_b32_e32 v67, 0xf0f0f0f, v67
	v_and_b32_e32 v69, 0xf0f0f0f, v69
	v_and_b32_e32 v71, 0xf0f0f0f, v71
	v_dot4c_i32_i8_e32 v140, s0, v66
	v_perm_b32 v66, v68, v64, s53
	v_perm_b32 v64, v68, v64, s54
	v_dot4c_i32_i8_e32 v137, s0, v66
	v_dot4c_i32_i8_e32 v139, s0, v64
	v_perm_b32 v64, v67, v65, s33
	v_perm_b32 v66, v71, v69, s33
	v_perm_b32 v65, v67, v65, s52
	v_perm_b32 v67, v71, v69, s52
	v_perm_b32 v68, v66, v64, s53
	v_perm_b32 v64, v66, v64, s54
	v_dot4c_i32_i8_e32 v135, s0, v64
	v_perm_b32 v64, v67, v65, s53
	v_dot4c_i32_i8_e32 v123, s0, v64
	v_perm_b32 v64, v67, v65, s54
	v_dot4c_i32_i8_e32 v125, s0, v64
	s_waitcnt vmcnt(7)
	v_and_b32_e32 v64, 0xf0f0f0f, v48
	s_waitcnt vmcnt(5)
	v_and_b32_e32 v65, 0xf0f0f0f, v52
	s_waitcnt vmcnt(3)
	v_and_b32_e32 v66, 0xf0f0f0f, v56
	s_waitcnt vmcnt(1)
	v_and_b32_e32 v67, 0xf0f0f0f, v60
	v_dot4c_i32_i8_e32 v134, s0, v68
	v_perm_b32 v68, v65, v64, s33
	v_perm_b32 v64, v65, v64, s52
	v_perm_b32 v65, v67, v66, s33
	v_dot4c_i32_i8_e32 v163, s0, v99
	v_dot4c_i32_i8_e32 v161, s0, v97
	v_dot4c_i32_i8_e32 v152, s0, v76
	v_dot4c_i32_i8_e32 v136, s0, v70
	v_readlane_b32 s0, v170, 4
	v_lshrrev_b32_e32 v48, 4, v48
	v_lshrrev_b32_e32 v52, 4, v52
	v_lshrrev_b32_e32 v56, 4, v56
	v_lshrrev_b32_e32 v60, 4, v60
	v_perm_b32 v66, v67, v66, s52
	v_perm_b32 v67, v65, v68, s53
	v_perm_b32 v65, v65, v68, s54
	v_and_b32_e32 v48, 0xf0f0f0f, v48
	v_and_b32_e32 v52, 0xf0f0f0f, v52
	v_and_b32_e32 v56, 0xf0f0f0f, v56
	v_and_b32_e32 v60, 0xf0f0f0f, v60
	v_dot4c_i32_i8_e32 v164, s0, v65
	v_perm_b32 v65, v66, v64, s53
	v_perm_b32 v64, v66, v64, s54
	v_dot4c_i32_i8_e32 v162, s0, v64
	v_perm_b32 v64, v52, v48, s33
	v_perm_b32 v48, v52, v48, s52
	v_perm_b32 v52, v60, v56, s33
	v_perm_b32 v56, v60, v56, s52
	v_perm_b32 v60, v52, v64, s53
	v_perm_b32 v52, v52, v64, s54
	v_dot4c_i32_i8_e32 v160, s0, v52
	v_perm_b32 v52, v56, v48, s53
	v_perm_b32 v48, v56, v48, s54
	v_dot4c_i32_i8_e32 v159, s0, v60
	v_dot4c_i32_i8_e32 v157, s0, v52
	v_dot4c_i32_i8_e32 v158, s0, v48
	v_and_b32_e32 v48, 0xf0f0f0f, v49
	v_and_b32_e32 v52, 0xf0f0f0f, v53
	v_and_b32_e32 v56, 0xf0f0f0f, v57
	v_and_b32_e32 v60, 0xf0f0f0f, v61
	v_perm_b32 v64, v52, v48, s33
	v_perm_b32 v48, v52, v48, s52
	v_perm_b32 v52, v60, v56, s33
	v_lshrrev_b32_e32 v49, 4, v49
	v_lshrrev_b32_e32 v53, 4, v53
	v_lshrrev_b32_e32 v57, 4, v57
	v_lshrrev_b32_e32 v61, 4, v61
	v_perm_b32 v56, v60, v56, s52
	v_perm_b32 v60, v52, v64, s53
	v_perm_b32 v52, v52, v64, s54
	v_and_b32_e32 v49, 0xf0f0f0f, v49
	v_and_b32_e32 v53, 0xf0f0f0f, v53
	v_and_b32_e32 v57, 0xf0f0f0f, v57
	v_and_b32_e32 v61, 0xf0f0f0f, v61
	v_dot4c_i32_i8_e32 v154, s0, v52
	v_perm_b32 v52, v56, v48, s53
	v_perm_b32 v48, v56, v48, s54
	v_dot4c_i32_i8_e32 v149, s0, v52
	v_dot4c_i32_i8_e32 v150, s0, v48
	v_perm_b32 v48, v53, v49, s33
	v_perm_b32 v52, v61, v57, s33
	v_perm_b32 v49, v53, v49, s52
	v_perm_b32 v53, v61, v57, s52
	v_perm_b32 v56, v52, v48, s53
	v_perm_b32 v48, v52, v48, s54
	v_dot4c_i32_i8_e32 v146, s0, v48
	v_perm_b32 v48, v53, v49, s53
	v_dot4c_i32_i8_e32 v155, s0, v48
	v_perm_b32 v48, v53, v49, s54
	v_dot4c_i32_i8_e32 v144, s0, v56
	v_dot4c_i32_i8_e32 v156, s0, v48
	v_and_b32_e32 v48, 0xf0f0f0f, v50
	v_lshrrev_b32_e32 v49, 4, v50
	v_and_b32_e32 v50, 0xf0f0f0f, v54
	v_and_b32_e32 v53, 0xf0f0f0f, v58
	v_and_b32_e32 v56, 0xf0f0f0f, v62
	v_lshrrev_b32_e32 v52, 4, v54
	v_lshrrev_b32_e32 v54, 4, v58
	v_perm_b32 v58, v50, v48, s33
	v_perm_b32 v48, v50, v48, s52
	v_perm_b32 v50, v56, v53, s33
	v_lshrrev_b32_e32 v57, 4, v62
	v_perm_b32 v53, v56, v53, s52
	v_perm_b32 v56, v50, v58, s53
	v_perm_b32 v50, v50, v58, s54
	v_and_b32_e32 v49, 0xf0f0f0f, v49
	v_and_b32_e32 v52, 0xf0f0f0f, v52
	v_and_b32_e32 v54, 0xf0f0f0f, v54
	v_and_b32_e32 v57, 0xf0f0f0f, v57
	v_dot4c_i32_i8_e32 v153, s0, v50
	v_perm_b32 v50, v53, v48, s53
	v_perm_b32 v48, v53, v48, s54
	v_dot4c_i32_i8_e32 v147, s0, v50
	v_dot4c_i32_i8_e32 v148, s0, v48
	v_perm_b32 v48, v52, v49, s33
	v_perm_b32 v50, v57, v54, s33
	v_perm_b32 v49, v52, v49, s52
	v_perm_b32 v52, v57, v54, s52
	v_perm_b32 v53, v50, v48, s53
	v_perm_b32 v48, v50, v48, s54
	v_dot4c_i32_i8_e32 v145, s0, v48
	v_perm_b32 v48, v52, v49, s53
	v_dot4c_i32_i8_e32 v141, s0, v48
	v_perm_b32 v48, v52, v49, s54
	v_dot4c_i32_i8_e32 v142, s0, v48
	v_and_b32_e32 v48, 0xf0f0f0f, v51
	v_and_b32_e32 v50, 0xf0f0f0f, v55
	v_and_b32_e32 v52, 0xf0f0f0f, v59
	v_and_b32_e32 v54, 0xf0f0f0f, v63
	v_dot4c_i32_i8_e32 v151, s0, v56
	v_perm_b32 v56, v50, v48, s33
	v_perm_b32 v48, v50, v48, s52
	v_perm_b32 v50, v54, v52, s33
	v_dot4c_i32_i8_e32 v143, s0, v53
; __device__ void phase_gather(const Params& p) {
;     ...
;         if (gi + 2 < 64 / GROWS) {
; #pragma unroll
;           for (int k = 0; k < GROWS; ++k) {
;             const int e = __builtin_amdgcn_readlane(idv, j0 + 2 * GROWS + k);
;             rr[(gi + 2) % 3][k] = *(const u32x4*)(vb + (size_t)e * 1024 + lane * 16);
;           }
;         }
; #pragma unroll
;         for (int sub = 0; sub < GROWS / 4; ++sub) {
;           const int W4 = __builtin_amdgcn_readlane(pkv, j0 + 4 * sub);
; #pragma unroll
;           for (int m = 0; m < 4; ++m) {
;             unsigned lo[4], hi[4];
; #pragma unroll
;             for (int k = 0; k < 4; ++k) {
;               const unsigned w = rr[gi % 3][sub * 4 + k][m];
;               lo[k] = w & 0x0f0f0f0fu;
;               hi[k] = (w >> 4) & 0x0f0f0f0fu;
;             }
;             {
;               const unsigned p01l = __builtin_amdgcn_perm(lo[1], lo[0], 0x05010400u), p01h = __builtin_amdgcn_perm(lo[1], lo[0], 0x07030602u);
;               const unsigned p23l = __builtin_amdgcn_perm(lo[3], lo[2], 0x05010400u), p23h = __builtin_amdgcn_perm(lo[3], lo[2], 0x07030602u);
;               acc[m * 8 + 0] = __builtin_amdgcn_sdot4((int)__builtin_amdgcn_perm(p23l, p01l, 0x05040100u), W4, acc[m * 8 + 0], false);
;               acc[m * 8 + 1] = __builtin_amdgcn_sdot4((int)__builtin_amdgcn_perm(p23l, p01l, 0x07060302u), W4, acc[m * 8 + 1], false);
;               acc[m * 8 + 2] = __builtin_amdgcn_sdot4((int)__builtin_amdgcn_perm(p23h, p01h, 0x05040100u), W4, acc[m * 8 + 2], false);
;               acc[m * 8 + 3] = __builtin_amdgcn_sdot4((int)__builtin_amdgcn_perm(p23h, p01h, 0x07060302u), W4, acc[m * 8 + 3], false);
;             }
;             {
;               const unsigned p01l = __builtin_amdgcn_perm(hi[1], hi[0], 0x05010400u), p01h = __builtin_amdgcn_perm(hi[1], hi[0], 0x07030602u);
;               const unsigned p23l = __builtin_amdgcn_perm(hi[3], hi[2], 0x05010400u), p23h = __builtin_amdgcn_perm(hi[3], hi[2], 0x07030602u);
;               acc[m * 8 + 4] = __builtin_amdgcn_sdot4((int)__builtin_amdgcn_perm(p23l, p01l, 0x05040100u), W4, acc[m * 8 + 4], false);
;               acc[m * 8 + 5] = __builtin_amdgcn_sdot4((int)__builtin_amdgcn_perm(p23l, p01l, 0x07060302u), W4, acc[m * 8 + 5], false);
;               acc[m * 8 + 6] = __builtin_amdgcn_sdot4((int)__builtin_amdgcn_perm(p23h, p01h, 0x05040100u), W4, acc[m * 8 + 6], false);
	v_lshrrev_b32_e32 v49, 4, v51
	v_lshrrev_b32_e32 v51, 4, v55
	v_lshrrev_b32_e32 v53, 4, v59
	v_lshrrev_b32_e32 v55, 4, v63
	v_perm_b32 v52, v54, v52, s52
	v_perm_b32 v54, v50, v56, s53
	v_perm_b32 v50, v50, v56, s54
	v_and_b32_e32 v49, 0xf0f0f0f, v49
	v_and_b32_e32 v51, 0xf0f0f0f, v51
	v_and_b32_e32 v53, 0xf0f0f0f, v53
	v_and_b32_e32 v55, 0xf0f0f0f, v55
	v_dot4c_i32_i8_e32 v140, s0, v50
	v_perm_b32 v50, v52, v48, s53
	v_perm_b32 v48, v52, v48, s54
	v_dot4c_i32_i8_e32 v137, s0, v50
	v_dot4c_i32_i8_e32 v139, s0, v48
	v_perm_b32 v48, v51, v49, s33
	v_perm_b32 v50, v55, v53, s33
	v_perm_b32 v49, v51, v49, s52
	v_perm_b32 v51, v55, v53, s52
	v_perm_b32 v52, v50, v48, s53
	v_perm_b32 v48, v50, v48, s54
	v_dot4c_i32_i8_e32 v135, s0, v48
	v_perm_b32 v48, v51, v49, s53
	v_and_b32_e32 v96, 0xf0f0f0f, v80
	v_and_b32_e32 v97, 0xf0f0f0f, v84
	v_and_b32_e32 v98, 0xf0f0f0f, v88
	v_and_b32_e32 v99, 0xf0f0f0f, v92
	v_dot4c_i32_i8_e32 v123, s0, v48
	v_perm_b32 v48, v51, v49, s54
	v_perm_b32 v100, v97, v96, s33
	v_perm_b32 v96, v97, v96, s52
	v_perm_b32 v97, v99, v98, s33
	v_dot4c_i32_i8_e32 v163, s0, v67
	v_dot4c_i32_i8_e32 v161, s0, v65
	v_dot4c_i32_i8_e32 v152, s0, v60
	v_dot4c_i32_i8_e32 v136, s0, v54
	v_dot4c_i32_i8_e32 v134, s0, v52
	v_dot4c_i32_i8_e32 v125, s0, v48
	v_readlane_b32 s0, v170, 8
	v_lshrrev_b32_e32 v80, 4, v80
	v_lshrrev_b32_e32 v84, 4, v84
	v_lshrrev_b32_e32 v88, 4, v88
	v_lshrrev_b32_e32 v92, 4, v92
	v_perm_b32 v98, v99, v98, s52
	v_perm_b32 v99, v97, v100, s53
	v_perm_b32 v97, v97, v100, s54
	v_and_b32_e32 v80, 0xf0f0f0f, v80
	v_and_b32_e32 v84, 0xf0f0f0f, v84
	v_and_b32_e32 v88, 0xf0f0f0f, v88
	v_and_b32_e32 v92, 0xf0f0f0f, v92
	v_dot4c_i32_i8_e32 v164, s0, v97
	v_perm_b32 v97, v98, v96, s53
	v_perm_b32 v96, v98, v96, s54
	v_dot4c_i32_i8_e32 v162, s0, v96
	v_perm_b32 v96, v84, v80, s33
	v_perm_b32 v80, v84, v80, s52
	v_perm_b32 v84, v92, v88, s33
	v_perm_b32 v88, v92, v88, s52
	v_perm_b32 v92, v84, v96, s53
	v_perm_b32 v84, v84, v96, s54
	v_dot4c_i32_i8_e32 v160, s0, v84
	v_perm_b32 v84, v88, v80, s53
	v_perm_b32 v80, v88, v80, s54
	v_dot4c_i32_i8_e32 v159, s0, v92
	v_dot4c_i32_i8_e32 v157, s0, v84
	v_dot4c_i32_i8_e32 v158, s0, v80
	v_and_b32_e32 v80, 0xf0f0f0f, v81
	v_and_b32_e32 v84, 0xf0f0f0f, v85
	v_and_b32_e32 v88, 0xf0f0f0f, v89
	v_and_b32_e32 v92, 0xf0f0f0f, v93
	v_perm_b32 v96, v84, v80, s33
	v_perm_b32 v80, v84, v80, s52
	v_perm_b32 v84, v92, v88, s33
	v_lshrrev_b32_e32 v81, 4, v81
	v_lshrrev_b32_e32 v85, 4, v85
	v_lshrrev_b32_e32 v89, 4, v89
	v_lshrrev_b32_e32 v93, 4, v93
	v_perm_b32 v88, v92, v88, s52
	v_perm_b32 v92, v84, v96, s53
	v_perm_b32 v84, v84, v96, s54
	v_and_b32_e32 v81, 0xf0f0f0f, v81
	v_and_b32_e32 v85, 0xf0f0f0f, v85
	v_and_b32_e32 v89, 0xf0f0f0f, v89
	v_and_b32_e32 v93, 0xf0f0f0f, v93
	v_dot4c_i32_i8_e32 v154, s0, v84
	v_perm_b32 v84, v88, v80, s53
	v_perm_b32 v80, v88, v80, s54
	v_dot4c_i32_i8_e32 v149, s0, v84
	v_dot4c_i32_i8_e32 v150, s0, v80
	v_perm_b32 v80, v85, v81, s33
	v_perm_b32 v84, v93, v89, s33
	v_perm_b32 v81, v85, v81, s52
	v_perm_b32 v85, v93, v89, s52
	v_perm_b32 v88, v84, v80, s53
	v_perm_b32 v80, v84, v80, s54
	v_dot4c_i32_i8_e32 v146, s0, v80
	v_perm_b32 v80, v85, v81, s53
	v_dot4c_i32_i8_e32 v155, s0, v80
	v_perm_b32 v80, v85, v81, s54
	v_dot4c_i32_i8_e32 v144, s0, v88
	v_dot4c_i32_i8_e32 v156, s0, v80
	v_and_b32_e32 v80, 0xf0f0f0f, v82
	v_lshrrev_b32_e32 v81, 4, v82
	v_and_b32_e32 v82, 0xf0f0f0f, v86
	v_and_b32_e32 v85, 0xf0f0f0f, v90
	v_and_b32_e32 v88, 0xf0f0f0f, v94
	v_lshrrev_b32_e32 v84, 4, v86
	v_lshrrev_b32_e32 v86, 4, v90
	v_perm_b32 v90, v82, v80, s33
	v_perm_b32 v80, v82, v80, s52
	v_perm_b32 v82, v88, v85, s33
	v_lshrrev_b32_e32 v89, 4, v94
	v_perm_b32 v85, v88, v85, s52
	v_perm_b32 v88, v82, v90, s53
	v_perm_b32 v82, v82, v90, s54
	v_and_b32_e32 v81, 0xf0f0f0f, v81
	v_and_b32_e32 v84, 0xf0f0f0f, v84
	v_and_b32_e32 v86, 0xf0f0f0f, v86
	v_and_b32_e32 v89, 0xf0f0f0f, v89
	v_dot4c_i32_i8_e32 v153, s0, v82
	v_perm_b32 v82, v85, v80, s53
	v_perm_b32 v80, v85, v80, s54
	v_dot4c_i32_i8_e32 v147, s0, v82
	v_dot4c_i32_i8_e32 v148, s0, v80
	v_perm_b32 v80, v84, v81, s33
	v_perm_b32 v82, v89, v86, s33
	v_perm_b32 v81, v84, v81, s52
	v_perm_b32 v84, v89, v86, s52
	v_perm_b32 v85, v82, v80, s53
	v_perm_b32 v80, v82, v80, s54
	v_dot4c_i32_i8_e32 v145, s0, v80
	v_perm_b32 v80, v84, v81, s53
	v_dot4c_i32_i8_e32 v141, s0, v80
	v_perm_b32 v80, v84, v81, s54
	v_dot4c_i32_i8_e32 v142, s0, v80
	v_and_b32_e32 v80, 0xf0f0f0f, v83
	v_and_b32_e32 v82, 0xf0f0f0f, v87
	v_and_b32_e32 v84, 0xf0f0f0f, v91
	v_and_b32_e32 v86, 0xf0f0f0f, v95
	v_dot4c_i32_i8_e32 v151, s0, v88
	v_perm_b32 v88, v82, v80, s33
	v_perm_b32 v80, v82, v80, s52
	v_perm_b32 v82, v86, v84, s33
	v_dot4c_i32_i8_e32 v143, s0, v85
	v_lshrrev_b32_e32 v81, 4, v83
	v_lshrrev_b32_e32 v83, 4, v87
	v_lshrrev_b32_e32 v85, 4, v91
	v_lshrrev_b32_e32 v87, 4, v95
	v_perm_b32 v84, v86, v84, s52
	v_perm_b32 v86, v82, v88, s53
	v_perm_b32 v82, v82, v88, s54
	v_and_b32_e32 v81, 0xf0f0f0f, v81
	v_and_b32_e32 v83, 0xf0f0f0f, v83
	v_and_b32_e32 v85, 0xf0f0f0f, v85
	v_and_b32_e32 v87, 0xf0f0f0f, v87
	v_dot4c_i32_i8_e32 v140, s0, v82
	v_perm_b32 v82, v84, v80, s53
	v_perm_b32 v80, v84, v80, s54
	v_dot4c_i32_i8_e32 v137, s0, v82
	v_dot4c_i32_i8_e32 v139, s0, v80
	v_perm_b32 v80, v83, v81, s33
	v_perm_b32 v82, v87, v85, s33
	v_perm_b32 v81, v83, v81, s52
	v_perm_b32 v83, v87, v85, s52
	v_perm_b32 v84, v82, v80, s53
	v_perm_b32 v80, v82, v80, s54
	v_dot4c_i32_i8_e32 v135, s0, v80
	v_perm_b32 v80, v83, v81, s53
	v_lshl_add_u64 v[48:49], v[116:117], 0, s[84:85]
	v_dot4c_i32_i8_e32 v123, s0, v80
	v_perm_b32 v80, v83, v81, s54
	global_load_dwordx4 v[72:75], v[48:49], off
	v_dot4c_i32_i8_e32 v125, s0, v80
	v_and_b32_e32 v80, 0xf0f0f0f, v32
	v_and_b32_e32 v81, 0xf0f0f0f, v36
	v_and_b32_e32 v82, 0xf0f0f0f, v40
	s_waitcnt vmcnt(1)
; __device__ void phase_gather(const Params& p) {
;     ...
;         if (gi + 2 < 64 / GROWS) {
; #pragma unroll
;           for (int k = 0; k < GROWS; ++k) {
;             const int e = __builtin_amdgcn_readlane(idv, j0 + 2 * GROWS + k);
;             rr[(gi + 2) % 3][k] = *(const u32x4*)(vb + (size_t)e * 1024 + lane * 16);
;           }
;         }
; #pragma unroll
;         for (int sub = 0; sub < GROWS / 4; ++sub) {
;           const int W4 = __builtin_amdgcn_readlane(pkv, j0 + 4 * sub);
; #pragma unroll
;           for (int m = 0; m < 4; ++m) {
;             unsigned lo[4], hi[4];
; #pragma unroll
;             for (int k = 0; k < 4; ++k) {
;               const unsigned w = rr[gi % 3][sub * 4 + k][m];
;               lo[k] = w & 0x0f0f0f0fu;
;               hi[k] = (w >> 4) & 0x0f0f0f0fu;
;             }
;             {
;               const unsigned p01l = __builtin_amdgcn_perm(lo[1], lo[0], 0x05010400u), p01h = __builtin_amdgcn_perm(lo[1], lo[0], 0x07030602u);
;               const unsigned p23l = __builtin_amdgcn_perm(lo[3], lo[2], 0x05010400u), p23h = __builtin_amdgcn_perm(lo[3], lo[2], 0x07030602u);
;               acc[m * 8 + 0] = __builtin_amdgcn_sdot4((int)__builtin_amdgcn_perm(p23l, p01l, 0x05040100u), W4, acc[m * 8 + 0], false);
;               acc[m * 8 + 1] = __builtin_amdgcn_sdot4((int)__builtin_amdgcn_perm(p23l, p01l, 0x07060302u), W4, acc[m * 8 + 1], false);
;               acc[m * 8 + 2] = __builtin_amdgcn_sdot4((int)__builtin_amdgcn_perm(p23h, p01h, 0x05040100u), W4, acc[m * 8 + 2], false);
;               acc[m * 8 + 3] = __builtin_amdgcn_sdot4((int)__builtin_amdgcn_perm(p23h, p01h, 0x07060302u), W4, acc[m * 8 + 3], false);
;             }
;             {
;               const unsigned p01l = __builtin_amdgcn_perm(hi[1], hi[0], 0x05010400u), p01h = __builtin_amdgcn_perm(hi[1], hi[0], 0x07030602u);
;               const unsigned p23l = __builtin_amdgcn_perm(hi[3], hi[2], 0x05010400u), p23h = __builtin_amdgcn_perm(hi[3], hi[2], 0x07030602u);
;               acc[m * 8 + 4] = __builtin_amdgcn_sdot4((int)__builtin_amdgcn_perm(p23l, p01l, 0x05040100u), W4, acc[m * 8 + 4], false);
;               acc[m * 8 + 5] = __builtin_amdgcn_sdot4((int)__builtin_amdgcn_perm(p23l, p01l, 0x07060302u), W4, acc[m * 8 + 5], false);
;               acc[m * 8 + 6] = __builtin_amdgcn_sdot4((int)__builtin_amdgcn_perm(p23h, p01h, 0x05040100u), W4, acc[m * 8 + 6], false);
	v_and_b32_e32 v83, 0xf0f0f0f, v44
	v_dot4c_i32_i8_e32 v134, s0, v84
	v_perm_b32 v84, v81, v80, s33
	v_perm_b32 v80, v81, v80, s52
	v_perm_b32 v81, v83, v82, s33
	v_dot4c_i32_i8_e32 v163, s0, v99
	v_dot4c_i32_i8_e32 v161, s0, v97
	v_dot4c_i32_i8_e32 v152, s0, v92
	v_dot4c_i32_i8_e32 v136, s0, v86
	v_readlane_b32 s0, v170, 12
	v_lshrrev_b32_e32 v32, 4, v32
	v_lshrrev_b32_e32 v36, 4, v36
	v_lshrrev_b32_e32 v40, 4, v40
	v_lshrrev_b32_e32 v44, 4, v44
	v_perm_b32 v82, v83, v82, s52
	v_perm_b32 v83, v81, v84, s53
	v_perm_b32 v81, v81, v84, s54
	v_and_b32_e32 v32, 0xf0f0f0f, v32
	v_and_b32_e32 v36, 0xf0f0f0f, v36
	v_and_b32_e32 v40, 0xf0f0f0f, v40
	v_and_b32_e32 v44, 0xf0f0f0f, v44
	v_dot4c_i32_i8_e32 v164, s0, v81
	v_perm_b32 v81, v82, v80, s53
	v_perm_b32 v80, v82, v80, s54
	v_dot4c_i32_i8_e32 v162, s0, v80
	v_perm_b32 v80, v36, v32, s33
	v_perm_b32 v32, v36, v32, s52
	v_perm_b32 v36, v44, v40, s33
	v_perm_b32 v40, v44, v40, s52
	v_perm_b32 v44, v36, v80, s53
	v_perm_b32 v36, v36, v80, s54
	v_dot4c_i32_i8_e32 v160, s0, v36
	v_perm_b32 v36, v40, v32, s53
	v_perm_b32 v32, v40, v32, s54
	v_dot4c_i32_i8_e32 v159, s0, v44
	v_dot4c_i32_i8_e32 v157, s0, v36
	v_dot4c_i32_i8_e32 v158, s0, v32
	v_and_b32_e32 v32, 0xf0f0f0f, v33
	v_and_b32_e32 v36, 0xf0f0f0f, v37
	v_and_b32_e32 v40, 0xf0f0f0f, v41
	v_and_b32_e32 v44, 0xf0f0f0f, v45
	v_perm_b32 v80, v36, v32, s33
	v_perm_b32 v32, v36, v32, s52
	v_perm_b32 v36, v44, v40, s33
	v_lshrrev_b32_e32 v33, 4, v33
	v_lshrrev_b32_e32 v37, 4, v37
	v_lshrrev_b32_e32 v41, 4, v41
	v_lshrrev_b32_e32 v45, 4, v45
	v_perm_b32 v40, v44, v40, s52
	v_perm_b32 v44, v36, v80, s53
	v_perm_b32 v36, v36, v80, s54
	v_and_b32_e32 v33, 0xf0f0f0f, v33
	v_and_b32_e32 v37, 0xf0f0f0f, v37
	v_and_b32_e32 v41, 0xf0f0f0f, v41
	v_and_b32_e32 v45, 0xf0f0f0f, v45
	v_dot4c_i32_i8_e32 v154, s0, v36
	v_perm_b32 v36, v40, v32, s53
	v_perm_b32 v32, v40, v32, s54
	v_dot4c_i32_i8_e32 v149, s0, v36
	v_dot4c_i32_i8_e32 v150, s0, v32
	v_perm_b32 v32, v37, v33, s33
	v_perm_b32 v36, v45, v41, s33
	v_perm_b32 v33, v37, v33, s52
	v_perm_b32 v37, v45, v41, s52
	v_perm_b32 v40, v36, v32, s53
	v_perm_b32 v32, v36, v32, s54
	v_dot4c_i32_i8_e32 v146, s0, v32
	v_perm_b32 v32, v37, v33, s53
	v_dot4c_i32_i8_e32 v155, s0, v32
	v_perm_b32 v32, v37, v33, s54
	v_dot4c_i32_i8_e32 v144, s0, v40
	v_dot4c_i32_i8_e32 v156, s0, v32
	v_and_b32_e32 v32, 0xf0f0f0f, v34
	v_lshrrev_b32_e32 v33, 4, v34
	v_and_b32_e32 v34, 0xf0f0f0f, v38
	v_and_b32_e32 v37, 0xf0f0f0f, v42
	v_and_b32_e32 v40, 0xf0f0f0f, v46
	v_lshrrev_b32_e32 v36, 4, v38
	v_lshrrev_b32_e32 v38, 4, v42
	v_perm_b32 v42, v34, v32, s33
	v_perm_b32 v32, v34, v32, s52
	v_perm_b32 v34, v40, v37, s33
	v_lshrrev_b32_e32 v41, 4, v46
	v_perm_b32 v37, v40, v37, s52
	v_perm_b32 v40, v34, v42, s53
	v_perm_b32 v34, v34, v42, s54
	v_and_b32_e32 v33, 0xf0f0f0f, v33
	v_and_b32_e32 v36, 0xf0f0f0f, v36
	v_and_b32_e32 v38, 0xf0f0f0f, v38
	v_and_b32_e32 v41, 0xf0f0f0f, v41
	v_dot4c_i32_i8_e32 v153, s0, v34
	v_perm_b32 v34, v37, v32, s53
	v_perm_b32 v32, v37, v32, s54
	v_dot4c_i32_i8_e32 v147, s0, v34
	v_dot4c_i32_i8_e32 v148, s0, v32
	v_perm_b32 v32, v36, v33, s33
	v_perm_b32 v34, v41, v38, s33
	v_perm_b32 v33, v36, v33, s52
	v_perm_b32 v36, v41, v38, s52
	v_perm_b32 v37, v34, v32, s53
	v_perm_b32 v32, v34, v32, s54
	v_dot4c_i32_i8_e32 v145, s0, v32
	v_perm_b32 v32, v36, v33, s53
	v_dot4c_i32_i8_e32 v141, s0, v32
	v_perm_b32 v32, v36, v33, s54
	v_dot4c_i32_i8_e32 v142, s0, v32
	v_and_b32_e32 v32, 0xf0f0f0f, v35
	v_and_b32_e32 v34, 0xf0f0f0f, v39
	v_and_b32_e32 v36, 0xf0f0f0f, v43
	v_and_b32_e32 v38, 0xf0f0f0f, v47
	v_dot4c_i32_i8_e32 v151, s0, v40
	v_perm_b32 v40, v34, v32, s33
	v_perm_b32 v32, v34, v32, s52
	v_perm_b32 v34, v38, v36, s33
	v_dot4c_i32_i8_e32 v143, s0, v37
	v_lshrrev_b32_e32 v33, 4, v35
	v_lshrrev_b32_e32 v35, 4, v39
	v_lshrrev_b32_e32 v37, 4, v43
	v_lshrrev_b32_e32 v39, 4, v47
	v_perm_b32 v36, v38, v36, s52
	v_perm_b32 v38, v34, v40, s53
	v_perm_b32 v34, v34, v40, s54
	v_and_b32_e32 v33, 0xf0f0f0f, v33
	v_and_b32_e32 v35, 0xf0f0f0f, v35
	v_and_b32_e32 v37, 0xf0f0f0f, v37
	v_and_b32_e32 v39, 0xf0f0f0f, v39
	v_dot4c_i32_i8_e32 v140, s0, v34
	v_perm_b32 v34, v36, v32, s53
	v_perm_b32 v32, v36, v32, s54
	v_dot4c_i32_i8_e32 v137, s0, v34
	v_dot4c_i32_i8_e32 v139, s0, v32
	v_perm_b32 v32, v35, v33, s33
	v_perm_b32 v34, v39, v37, s33
	v_perm_b32 v33, v35, v33, s52
	v_perm_b32 v35, v39, v37, s52
	v_perm_b32 v36, v34, v32, s53
	v_perm_b32 v32, v34, v32, s54
	v_dot4c_i32_i8_e32 v135, s0, v32
	v_perm_b32 v32, v35, v33, s53
	v_dot4c_i32_i8_e32 v123, s0, v32
	v_perm_b32 v32, v35, v33, s54
	v_lshl_add_u64 v[0:1], v[116:117], 0, s[16:17]
	v_dot4c_i32_i8_e32 v125, s0, v32
	v_lshl_add_u64 v[32:33], v[116:117], 0, s[66:67]
	global_load_dwordx4 v[28:31], v[0:1], off
	global_load_dwordx4 v[108:111], v[32:33], off
	v_lshl_add_u64 v[0:1], v[116:117], 0, s[14:15]
	v_lshl_add_u64 v[32:33], v[116:117], 0, s[68:69]
	global_load_dwordx4 v[24:27], v[0:1], off
	global_load_dwordx4 v[104:107], v[32:33], off
	v_lshl_add_u64 v[0:1], v[116:117], 0, s[12:13]
	v_lshl_add_u64 v[32:33], v[116:117], 0, s[70:71]
	global_load_dwordx4 v[20:23], v[0:1], off
	global_load_dwordx4 v[100:103], v[32:33], off
	v_lshl_add_u64 v[0:1], v[116:117], 0, s[10:11]
	global_load_dwordx4 v[16:19], v[0:1], off
	v_lshl_add_u64 v[32:33], v[116:117], 0, s[72:73]
	v_dot4c_i32_i8_e32 v163, s0, v83
	v_dot4c_i32_i8_e32 v161, s0, v81
	global_load_dwordx4 v[96:99], v[32:33], off
	v_dot4c_i32_i8_e32 v152, s0, v44
	v_dot4c_i32_i8_e32 v136, s0, v38
	v_dot4c_i32_i8_e32 v134, s0, v36
	v_readlane_b32 s0, v170, 16
	v_lshl_add_u64 v[0:1], v[116:117], 0, s[8:9]
	global_load_dwordx4 v[12:15], v[0:1], off
	v_lshl_add_u64 v[32:33], v[116:117], 0, s[74:75]
	global_load_dwordx4 v[44:47], v[32:33], off
	v_lshl_add_u64 v[32:33], v[116:117], 0, s[76:77]
	v_lshl_add_u64 v[48:49], v[116:117], 0, s[82:83]
	global_load_dwordx4 v[40:43], v[32:33], off
	v_lshl_add_u64 v[32:33], v[116:117], 0, s[78:79]
	global_load_dwordx4 v[76:79], v[48:49], off
	global_load_dwordx4 v[36:39], v[32:33], off
	v_lshl_add_u64 v[48:49], v[116:117], 0, s[86:87]
	v_lshl_add_u64 v[32:33], v[116:117], 0, s[80:81]
	global_load_dwordx4 v[68:71], v[48:49], off
	s_waitcnt vmcnt(13)
; __device__ void phase_gather(const Params& p) {
;     ...
;         if (gi + 2 < 64 / GROWS) {
; #pragma unroll
;           for (int k = 0; k < GROWS; ++k) {
;             const int e = __builtin_amdgcn_readlane(idv, j0 + 2 * GROWS + k);
;             rr[(gi + 2) % 3][k] = *(const u32x4*)(vb + (size_t)e * 1024 + lane * 16);
;           }
;         }
; #pragma unroll
;         for (int sub = 0; sub < GROWS / 4; ++sub) {
;           const int W4 = __builtin_amdgcn_readlane(pkv, j0 + 4 * sub);
; #pragma unroll
;           for (int m = 0; m < 4; ++m) {
;             unsigned lo[4], hi[4];
; #pragma unroll
;             for (int k = 0; k < 4; ++k) {
;               const unsigned w = rr[gi % 3][sub * 4 + k][m];
;               lo[k] = w & 0x0f0f0f0fu;
;               hi[k] = (w >> 4) & 0x0f0f0f0fu;
;             }
;             {
;               const unsigned p01l = __builtin_amdgcn_perm(lo[1], lo[0], 0x05010400u), p01h = __builtin_amdgcn_perm(lo[1], lo[0], 0x07030602u);
;               const unsigned p23l = __builtin_amdgcn_perm(lo[3], lo[2], 0x05010400u), p23h = __builtin_amdgcn_perm(lo[3], lo[2], 0x07030602u);
;               acc[m * 8 + 0] = __builtin_amdgcn_sdot4((int)__builtin_amdgcn_perm(p23l, p01l, 0x05040100u), W4, acc[m * 8 + 0], false);
;               acc[m * 8 + 1] = __builtin_amdgcn_sdot4((int)__builtin_amdgcn_perm(p23l, p01l, 0x07060302u), W4, acc[m * 8 + 1], false);
;               acc[m * 8 + 2] = __builtin_amdgcn_sdot4((int)__builtin_amdgcn_perm(p23h, p01h, 0x05040100u), W4, acc[m * 8 + 2], false);
;               acc[m * 8 + 3] = __builtin_amdgcn_sdot4((int)__builtin_amdgcn_perm(p23h, p01h, 0x07060302u), W4, acc[m * 8 + 3], false);
;             }
;             {
;               const unsigned p01l = __builtin_amdgcn_perm(hi[1], hi[0], 0x05010400u), p01h = __builtin_amdgcn_perm(hi[1], hi[0], 0x07030602u);
;               const unsigned p23l = __builtin_amdgcn_perm(hi[3], hi[2], 0x05010400u), p23h = __builtin_amdgcn_perm(hi[3], hi[2], 0x07030602u);
;               acc[m * 8 + 4] = __builtin_amdgcn_sdot4((int)__builtin_amdgcn_perm(p23l, p01l, 0x05040100u), W4, acc[m * 8 + 4], false);
;               acc[m * 8 + 5] = __builtin_amdgcn_sdot4((int)__builtin_amdgcn_perm(p23l, p01l, 0x07060302u), W4, acc[m * 8 + 5], false);
;               acc[m * 8 + 6] = __builtin_amdgcn_sdot4((int)__builtin_amdgcn_perm(p23h, p01h, 0x05040100u), W4, acc[m * 8 + 6], false);
	v_and_b32_e32 v80, 0xf0f0f0f, v28
	v_lshrrev_b32_e32 v28, 4, v28
	v_and_b32_e32 v28, 0xf0f0f0f, v28
	global_load_dwordx4 v[32:35], v[32:33], off
	s_waitcnt vmcnt(12)
	v_and_b32_e32 v81, 0xf0f0f0f, v24
	v_perm_b32 v84, v81, v80, s33
	v_perm_b32 v80, v81, v80, s52
	v_lshrrev_b32_e32 v24, 4, v24
	s_waitcnt vmcnt(10)
	v_and_b32_e32 v82, 0xf0f0f0f, v20
	v_lshrrev_b32_e32 v20, 4, v20
	v_and_b32_e32 v24, 0xf0f0f0f, v24
	s_waitcnt vmcnt(8)
	v_and_b32_e32 v83, 0xf0f0f0f, v16
	v_perm_b32 v81, v83, v82, s33
	v_lshrrev_b32_e32 v16, 4, v16
	v_perm_b32 v82, v83, v82, s52
	v_perm_b32 v83, v81, v84, s53
	v_perm_b32 v81, v81, v84, s54
	v_and_b32_e32 v20, 0xf0f0f0f, v20
	v_and_b32_e32 v16, 0xf0f0f0f, v16
	v_dot4c_i32_i8_e32 v164, s0, v81
	v_perm_b32 v81, v82, v80, s53
	v_perm_b32 v80, v82, v80, s54
	v_dot4c_i32_i8_e32 v162, s0, v80
	v_perm_b32 v80, v24, v28, s33
	v_perm_b32 v24, v24, v28, s52
	v_perm_b32 v28, v16, v20, s33
	v_perm_b32 v16, v16, v20, s52
	v_perm_b32 v20, v28, v80, s53
	v_dot4c_i32_i8_e32 v159, s0, v20
	v_perm_b32 v20, v28, v80, s54
	v_dot4c_i32_i8_e32 v160, s0, v20
	v_perm_b32 v20, v16, v24, s53
	v_perm_b32 v16, v16, v24, s54
	v_dot4c_i32_i8_e32 v157, s0, v20
	v_dot4c_i32_i8_e32 v158, s0, v16
	v_and_b32_e32 v16, 0xf0f0f0f, v29
	v_lshrrev_b32_e32 v20, 4, v29
	v_and_b32_e32 v24, 0xf0f0f0f, v25
	v_and_b32_e32 v28, 0xf0f0f0f, v21
	v_and_b32_e32 v29, 0xf0f0f0f, v17
	v_perm_b32 v80, v24, v16, s33
	v_perm_b32 v16, v24, v16, s52
	v_perm_b32 v24, v29, v28, s33
	v_lshrrev_b32_e32 v25, 4, v25
	v_lshrrev_b32_e32 v21, 4, v21
	v_lshrrev_b32_e32 v17, 4, v17
	v_perm_b32 v28, v29, v28, s52
	v_perm_b32 v29, v24, v80, s53
	v_perm_b32 v24, v24, v80, s54
	v_and_b32_e32 v20, 0xf0f0f0f, v20
	v_and_b32_e32 v25, 0xf0f0f0f, v25
	v_and_b32_e32 v21, 0xf0f0f0f, v21
	v_and_b32_e32 v17, 0xf0f0f0f, v17
	v_dot4c_i32_i8_e32 v154, s0, v24
	v_perm_b32 v24, v28, v16, s53
	v_perm_b32 v16, v28, v16, s54
	v_dot4c_i32_i8_e32 v149, s0, v24
	v_dot4c_i32_i8_e32 v150, s0, v16
	v_perm_b32 v16, v25, v20, s33
	v_perm_b32 v24, v17, v21, s33
	v_perm_b32 v20, v25, v20, s52
	v_perm_b32 v17, v17, v21, s52
	v_perm_b32 v21, v24, v16, s53
	v_perm_b32 v16, v24, v16, s54
	v_dot4c_i32_i8_e32 v146, s0, v16
	v_perm_b32 v16, v17, v20, s53
	v_dot4c_i32_i8_e32 v155, s0, v16
	v_perm_b32 v16, v17, v20, s54
	v_dot4c_i32_i8_e32 v156, s0, v16
	v_and_b32_e32 v16, 0xf0f0f0f, v30
	v_and_b32_e32 v20, 0xf0f0f0f, v26
	v_and_b32_e32 v24, 0xf0f0f0f, v22
	v_and_b32_e32 v25, 0xf0f0f0f, v18
	v_dot4c_i32_i8_e32 v144, s0, v21
	v_lshrrev_b32_e32 v21, 4, v26
	v_perm_b32 v26, v20, v16, s33
	v_perm_b32 v16, v20, v16, s52
	v_perm_b32 v20, v25, v24, s33
	v_lshrrev_b32_e32 v17, 4, v30
	v_lshrrev_b32_e32 v22, 4, v22
	v_lshrrev_b32_e32 v18, 4, v18
	v_perm_b32 v24, v25, v24, s52
	v_perm_b32 v25, v20, v26, s53
	v_perm_b32 v20, v20, v26, s54
	v_and_b32_e32 v17, 0xf0f0f0f, v17
	v_and_b32_e32 v21, 0xf0f0f0f, v21
	v_and_b32_e32 v22, 0xf0f0f0f, v22
	v_and_b32_e32 v18, 0xf0f0f0f, v18
	v_dot4c_i32_i8_e32 v153, s0, v20
	v_perm_b32 v20, v24, v16, s53
	v_perm_b32 v16, v24, v16, s54
	v_dot4c_i32_i8_e32 v147, s0, v20
	v_dot4c_i32_i8_e32 v148, s0, v16
	v_perm_b32 v16, v21, v17, s33
	v_perm_b32 v20, v18, v22, s33
	v_perm_b32 v17, v21, v17, s52
	v_perm_b32 v18, v18, v22, s52
	v_perm_b32 v21, v20, v16, s53
	v_perm_b32 v16, v20, v16, s54
	v_dot4c_i32_i8_e32 v145, s0, v16
	v_perm_b32 v16, v18, v17, s53
	v_dot4c_i32_i8_e32 v141, s0, v16
	v_perm_b32 v16, v18, v17, s54
	v_dot4c_i32_i8_e32 v143, s0, v21
	v_dot4c_i32_i8_e32 v142, s0, v16
	v_and_b32_e32 v16, 0xf0f0f0f, v31
	v_and_b32_e32 v18, 0xf0f0f0f, v27
	v_and_b32_e32 v21, 0xf0f0f0f, v23
	v_lshrrev_b32_e32 v22, 4, v23
	v_and_b32_e32 v23, 0xf0f0f0f, v19
	v_perm_b32 v24, v18, v16, s33
	v_perm_b32 v16, v18, v16, s52
	v_perm_b32 v18, v23, v21, s33
	v_dot4c_i32_i8_e32 v151, s0, v25
	v_perm_b32 v21, v23, v21, s52
	v_perm_b32 v23, v18, v24, s53
	v_perm_b32 v18, v18, v24, s54
	v_lshl_add_u64 v[24:25], v[116:117], 0, s[62:63]
	v_dot4c_i32_i8_e32 v152, s0, v29
	v_lshrrev_b32_e32 v20, 4, v27
	global_load_dwordx4 v[24:27], v[24:25], off
	v_lshl_add_u64 v[0:1], v[116:117], 0, s[6:7]
	v_lshl_add_u64 v[28:29], v[116:117], 0, s[64:65]
	global_load_dwordx4 v[8:11], v[0:1], off
	v_lshrrev_b32_e32 v17, 4, v31
	global_load_dwordx4 v[28:31], v[28:29], off
	v_lshl_add_u64 v[0:1], v[116:117], 0, s[4:5]
	global_load_dwordx4 v[4:7], v[0:1], off
	v_lshl_add_u64 v[0:1], v[116:117], 0, s[2:3]
	global_load_dwordx4 v[0:3], v[0:1], off
	v_lshl_add_u64 v[48:49], v[116:117], 0, s[88:89]
	global_load_dwordx4 v[64:67], v[48:49], off
	v_lshl_add_u64 v[48:49], v[116:117], 0, s[90:91]
	global_load_dwordx4 v[60:63], v[48:49], off
	v_lshl_add_u64 v[48:49], v[116:117], 0, s[92:93]
	global_load_dwordx4 v[56:59], v[48:49], off
	v_lshl_add_u64 v[48:49], v[116:117], 0, s[94:95]
	global_load_dwordx4 v[52:55], v[48:49], off
	v_lshl_add_u64 v[48:49], v[116:117], 0, s[96:97]
	global_load_dwordx4 v[48:51], v[48:49], off
	v_lshrrev_b32_e32 v19, 4, v19
	v_and_b32_e32 v17, 0xf0f0f0f, v17
	v_and_b32_e32 v20, 0xf0f0f0f, v20
	v_and_b32_e32 v22, 0xf0f0f0f, v22
	v_and_b32_e32 v19, 0xf0f0f0f, v19
	v_dot4c_i32_i8_e32 v140, s0, v18
	v_perm_b32 v18, v21, v16, s53
	v_perm_b32 v16, v21, v16, s54
	v_dot4c_i32_i8_e32 v137, s0, v18
	v_dot4c_i32_i8_e32 v139, s0, v16
	v_perm_b32 v16, v20, v17, s33
	v_perm_b32 v18, v19, v22, s33
	v_perm_b32 v17, v20, v17, s52
	v_perm_b32 v19, v19, v22, s52
	v_perm_b32 v20, v18, v16, s53
	v_perm_b32 v16, v18, v16, s54
	v_dot4c_i32_i8_e32 v135, s0, v16
	v_perm_b32 v16, v19, v17, s53
	v_dot4c_i32_i8_e32 v123, s0, v16
	v_perm_b32 v16, v19, v17, s54
	v_dot4c_i32_i8_e32 v125, s0, v16
	s_waitcnt vmcnt(16)
; __device__ void phase_gather(const Params& p) {
;     ...
; #pragma unroll
;         for (int sub = 0; sub < GROWS / 4; ++sub) {
;           const int W4 = __builtin_amdgcn_readlane(pkv, j0 + 4 * sub);
; #pragma unroll
;           for (int m = 0; m < 4; ++m) {
;             unsigned lo[4], hi[4];
; #pragma unroll
;             for (int k = 0; k < 4; ++k) {
;               const unsigned w = rr[gi % 3][sub * 4 + k][m];
;               lo[k] = w & 0x0f0f0f0fu;
;               hi[k] = (w >> 4) & 0x0f0f0f0fu;
;             }
;             {
;               const unsigned p01l = __builtin_amdgcn_perm(lo[1], lo[0], 0x05010400u), p01h = __builtin_amdgcn_perm(lo[1], lo[0], 0x07030602u);
;               const unsigned p23l = __builtin_amdgcn_perm(lo[3], lo[2], 0x05010400u), p23h = __builtin_amdgcn_perm(lo[3], lo[2], 0x07030602u);
;               acc[m * 8 + 0] = __builtin_amdgcn_sdot4((int)__builtin_amdgcn_perm(p23l, p01l, 0x05040100u), W4, acc[m * 8 + 0], false);
;               acc[m * 8 + 1] = __builtin_amdgcn_sdot4((int)__builtin_amdgcn_perm(p23l, p01l, 0x07060302u), W4, acc[m * 8 + 1], false);
;               acc[m * 8 + 2] = __builtin_amdgcn_sdot4((int)__builtin_amdgcn_perm(p23h, p01h, 0x05040100u), W4, acc[m * 8 + 2], false);
;               acc[m * 8 + 3] = __builtin_amdgcn_sdot4((int)__builtin_amdgcn_perm(p23h, p01h, 0x07060302u), W4, acc[m * 8 + 3], false);
;             }
;             {
;               const unsigned p01l = __builtin_amdgcn_perm(hi[1], hi[0], 0x05010400u), p01h = __builtin_amdgcn_perm(hi[1], hi[0], 0x07030602u);
;               const unsigned p23l = __builtin_amdgcn_perm(hi[3], hi[2], 0x05010400u), p23h = __builtin_amdgcn_perm(hi[3], hi[2], 0x07030602u);
;               acc[m * 8 + 4] = __builtin_amdgcn_sdot4((int)__builtin_amdgcn_perm(p23l, p01l, 0x05040100u), W4, acc[m * 8 + 4], false);
;               acc[m * 8 + 5] = __builtin_amdgcn_sdot4((int)__builtin_amdgcn_perm(p23l, p01l, 0x07060302u), W4, acc[m * 8 + 5], false);
;               acc[m * 8 + 6] = __builtin_amdgcn_sdot4((int)__builtin_amdgcn_perm(p23h, p01h, 0x05040100u), W4, acc[m * 8 + 6], false);
;               acc[m * 8 + 7] = __builtin_amdgcn_sdot4((int)__builtin_amdgcn_perm(p23h, p01h, 0x07060302u), W4, acc[m * 8 + 7], false);
;             }
;           }
	v_and_b32_e32 v16, 0xf0f0f0f, v12
	v_dot4c_i32_i8_e32 v134, s0, v20
	v_dot4c_i32_i8_e32 v163, s0, v83
	v_dot4c_i32_i8_e32 v161, s0, v81
	v_dot4c_i32_i8_e32 v136, s0, v23
	v_readlane_b32 s0, v170, 20
	v_lshrrev_b32_e32 v12, 4, v12
	v_and_b32_e32 v12, 0xf0f0f0f, v12
	v_and_b32_e32 v80, 0xf0f0f0f, v72
	s_waitcnt vmcnt(13)
	v_and_b32_e32 v81, 0xf0f0f0f, v76
	s_waitcnt vmcnt(11)
	v_and_b32_e32 v82, 0xf0f0f0f, v68
	v_perm_b32 v84, v81, v80, s33
	v_perm_b32 v80, v81, v80, s52
	v_lshrrev_b32_e32 v72, 4, v72
	v_lshrrev_b32_e32 v76, 4, v76
	v_lshrrev_b32_e32 v68, 4, v68
	v_and_b32_e32 v72, 0xf0f0f0f, v72
	v_and_b32_e32 v76, 0xf0f0f0f, v76
	v_and_b32_e32 v68, 0xf0f0f0f, v68
	v_readlane_b32 s2, v170, 48
	v_readlane_b32 s3, v170, 52
	s_waitcnt vmcnt(8)
	v_and_b32_e32 v17, 0xf0f0f0f, v8
	v_perm_b32 v20, v17, v16, s33
	v_perm_b32 v16, v17, v16, s52
	v_lshrrev_b32_e32 v8, 4, v8
	s_waitcnt vmcnt(6)
	v_and_b32_e32 v18, 0xf0f0f0f, v4
	v_lshrrev_b32_e32 v4, 4, v4
	s_waitcnt vmcnt(5)
	v_and_b32_e32 v19, 0xf0f0f0f, v0
	v_perm_b32 v17, v19, v18, s33
	v_lshrrev_b32_e32 v0, 4, v0
	v_perm_b32 v18, v19, v18, s52
	v_perm_b32 v19, v17, v20, s53
	v_perm_b32 v17, v17, v20, s54
	v_and_b32_e32 v8, 0xf0f0f0f, v8
	v_and_b32_e32 v4, 0xf0f0f0f, v4
	v_and_b32_e32 v0, 0xf0f0f0f, v0
	v_dot4c_i32_i8_e32 v164, s0, v17
	v_perm_b32 v17, v18, v16, s53
	v_perm_b32 v16, v18, v16, s54
	v_dot4c_i32_i8_e32 v162, s0, v16
	v_perm_b32 v16, v8, v12, s33
	v_perm_b32 v8, v8, v12, s52
	v_perm_b32 v12, v0, v4, s33
	v_perm_b32 v0, v0, v4, s52
	v_perm_b32 v4, v12, v16, s53
	v_dot4c_i32_i8_e32 v159, s0, v4
	v_perm_b32 v4, v12, v16, s54
	v_dot4c_i32_i8_e32 v160, s0, v4
	v_perm_b32 v4, v0, v8, s53
	v_perm_b32 v0, v0, v8, s54
	v_dot4c_i32_i8_e32 v157, s0, v4
	v_dot4c_i32_i8_e32 v158, s0, v0
	v_and_b32_e32 v0, 0xf0f0f0f, v13
	v_lshrrev_b32_e32 v4, 4, v13
	v_and_b32_e32 v8, 0xf0f0f0f, v9
	v_and_b32_e32 v12, 0xf0f0f0f, v5
	v_and_b32_e32 v13, 0xf0f0f0f, v1
	v_perm_b32 v16, v8, v0, s33
	v_perm_b32 v0, v8, v0, s52
	v_perm_b32 v8, v13, v12, s33
	v_lshrrev_b32_e32 v9, 4, v9
	v_lshrrev_b32_e32 v5, 4, v5
	v_lshrrev_b32_e32 v1, 4, v1
	v_perm_b32 v12, v13, v12, s52
	v_perm_b32 v13, v8, v16, s53
	v_perm_b32 v8, v8, v16, s54
	v_and_b32_e32 v4, 0xf0f0f0f, v4
	v_and_b32_e32 v9, 0xf0f0f0f, v9
	v_and_b32_e32 v5, 0xf0f0f0f, v5
	v_and_b32_e32 v1, 0xf0f0f0f, v1
	v_dot4c_i32_i8_e32 v154, s0, v8
	v_perm_b32 v8, v12, v0, s53
	v_perm_b32 v0, v12, v0, s54
	v_dot4c_i32_i8_e32 v149, s0, v8
	v_dot4c_i32_i8_e32 v150, s0, v0
	v_perm_b32 v0, v9, v4, s33
	v_perm_b32 v8, v1, v5, s33
	v_perm_b32 v4, v9, v4, s52
	v_perm_b32 v1, v1, v5, s52
	v_perm_b32 v5, v8, v0, s53
	v_perm_b32 v0, v8, v0, s54
	v_dot4c_i32_i8_e32 v146, s0, v0
	v_perm_b32 v0, v1, v4, s53
	v_dot4c_i32_i8_e32 v155, s0, v0
	v_perm_b32 v0, v1, v4, s54
	v_dot4c_i32_i8_e32 v156, s0, v0
	v_and_b32_e32 v0, 0xf0f0f0f, v14
	v_and_b32_e32 v4, 0xf0f0f0f, v10
	v_and_b32_e32 v8, 0xf0f0f0f, v6
	v_and_b32_e32 v9, 0xf0f0f0f, v2
	v_dot4c_i32_i8_e32 v144, s0, v5
	v_lshrrev_b32_e32 v5, 4, v10
	v_perm_b32 v10, v4, v0, s33
	v_perm_b32 v0, v4, v0, s52
	v_perm_b32 v4, v9, v8, s33
	v_lshrrev_b32_e32 v1, 4, v14
	v_lshrrev_b32_e32 v6, 4, v6
	v_lshrrev_b32_e32 v2, 4, v2
	v_perm_b32 v8, v9, v8, s52
	v_perm_b32 v9, v4, v10, s53
	v_perm_b32 v4, v4, v10, s54
	v_and_b32_e32 v1, 0xf0f0f0f, v1
	v_and_b32_e32 v5, 0xf0f0f0f, v5
	v_and_b32_e32 v6, 0xf0f0f0f, v6
	v_and_b32_e32 v2, 0xf0f0f0f, v2
	v_dot4c_i32_i8_e32 v153, s0, v4
	v_perm_b32 v4, v8, v0, s53
	v_perm_b32 v0, v8, v0, s54
	v_dot4c_i32_i8_e32 v147, s0, v4
	v_dot4c_i32_i8_e32 v148, s0, v0
	v_perm_b32 v0, v5, v1, s33
	v_perm_b32 v4, v2, v6, s33
	v_perm_b32 v1, v5, v1, s52
	v_perm_b32 v2, v2, v6, s52
	v_perm_b32 v5, v4, v0, s53
	v_perm_b32 v0, v4, v0, s54
	v_dot4c_i32_i8_e32 v145, s0, v0
	v_perm_b32 v0, v2, v1, s53
	v_dot4c_i32_i8_e32 v141, s0, v0
	v_perm_b32 v0, v2, v1, s54
	v_dot4c_i32_i8_e32 v143, s0, v5
	v_dot4c_i32_i8_e32 v142, s0, v0
	v_and_b32_e32 v0, 0xf0f0f0f, v15
	v_and_b32_e32 v2, 0xf0f0f0f, v11
	v_and_b32_e32 v5, 0xf0f0f0f, v7
	v_lshrrev_b32_e32 v6, 4, v7
	v_and_b32_e32 v7, 0xf0f0f0f, v3
	v_perm_b32 v8, v2, v0, s33
	v_perm_b32 v0, v2, v0, s52
	v_perm_b32 v2, v7, v5, s33
	v_lshrrev_b32_e32 v1, 4, v15
	v_lshrrev_b32_e32 v4, 4, v11
	v_lshrrev_b32_e32 v3, 4, v3
	v_perm_b32 v5, v7, v5, s52
	v_perm_b32 v7, v2, v8, s53
	v_perm_b32 v2, v2, v8, s54
	v_and_b32_e32 v1, 0xf0f0f0f, v1
	v_and_b32_e32 v4, 0xf0f0f0f, v4
	v_and_b32_e32 v6, 0xf0f0f0f, v6
	v_and_b32_e32 v3, 0xf0f0f0f, v3
	v_dot4c_i32_i8_e32 v140, s0, v2
	v_perm_b32 v2, v5, v0, s53
	v_perm_b32 v0, v5, v0, s54
	v_dot4c_i32_i8_e32 v137, s0, v2
	v_dot4c_i32_i8_e32 v139, s0, v0
	v_perm_b32 v0, v4, v1, s33
	v_perm_b32 v2, v3, v6, s33
	v_perm_b32 v1, v4, v1, s52
	v_perm_b32 v3, v3, v6, s52
	v_perm_b32 v4, v2, v0, s53
	v_perm_b32 v0, v2, v0, s54
	v_dot4c_i32_i8_e32 v135, s0, v0
	v_perm_b32 v0, v3, v1, s53
	v_dot4c_i32_i8_e32 v123, s0, v0
	v_perm_b32 v0, v3, v1, s54
	v_dot4c_i32_i8_e32 v163, s0, v19
	v_dot4c_i32_i8_e32 v161, s0, v17
	v_dot4c_i32_i8_e32 v152, s0, v13
	v_dot4c_i32_i8_e32 v151, s0, v9
	v_dot4c_i32_i8_e32 v136, s0, v7
	v_dot4c_i32_i8_e32 v134, s0, v4
	v_dot4c_i32_i8_e32 v125, s0, v0
	v_readlane_b32 s0, v250, 34
	v_readlane_b32 s1, v250, 35
	s_waitcnt vmcnt(4)
; __device__ void phase_gather(const Params& p) {
;     ...
;         if (gi + 2 < 64 / GROWS) {
; #pragma unroll
;           for (int k = 0; k < GROWS; ++k) {
;             const int e = __builtin_amdgcn_readlane(idv, j0 + 2 * GROWS + k);
;             rr[(gi + 2) % 3][k] = *(const u32x4*)(vb + (size_t)e * 1024 + lane * 16);
;           }
;         }
; #pragma unroll
;         for (int sub = 0; sub < GROWS / 4; ++sub) {
;           const int W4 = __builtin_amdgcn_readlane(pkv, j0 + 4 * sub);
; #pragma unroll
;           for (int m = 0; m < 4; ++m) {
;             unsigned lo[4], hi[4];
; #pragma unroll
;             for (int k = 0; k < 4; ++k) {
;               const unsigned w = rr[gi % 3][sub * 4 + k][m];
;               lo[k] = w & 0x0f0f0f0fu;
;               hi[k] = (w >> 4) & 0x0f0f0f0fu;
;             }
;             {
;               const unsigned p01l = __builtin_amdgcn_perm(lo[1], lo[0], 0x05010400u), p01h = __builtin_amdgcn_perm(lo[1], lo[0], 0x07030602u);
;               const unsigned p23l = __builtin_amdgcn_perm(lo[3], lo[2], 0x05010400u), p23h = __builtin_amdgcn_perm(lo[3], lo[2], 0x07030602u);
;               acc[m * 8 + 0] = __builtin_amdgcn_sdot4((int)__builtin_amdgcn_perm(p23l, p01l, 0x05040100u), W4, acc[m * 8 + 0], false);
;               acc[m * 8 + 1] = __builtin_amdgcn_sdot4((int)__builtin_amdgcn_perm(p23l, p01l, 0x07060302u), W4, acc[m * 8 + 1], false);
;               acc[m * 8 + 2] = __builtin_amdgcn_sdot4((int)__builtin_amdgcn_perm(p23h, p01h, 0x05040100u), W4, acc[m * 8 + 2], false);
;               acc[m * 8 + 3] = __builtin_amdgcn_sdot4((int)__builtin_amdgcn_perm(p23h, p01h, 0x07060302u), W4, acc[m * 8 + 3], false);
;             }
;             {
;               const unsigned p01l = __builtin_amdgcn_perm(hi[1], hi[0], 0x05010400u), p01h = __builtin_amdgcn_perm(hi[1], hi[0], 0x07030602u);
;               const unsigned p23l = __builtin_amdgcn_perm(hi[3], hi[2], 0x05010400u), p23h = __builtin_amdgcn_perm(hi[3], hi[2], 0x07030602u);
;               acc[m * 8 + 4] = __builtin_amdgcn_sdot4((int)__builtin_amdgcn_perm(p23l, p01l, 0x05040100u), W4, acc[m * 8 + 4], false);
;               acc[m * 8 + 5] = __builtin_amdgcn_sdot4((int)__builtin_amdgcn_perm(p23l, p01l, 0x07060302u), W4, acc[m * 8 + 5], false);
;               acc[m * 8 + 6] = __builtin_amdgcn_sdot4((int)__builtin_amdgcn_perm(p23h, p01h, 0x05040100u), W4, acc[m * 8 + 6], false);
	v_and_b32_e32 v83, 0xf0f0f0f, v64
	v_perm_b32 v81, v83, v82, s33
	v_lshl_add_u64 v[0:1], v[116:117], 0, s[0:1]
	v_readlane_b32 s0, v250, 36
	v_readlane_b32 s1, v250, 37
	v_lshrrev_b32_e32 v64, 4, v64
	v_perm_b32 v82, v83, v82, s52
	v_lshl_add_u64 v[4:5], v[116:117], 0, s[0:1]
	v_readlane_b32 s0, v250, 38
	v_readlane_b32 s1, v250, 39
	v_perm_b32 v83, v81, v84, s53
	v_perm_b32 v81, v81, v84, s54
	v_lshl_add_u64 v[8:9], v[116:117], 0, s[0:1]
	v_readlane_b32 s0, v170, 24
	v_and_b32_e32 v64, 0xf0f0f0f, v64
	v_lshl_add_u64 v[12:13], v[116:117], 0, s[56:57]
	v_dot4c_i32_i8_e32 v164, s0, v81
	v_perm_b32 v81, v82, v80, s53
	v_perm_b32 v80, v82, v80, s54
	v_dot4c_i32_i8_e32 v162, s0, v80
	v_perm_b32 v80, v76, v72, s33
	v_perm_b32 v72, v76, v72, s52
	v_perm_b32 v76, v64, v68, s33
	v_perm_b32 v64, v64, v68, s52
	v_perm_b32 v68, v76, v80, s53
	v_dot4c_i32_i8_e32 v159, s0, v68
	v_perm_b32 v68, v76, v80, s54
	v_dot4c_i32_i8_e32 v160, s0, v68
	v_perm_b32 v68, v64, v72, s53
	v_perm_b32 v64, v64, v72, s54
	v_dot4c_i32_i8_e32 v157, s0, v68
	v_dot4c_i32_i8_e32 v158, s0, v64
	v_and_b32_e32 v64, 0xf0f0f0f, v73
	v_lshrrev_b32_e32 v68, 4, v73
	v_and_b32_e32 v72, 0xf0f0f0f, v77
	v_lshrrev_b32_e32 v73, 4, v77
	v_and_b32_e32 v76, 0xf0f0f0f, v69
	v_and_b32_e32 v77, 0xf0f0f0f, v65
	v_perm_b32 v80, v72, v64, s33
	v_perm_b32 v64, v72, v64, s52
	v_perm_b32 v72, v77, v76, s33
	v_lshrrev_b32_e32 v69, 4, v69
	v_lshrrev_b32_e32 v65, 4, v65
	v_perm_b32 v76, v77, v76, s52
	v_perm_b32 v77, v72, v80, s53
	v_perm_b32 v72, v72, v80, s54
	v_and_b32_e32 v68, 0xf0f0f0f, v68
	v_and_b32_e32 v73, 0xf0f0f0f, v73
	v_and_b32_e32 v69, 0xf0f0f0f, v69
	v_and_b32_e32 v65, 0xf0f0f0f, v65
	v_dot4c_i32_i8_e32 v154, s0, v72
	v_perm_b32 v72, v76, v64, s53
	v_perm_b32 v64, v76, v64, s54
	v_dot4c_i32_i8_e32 v149, s0, v72
	v_dot4c_i32_i8_e32 v150, s0, v64
	v_perm_b32 v64, v73, v68, s33
	v_perm_b32 v72, v65, v69, s33
	v_perm_b32 v68, v73, v68, s52
	v_perm_b32 v65, v65, v69, s52
	v_perm_b32 v69, v72, v64, s53
	v_perm_b32 v64, v72, v64, s54
	v_dot4c_i32_i8_e32 v146, s0, v64
	v_perm_b32 v64, v65, v68, s53
	v_dot4c_i32_i8_e32 v155, s0, v64
	v_perm_b32 v64, v65, v68, s54
	v_dot4c_i32_i8_e32 v156, s0, v64
	v_and_b32_e32 v64, 0xf0f0f0f, v74
	v_and_b32_e32 v68, 0xf0f0f0f, v78
	v_and_b32_e32 v72, 0xf0f0f0f, v70
	v_and_b32_e32 v73, 0xf0f0f0f, v66
	v_lshrrev_b32_e32 v65, 4, v74
	v_perm_b32 v74, v68, v64, s33
	v_perm_b32 v64, v68, v64, s52
	v_perm_b32 v68, v73, v72, s33
	v_dot4c_i32_i8_e32 v144, s0, v69
	v_lshrrev_b32_e32 v69, 4, v78
	v_lshrrev_b32_e32 v70, 4, v70
	v_lshrrev_b32_e32 v66, 4, v66
	v_perm_b32 v72, v73, v72, s52
	v_perm_b32 v73, v68, v74, s53
	v_perm_b32 v68, v68, v74, s54
	v_and_b32_e32 v65, 0xf0f0f0f, v65
	v_and_b32_e32 v69, 0xf0f0f0f, v69
	v_and_b32_e32 v70, 0xf0f0f0f, v70
	v_and_b32_e32 v66, 0xf0f0f0f, v66
	v_dot4c_i32_i8_e32 v153, s0, v68
	v_perm_b32 v68, v72, v64, s53
	v_perm_b32 v64, v72, v64, s54
	v_dot4c_i32_i8_e32 v147, s0, v68
	v_dot4c_i32_i8_e32 v148, s0, v64
	v_perm_b32 v64, v69, v65, s33
	v_perm_b32 v68, v66, v70, s33
	v_perm_b32 v65, v69, v65, s52
	v_perm_b32 v66, v66, v70, s52
	v_perm_b32 v69, v68, v64, s53
	v_perm_b32 v64, v68, v64, s54
	v_dot4c_i32_i8_e32 v145, s0, v64
	v_perm_b32 v64, v66, v65, s53
	v_dot4c_i32_i8_e32 v141, s0, v64
	v_perm_b32 v64, v66, v65, s54
	v_dot4c_i32_i8_e32 v143, s0, v69
	v_dot4c_i32_i8_e32 v142, s0, v64
	v_and_b32_e32 v64, 0xf0f0f0f, v75
	v_and_b32_e32 v66, 0xf0f0f0f, v79
	v_and_b32_e32 v69, 0xf0f0f0f, v71
	v_lshrrev_b32_e32 v70, 4, v71
	v_and_b32_e32 v71, 0xf0f0f0f, v67
	v_perm_b32 v72, v66, v64, s33
	v_perm_b32 v64, v66, v64, s52
	v_perm_b32 v66, v71, v69, s33
	v_lshrrev_b32_e32 v65, 4, v75
	v_lshrrev_b32_e32 v68, 4, v79
	v_lshrrev_b32_e32 v67, 4, v67
	v_perm_b32 v69, v71, v69, s52
	v_perm_b32 v71, v66, v72, s53
	v_perm_b32 v66, v66, v72, s54
	v_and_b32_e32 v65, 0xf0f0f0f, v65
	v_and_b32_e32 v68, 0xf0f0f0f, v68
	v_and_b32_e32 v70, 0xf0f0f0f, v70
	v_and_b32_e32 v67, 0xf0f0f0f, v67
	v_dot4c_i32_i8_e32 v140, s0, v66
	v_perm_b32 v66, v69, v64, s53
	v_perm_b32 v64, v69, v64, s54
	v_dot4c_i32_i8_e32 v137, s0, v66
	v_dot4c_i32_i8_e32 v139, s0, v64
	v_perm_b32 v64, v68, v65, s33
	v_perm_b32 v66, v67, v70, s33
	v_perm_b32 v65, v68, v65, s52
	v_perm_b32 v67, v67, v70, s52
	v_perm_b32 v68, v66, v64, s53
	v_perm_b32 v64, v66, v64, s54
	v_dot4c_i32_i8_e32 v135, s0, v64
	v_perm_b32 v64, v67, v65, s53
	v_dot4c_i32_i8_e32 v123, s0, v64
	v_perm_b32 v64, v67, v65, s54
	v_dot4c_i32_i8_e32 v125, s0, v64
	s_waitcnt vmcnt(3)
	v_and_b32_e32 v64, 0xf0f0f0f, v60
	s_waitcnt vmcnt(2)
	v_and_b32_e32 v65, 0xf0f0f0f, v56
	s_waitcnt vmcnt(1)
	v_and_b32_e32 v66, 0xf0f0f0f, v52
	s_waitcnt vmcnt(0)
; __device__ void phase_gather(const Params& p) {
;     ...
;         if (gi + 2 < 64 / GROWS) {
; #pragma unroll
;           for (int k = 0; k < GROWS; ++k) {
;             const int e = __builtin_amdgcn_readlane(idv, j0 + 2 * GROWS + k);
;             rr[(gi + 2) % 3][k] = *(const u32x4*)(vb + (size_t)e * 1024 + lane * 16);
;           }
;         }
; #pragma unroll
;         for (int sub = 0; sub < GROWS / 4; ++sub) {
;           const int W4 = __builtin_amdgcn_readlane(pkv, j0 + 4 * sub);
; #pragma unroll
;           for (int m = 0; m < 4; ++m) {
;             unsigned lo[4], hi[4];
; #pragma unroll
;             for (int k = 0; k < 4; ++k) {
;               const unsigned w = rr[gi % 3][sub * 4 + k][m];
;               lo[k] = w & 0x0f0f0f0fu;
;               hi[k] = (w >> 4) & 0x0f0f0f0fu;
;             }
;             {
;               const unsigned p01l = __builtin_amdgcn_perm(lo[1], lo[0], 0x05010400u), p01h = __builtin_amdgcn_perm(lo[1], lo[0], 0x07030602u);
;               const unsigned p23l = __builtin_amdgcn_perm(lo[3], lo[2], 0x05010400u), p23h = __builtin_amdgcn_perm(lo[3], lo[2], 0x07030602u);
;               acc[m * 8 + 0] = __builtin_amdgcn_sdot4((int)__builtin_amdgcn_perm(p23l, p01l, 0x05040100u), W4, acc[m * 8 + 0], false);
;               acc[m * 8 + 1] = __builtin_amdgcn_sdot4((int)__builtin_amdgcn_perm(p23l, p01l, 0x07060302u), W4, acc[m * 8 + 1], false);
;               acc[m * 8 + 2] = __builtin_amdgcn_sdot4((int)__builtin_amdgcn_perm(p23h, p01h, 0x05040100u), W4, acc[m * 8 + 2], false);
;               acc[m * 8 + 3] = __builtin_amdgcn_sdot4((int)__builtin_amdgcn_perm(p23h, p01h, 0x07060302u), W4, acc[m * 8 + 3], false);
;             }
;             {
;               const unsigned p01l = __builtin_amdgcn_perm(hi[1], hi[0], 0x05010400u), p01h = __builtin_amdgcn_perm(hi[1], hi[0], 0x07030602u);
;               const unsigned p23l = __builtin_amdgcn_perm(hi[3], hi[2], 0x05010400u), p23h = __builtin_amdgcn_perm(hi[3], hi[2], 0x07030602u);
;               acc[m * 8 + 4] = __builtin_amdgcn_sdot4((int)__builtin_amdgcn_perm(p23l, p01l, 0x05040100u), W4, acc[m * 8 + 4], false);
;               acc[m * 8 + 5] = __builtin_amdgcn_sdot4((int)__builtin_amdgcn_perm(p23l, p01l, 0x07060302u), W4, acc[m * 8 + 5], false);
;               acc[m * 8 + 6] = __builtin_amdgcn_sdot4((int)__builtin_amdgcn_perm(p23h, p01h, 0x05040100u), W4, acc[m * 8 + 6], false);
	v_and_b32_e32 v67, 0xf0f0f0f, v48
	v_dot4c_i32_i8_e32 v134, s0, v68
	v_perm_b32 v68, v65, v64, s33
	v_perm_b32 v64, v65, v64, s52
	v_perm_b32 v65, v67, v66, s33
	v_dot4c_i32_i8_e32 v163, s0, v83
	v_dot4c_i32_i8_e32 v161, s0, v81
	v_dot4c_i32_i8_e32 v152, s0, v77
	v_dot4c_i32_i8_e32 v151, s0, v73
	v_dot4c_i32_i8_e32 v136, s0, v71
	v_readlane_b32 s0, v170, 28
	v_lshrrev_b32_e32 v60, 4, v60
	v_lshrrev_b32_e32 v56, 4, v56
	v_lshrrev_b32_e32 v52, 4, v52
	v_lshrrev_b32_e32 v48, 4, v48
	v_perm_b32 v66, v67, v66, s52
	v_perm_b32 v67, v65, v68, s53
	v_perm_b32 v65, v65, v68, s54
	v_and_b32_e32 v60, 0xf0f0f0f, v60
	v_and_b32_e32 v56, 0xf0f0f0f, v56
	v_and_b32_e32 v52, 0xf0f0f0f, v52
	v_and_b32_e32 v48, 0xf0f0f0f, v48
	v_dot4c_i32_i8_e32 v164, s0, v65
	v_perm_b32 v65, v66, v64, s53
	v_perm_b32 v64, v66, v64, s54
	v_dot4c_i32_i8_e32 v162, s0, v64
	v_perm_b32 v64, v56, v60, s33
	v_perm_b32 v56, v56, v60, s52
	v_perm_b32 v60, v48, v52, s33
	v_perm_b32 v48, v48, v52, s52
	v_perm_b32 v52, v60, v64, s53
	v_dot4c_i32_i8_e32 v159, s0, v52
	v_perm_b32 v52, v60, v64, s54
	v_dot4c_i32_i8_e32 v160, s0, v52
	v_perm_b32 v52, v48, v56, s53
	v_perm_b32 v48, v48, v56, s54
	v_dot4c_i32_i8_e32 v157, s0, v52
	v_dot4c_i32_i8_e32 v158, s0, v48
	v_and_b32_e32 v48, 0xf0f0f0f, v61
	v_lshrrev_b32_e32 v52, 4, v61
	v_and_b32_e32 v56, 0xf0f0f0f, v57
	v_and_b32_e32 v60, 0xf0f0f0f, v53
	v_and_b32_e32 v61, 0xf0f0f0f, v49
	v_perm_b32 v64, v56, v48, s33
	v_perm_b32 v48, v56, v48, s52
	v_perm_b32 v56, v61, v60, s33
	v_lshrrev_b32_e32 v57, 4, v57
	v_lshrrev_b32_e32 v53, 4, v53
	v_lshrrev_b32_e32 v49, 4, v49
	v_perm_b32 v60, v61, v60, s52
	v_perm_b32 v61, v56, v64, s53
	v_perm_b32 v56, v56, v64, s54
	v_and_b32_e32 v52, 0xf0f0f0f, v52
	v_and_b32_e32 v57, 0xf0f0f0f, v57
	v_and_b32_e32 v53, 0xf0f0f0f, v53
	v_and_b32_e32 v49, 0xf0f0f0f, v49
	v_dot4c_i32_i8_e32 v154, s0, v56
	v_perm_b32 v56, v60, v48, s53
	v_perm_b32 v48, v60, v48, s54
	v_dot4c_i32_i8_e32 v149, s0, v56
	v_dot4c_i32_i8_e32 v150, s0, v48
	v_perm_b32 v48, v57, v52, s33
	v_perm_b32 v56, v49, v53, s33
	v_perm_b32 v52, v57, v52, s52
	v_perm_b32 v49, v49, v53, s52
	v_perm_b32 v53, v56, v48, s53
	v_perm_b32 v48, v56, v48, s54
	v_dot4c_i32_i8_e32 v146, s0, v48
	v_perm_b32 v48, v49, v52, s53
	v_dot4c_i32_i8_e32 v155, s0, v48
	v_perm_b32 v48, v49, v52, s54
	v_dot4c_i32_i8_e32 v156, s0, v48
	v_and_b32_e32 v48, 0xf0f0f0f, v62
	v_and_b32_e32 v52, 0xf0f0f0f, v58
	v_and_b32_e32 v56, 0xf0f0f0f, v54
	v_and_b32_e32 v57, 0xf0f0f0f, v50
	v_dot4c_i32_i8_e32 v144, s0, v53
	v_lshrrev_b32_e32 v53, 4, v58
	v_perm_b32 v58, v52, v48, s33
	v_perm_b32 v48, v52, v48, s52
	v_perm_b32 v52, v57, v56, s33
	v_lshrrev_b32_e32 v49, 4, v62
	v_lshrrev_b32_e32 v54, 4, v54
	v_lshrrev_b32_e32 v50, 4, v50
	v_perm_b32 v56, v57, v56, s52
	v_perm_b32 v57, v52, v58, s53
	v_perm_b32 v52, v52, v58, s54
	v_and_b32_e32 v49, 0xf0f0f0f, v49
	v_and_b32_e32 v53, 0xf0f0f0f, v53
	v_and_b32_e32 v54, 0xf0f0f0f, v54
	v_and_b32_e32 v50, 0xf0f0f0f, v50
	v_dot4c_i32_i8_e32 v153, s0, v52
	v_perm_b32 v52, v56, v48, s53
	v_perm_b32 v48, v56, v48, s54
	v_dot4c_i32_i8_e32 v147, s0, v52
	v_dot4c_i32_i8_e32 v148, s0, v48
	v_perm_b32 v48, v53, v49, s33
	v_perm_b32 v52, v50, v54, s33
	v_perm_b32 v49, v53, v49, s52
	v_perm_b32 v50, v50, v54, s52
	v_perm_b32 v53, v52, v48, s53
	v_perm_b32 v48, v52, v48, s54
	v_dot4c_i32_i8_e32 v145, s0, v48
	v_perm_b32 v48, v50, v49, s53
	v_dot4c_i32_i8_e32 v141, s0, v48
	v_perm_b32 v48, v50, v49, s54
	v_dot4c_i32_i8_e32 v143, s0, v53
	v_dot4c_i32_i8_e32 v142, s0, v48
	v_and_b32_e32 v48, 0xf0f0f0f, v63
	v_and_b32_e32 v50, 0xf0f0f0f, v59
	v_and_b32_e32 v53, 0xf0f0f0f, v55
	v_lshrrev_b32_e32 v54, 4, v55
	v_and_b32_e32 v55, 0xf0f0f0f, v51
	v_perm_b32 v56, v50, v48, s33
	v_perm_b32 v48, v50, v48, s52
	v_perm_b32 v50, v55, v53, s33
	v_lshrrev_b32_e32 v49, 4, v63
	v_lshrrev_b32_e32 v52, 4, v59
	v_lshrrev_b32_e32 v51, 4, v51
	v_perm_b32 v53, v55, v53, s52
	v_perm_b32 v55, v50, v56, s53
	v_perm_b32 v50, v50, v56, s54
	v_and_b32_e32 v49, 0xf0f0f0f, v49
	v_and_b32_e32 v52, 0xf0f0f0f, v52
	v_and_b32_e32 v54, 0xf0f0f0f, v54
	v_and_b32_e32 v51, 0xf0f0f0f, v51
	v_dot4c_i32_i8_e32 v140, s0, v50
	v_perm_b32 v50, v53, v48, s53
	v_perm_b32 v48, v53, v48, s54
	v_dot4c_i32_i8_e32 v137, s0, v50
	v_dot4c_i32_i8_e32 v139, s0, v48
	v_perm_b32 v48, v52, v49, s33
	v_perm_b32 v50, v51, v54, s33
	v_perm_b32 v49, v52, v49, s52
	v_perm_b32 v51, v51, v54, s52
	v_perm_b32 v52, v50, v48, s53
	v_perm_b32 v48, v50, v48, s54
	v_dot4c_i32_i8_e32 v135, s0, v48
	v_perm_b32 v48, v51, v49, s53
	v_dot4c_i32_i8_e32 v123, s0, v48
	v_perm_b32 v48, v51, v49, s54
	v_dot4c_i32_i8_e32 v163, s0, v67
	v_dot4c_i32_i8_e32 v161, s0, v65
	v_dot4c_i32_i8_e32 v152, s0, v61
	v_dot4c_i32_i8_e32 v151, s0, v57
	v_dot4c_i32_i8_e32 v136, s0, v55
	v_dot4c_i32_i8_e32 v134, s0, v52
	v_dot4c_i32_i8_e32 v125, s0, v48
	v_readlane_b32 s0, v250, 40
	v_readlane_b32 s1, v250, 41
	global_load_dwordx4 v[0:3], v[0:1], off
	v_lshl_add_u64 v[16:17], v[116:117], 0, s[58:59]
	v_lshl_add_u64 v[48:49], v[116:117], 0, s[0:1]
	v_readlane_b32 s0, v250, 42
	v_readlane_b32 s1, v250, 43
	global_load_dwordx4 v[64:67], v[48:49], off
	v_lshl_add_u64 v[20:21], v[116:117], 0, s[60:61]
	v_lshl_add_u64 v[48:49], v[116:117], 0, s[0:1]
	v_readlane_b32 s0, v250, 44
	v_readlane_b32 s1, v250, 45
	global_load_dwordx4 v[68:71], v[48:49], off
	v_and_b32_e32 v50, 0xf0f0f0f, v104
	v_lshl_add_u64 v[48:49], v[116:117], 0, s[0:1]
	v_readlane_b32 s0, v250, 46
	v_readlane_b32 s1, v250, 47
	global_load_dwordx4 v[72:75], v[48:49], off
	v_and_b32_e32 v52, 0xf0f0f0f, v100
	v_lshl_add_u64 v[48:49], v[116:117], 0, s[0:1]
	v_readlane_b32 s0, v250, 48
	v_readlane_b32 s1, v250, 49
; __device__ void phase_gather(const Params& p) {
;     ...
;         if (gi + 2 < 64 / GROWS) {
; #pragma unroll
;           for (int k = 0; k < GROWS; ++k) {
;             const int e = __builtin_amdgcn_readlane(idv, j0 + 2 * GROWS + k);
;             rr[(gi + 2) % 3][k] = *(const u32x4*)(vb + (size_t)e * 1024 + lane * 16);
;           }
;         }
; #pragma unroll
;         for (int sub = 0; sub < GROWS / 4; ++sub) {
;           const int W4 = __builtin_amdgcn_readlane(pkv, j0 + 4 * sub);
; #pragma unroll
;           for (int m = 0; m < 4; ++m) {
;             unsigned lo[4], hi[4];
; #pragma unroll
;             for (int k = 0; k < 4; ++k) {
;               const unsigned w = rr[gi % 3][sub * 4 + k][m];
;               lo[k] = w & 0x0f0f0f0fu;
;               hi[k] = (w >> 4) & 0x0f0f0f0fu;
;             }
;             {
;               const unsigned p01l = __builtin_amdgcn_perm(lo[1], lo[0], 0x05010400u), p01h = __builtin_amdgcn_perm(lo[1], lo[0], 0x07030602u);
;               const unsigned p23l = __builtin_amdgcn_perm(lo[3], lo[2], 0x05010400u), p23h = __builtin_amdgcn_perm(lo[3], lo[2], 0x07030602u);
;               acc[m * 8 + 0] = __builtin_amdgcn_sdot4((int)__builtin_amdgcn_perm(p23l, p01l, 0x05040100u), W4, acc[m * 8 + 0], false);
;               acc[m * 8 + 1] = __builtin_amdgcn_sdot4((int)__builtin_amdgcn_perm(p23l, p01l, 0x07060302u), W4, acc[m * 8 + 1], false);
;               acc[m * 8 + 2] = __builtin_amdgcn_sdot4((int)__builtin_amdgcn_perm(p23h, p01h, 0x05040100u), W4, acc[m * 8 + 2], false);
;               acc[m * 8 + 3] = __builtin_amdgcn_sdot4((int)__builtin_amdgcn_perm(p23h, p01h, 0x07060302u), W4, acc[m * 8 + 3], false);
;             }
;             {
;               const unsigned p01l = __builtin_amdgcn_perm(hi[1], hi[0], 0x05010400u), p01h = __builtin_amdgcn_perm(hi[1], hi[0], 0x07030602u);
;               const unsigned p23l = __builtin_amdgcn_perm(hi[3], hi[2], 0x05010400u), p23h = __builtin_amdgcn_perm(hi[3], hi[2], 0x07030602u);
;               acc[m * 8 + 4] = __builtin_amdgcn_sdot4((int)__builtin_amdgcn_perm(p23l, p01l, 0x05040100u), W4, acc[m * 8 + 4], false);
;               acc[m * 8 + 5] = __builtin_amdgcn_sdot4((int)__builtin_amdgcn_perm(p23l, p01l, 0x07060302u), W4, acc[m * 8 + 5], false);
;               acc[m * 8 + 6] = __builtin_amdgcn_sdot4((int)__builtin_amdgcn_perm(p23h, p01h, 0x05040100u), W4, acc[m * 8 + 6], false);
	global_load_dwordx4 v[76:79], v[48:49], off
	v_and_b32_e32 v54, 0xf0f0f0f, v96
	v_lshl_add_u64 v[48:49], v[116:117], 0, s[0:1]
	v_readlane_b32 s0, v250, 50
	v_readlane_b32 s1, v250, 51
	global_load_dwordx4 v[80:83], v[48:49], off
	v_lshrrev_b32_e32 v51, 4, v104
	v_lshl_add_u64 v[48:49], v[116:117], 0, s[0:1]
	v_readlane_b32 s0, v250, 52
	v_readlane_b32 s1, v250, 53
	global_load_dwordx4 v[4:7], v[4:5], off
	v_lshrrev_b32_e32 v53, 4, v100
	global_load_dwordx4 v[8:11], v[8:9], off
	v_lshrrev_b32_e32 v55, 4, v96
	global_load_dwordx4 v[12:15], v[12:13], off
	v_and_b32_e32 v51, 0xf0f0f0f, v51
	global_load_dwordx4 v[84:87], v[48:49], off
	v_lshl_add_u64 v[48:49], v[116:117], 0, s[0:1]
	v_readlane_b32 s0, v250, 54
	global_load_dwordx4 v[16:19], v[16:17], off
	v_readlane_b32 s1, v250, 55
	global_load_dwordx4 v[20:23], v[20:21], off
	v_and_b32_e32 v53, 0xf0f0f0f, v53
	global_load_dwordx4 v[88:91], v[48:49], off
	v_lshl_add_u64 v[48:49], v[116:117], 0, s[0:1]
	global_load_dwordx4 v[92:95], v[48:49], off
	v_and_b32_e32 v48, 0xf0f0f0f, v108
	v_perm_b32 v56, v50, v48, s33
	v_perm_b32 v48, v50, v48, s52
	v_perm_b32 v50, v54, v52, s33
	v_readlane_b32 s0, v170, 32
	v_lshrrev_b32_e32 v49, 4, v108
	v_perm_b32 v52, v54, v52, s52
	v_perm_b32 v54, v50, v56, s53
	v_perm_b32 v50, v50, v56, s54
	v_and_b32_e32 v49, 0xf0f0f0f, v49
	v_and_b32_e32 v55, 0xf0f0f0f, v55
	v_dot4c_i32_i8_e32 v164, s0, v50
	v_perm_b32 v50, v52, v48, s53
	v_perm_b32 v48, v52, v48, s54
	v_dot4c_i32_i8_e32 v161, s0, v50
	v_dot4c_i32_i8_e32 v162, s0, v48
	v_perm_b32 v48, v51, v49, s33
	v_perm_b32 v50, v55, v53, s33
	v_perm_b32 v49, v51, v49, s52
	v_perm_b32 v51, v55, v53, s52
	v_perm_b32 v52, v50, v48, s53
	v_perm_b32 v48, v50, v48, s54
	v_dot4c_i32_i8_e32 v160, s0, v48
	v_perm_b32 v48, v51, v49, s53
	v_dot4c_i32_i8_e32 v157, s0, v48
	v_perm_b32 v48, v51, v49, s54
	v_dot4c_i32_i8_e32 v163, s0, v54
	v_dot4c_i32_i8_e32 v159, s0, v52
	v_dot4c_i32_i8_e32 v158, s0, v48
	v_and_b32_e32 v48, 0xf0f0f0f, v109
	v_and_b32_e32 v50, 0xf0f0f0f, v105
	v_and_b32_e32 v52, 0xf0f0f0f, v101
	v_and_b32_e32 v54, 0xf0f0f0f, v97
	v_perm_b32 v56, v50, v48, s33
	v_perm_b32 v48, v50, v48, s52
	v_perm_b32 v50, v54, v52, s33
	v_lshrrev_b32_e32 v49, 4, v109
	v_lshrrev_b32_e32 v51, 4, v105
	v_lshrrev_b32_e32 v53, 4, v101
	v_lshrrev_b32_e32 v55, 4, v97
	v_perm_b32 v52, v54, v52, s52
	v_perm_b32 v54, v50, v56, s53
	v_perm_b32 v50, v50, v56, s54
	v_and_b32_e32 v49, 0xf0f0f0f, v49
	v_and_b32_e32 v51, 0xf0f0f0f, v51
	v_and_b32_e32 v53, 0xf0f0f0f, v53
	v_and_b32_e32 v55, 0xf0f0f0f, v55
	v_dot4c_i32_i8_e32 v154, s0, v50
	v_perm_b32 v50, v52, v48, s53
	v_perm_b32 v48, v52, v48, s54
	v_dot4c_i32_i8_e32 v149, s0, v50
	v_dot4c_i32_i8_e32 v150, s0, v48
	v_perm_b32 v48, v51, v49, s33
	v_perm_b32 v50, v55, v53, s33
	v_perm_b32 v49, v51, v49, s52
	v_perm_b32 v51, v55, v53, s52
	v_perm_b32 v52, v50, v48, s53
	v_perm_b32 v48, v50, v48, s54
	v_dot4c_i32_i8_e32 v146, s0, v48
	v_perm_b32 v48, v51, v49, s53
	v_dot4c_i32_i8_e32 v155, s0, v48
	v_perm_b32 v48, v51, v49, s54
	v_dot4c_i32_i8_e32 v152, s0, v54
	v_dot4c_i32_i8_e32 v144, s0, v52
	v_dot4c_i32_i8_e32 v156, s0, v48
	v_and_b32_e32 v48, 0xf0f0f0f, v110
	v_and_b32_e32 v50, 0xf0f0f0f, v106
	v_and_b32_e32 v52, 0xf0f0f0f, v102
	v_and_b32_e32 v54, 0xf0f0f0f, v98
	v_perm_b32 v56, v50, v48, s33
	v_perm_b32 v48, v50, v48, s52
	v_perm_b32 v50, v54, v52, s33
	v_lshrrev_b32_e32 v49, 4, v110
	v_lshrrev_b32_e32 v51, 4, v106
	v_lshrrev_b32_e32 v53, 4, v102
	v_lshrrev_b32_e32 v55, 4, v98
	v_perm_b32 v52, v54, v52, s52
	v_perm_b32 v54, v50, v56, s53
	v_perm_b32 v50, v50, v56, s54
	v_and_b32_e32 v49, 0xf0f0f0f, v49
	v_and_b32_e32 v51, 0xf0f0f0f, v51
	v_and_b32_e32 v53, 0xf0f0f0f, v53
	v_and_b32_e32 v55, 0xf0f0f0f, v55
	v_dot4c_i32_i8_e32 v153, s0, v50
	v_perm_b32 v50, v52, v48, s53
	v_perm_b32 v48, v52, v48, s54
	v_dot4c_i32_i8_e32 v147, s0, v50
	v_dot4c_i32_i8_e32 v148, s0, v48
	v_perm_b32 v48, v51, v49, s33
	v_perm_b32 v50, v55, v53, s33
	v_perm_b32 v49, v51, v49, s52
	v_perm_b32 v51, v55, v53, s52
	v_perm_b32 v52, v50, v48, s53
	v_perm_b32 v48, v50, v48, s54
	v_dot4c_i32_i8_e32 v145, s0, v48
	v_perm_b32 v48, v51, v49, s53
	v_dot4c_i32_i8_e32 v141, s0, v48
	v_perm_b32 v48, v51, v49, s54
	v_dot4c_i32_i8_e32 v151, s0, v54
	v_dot4c_i32_i8_e32 v143, s0, v52
	v_dot4c_i32_i8_e32 v142, s0, v48
	v_and_b32_e32 v48, 0xf0f0f0f, v111
	v_and_b32_e32 v50, 0xf0f0f0f, v107
	v_and_b32_e32 v52, 0xf0f0f0f, v103
	v_and_b32_e32 v54, 0xf0f0f0f, v99
	v_perm_b32 v56, v50, v48, s33
	v_perm_b32 v48, v50, v48, s52
	v_perm_b32 v50, v54, v52, s33
	v_lshrrev_b32_e32 v49, 4, v111
	v_lshrrev_b32_e32 v51, 4, v107
	v_lshrrev_b32_e32 v53, 4, v103
	v_lshrrev_b32_e32 v55, 4, v99
	v_perm_b32 v52, v54, v52, s52
	v_perm_b32 v54, v50, v56, s53
	v_perm_b32 v50, v50, v56, s54
	v_and_b32_e32 v49, 0xf0f0f0f, v49
	v_and_b32_e32 v51, 0xf0f0f0f, v51
	v_and_b32_e32 v53, 0xf0f0f0f, v53
	v_and_b32_e32 v55, 0xf0f0f0f, v55
	v_dot4c_i32_i8_e32 v140, s0, v50
	v_perm_b32 v50, v52, v48, s53
	v_perm_b32 v48, v52, v48, s54
	v_dot4c_i32_i8_e32 v137, s0, v50
	v_dot4c_i32_i8_e32 v139, s0, v48
	v_perm_b32 v48, v51, v49, s33
	v_perm_b32 v50, v55, v53, s33
	v_perm_b32 v49, v51, v49, s52
	v_perm_b32 v51, v55, v53, s52
	v_perm_b32 v52, v50, v48, s53
	v_perm_b32 v48, v50, v48, s54
	v_dot4c_i32_i8_e32 v135, s0, v48
	v_perm_b32 v48, v51, v49, s53
	v_dot4c_i32_i8_e32 v123, s0, v48
	v_perm_b32 v48, v51, v49, s54
	v_dot4c_i32_i8_e32 v125, s0, v48
	v_and_b32_e32 v48, 0xf0f0f0f, v44
	v_and_b32_e32 v49, 0xf0f0f0f, v40
	v_and_b32_e32 v50, 0xf0f0f0f, v36
	v_and_b32_e32 v51, 0xf0f0f0f, v32
	v_dot4c_i32_i8_e32 v134, s0, v52
	v_perm_b32 v52, v49, v48, s33
	v_perm_b32 v48, v49, v48, s52
; __device__ void phase_gather(const Params& p) {
;     ...
;         if (gi + 2 < 64 / GROWS) {
; #pragma unroll
;           for (int k = 0; k < GROWS; ++k) {
;             const int e = __builtin_amdgcn_readlane(idv, j0 + 2 * GROWS + k);
;             rr[(gi + 2) % 3][k] = *(const u32x4*)(vb + (size_t)e * 1024 + lane * 16);
;           }
;         }
; #pragma unroll
;         for (int sub = 0; sub < GROWS / 4; ++sub) {
;           const int W4 = __builtin_amdgcn_readlane(pkv, j0 + 4 * sub);
; #pragma unroll
;           for (int m = 0; m < 4; ++m) {
;             unsigned lo[4], hi[4];
; #pragma unroll
;             for (int k = 0; k < 4; ++k) {
;               const unsigned w = rr[gi % 3][sub * 4 + k][m];
;               lo[k] = w & 0x0f0f0f0fu;
;               hi[k] = (w >> 4) & 0x0f0f0f0fu;
;             }
;             {
;               const unsigned p01l = __builtin_amdgcn_perm(lo[1], lo[0], 0x05010400u), p01h = __builtin_amdgcn_perm(lo[1], lo[0], 0x07030602u);
;               const unsigned p23l = __builtin_amdgcn_perm(lo[3], lo[2], 0x05010400u), p23h = __builtin_amdgcn_perm(lo[3], lo[2], 0x07030602u);
;               acc[m * 8 + 0] = __builtin_amdgcn_sdot4((int)__builtin_amdgcn_perm(p23l, p01l, 0x05040100u), W4, acc[m * 8 + 0], false);
;               acc[m * 8 + 1] = __builtin_amdgcn_sdot4((int)__builtin_amdgcn_perm(p23l, p01l, 0x07060302u), W4, acc[m * 8 + 1], false);
;               acc[m * 8 + 2] = __builtin_amdgcn_sdot4((int)__builtin_amdgcn_perm(p23h, p01h, 0x05040100u), W4, acc[m * 8 + 2], false);
;               acc[m * 8 + 3] = __builtin_amdgcn_sdot4((int)__builtin_amdgcn_perm(p23h, p01h, 0x07060302u), W4, acc[m * 8 + 3], false);
;             }
;             {
;               const unsigned p01l = __builtin_amdgcn_perm(hi[1], hi[0], 0x05010400u), p01h = __builtin_amdgcn_perm(hi[1], hi[0], 0x07030602u);
;               const unsigned p23l = __builtin_amdgcn_perm(hi[3], hi[2], 0x05010400u), p23h = __builtin_amdgcn_perm(hi[3], hi[2], 0x07030602u);
;               acc[m * 8 + 4] = __builtin_amdgcn_sdot4((int)__builtin_amdgcn_perm(p23l, p01l, 0x05040100u), W4, acc[m * 8 + 4], false);
;               acc[m * 8 + 5] = __builtin_amdgcn_sdot4((int)__builtin_amdgcn_perm(p23l, p01l, 0x07060302u), W4, acc[m * 8 + 5], false);
;               acc[m * 8 + 6] = __builtin_amdgcn_sdot4((int)__builtin_amdgcn_perm(p23h, p01h, 0x05040100u), W4, acc[m * 8 + 6], false);
	v_perm_b32 v49, v51, v50, s33
	v_dot4c_i32_i8_e32 v136, s0, v54
	v_readlane_b32 s0, v170, 36
	v_lshrrev_b32_e32 v44, 4, v44
	v_lshrrev_b32_e32 v40, 4, v40
	v_lshrrev_b32_e32 v36, 4, v36
	v_lshrrev_b32_e32 v32, 4, v32
	v_perm_b32 v50, v51, v50, s52
	v_perm_b32 v51, v49, v52, s53
	v_perm_b32 v49, v49, v52, s54
	v_and_b32_e32 v44, 0xf0f0f0f, v44
	v_and_b32_e32 v40, 0xf0f0f0f, v40
	v_and_b32_e32 v36, 0xf0f0f0f, v36
	v_and_b32_e32 v32, 0xf0f0f0f, v32
	v_dot4c_i32_i8_e32 v164, s0, v49
	v_perm_b32 v49, v50, v48, s53
	v_perm_b32 v48, v50, v48, s54
	v_dot4c_i32_i8_e32 v162, s0, v48
	v_perm_b32 v48, v40, v44, s33
	v_perm_b32 v40, v40, v44, s52
	v_perm_b32 v44, v32, v36, s33
	v_perm_b32 v32, v32, v36, s52
	v_perm_b32 v36, v44, v48, s53
	v_dot4c_i32_i8_e32 v159, s0, v36
	v_perm_b32 v36, v44, v48, s54
	v_dot4c_i32_i8_e32 v160, s0, v36
	v_perm_b32 v36, v32, v40, s53
	v_perm_b32 v32, v32, v40, s54
	v_dot4c_i32_i8_e32 v157, s0, v36
	v_dot4c_i32_i8_e32 v158, s0, v32
	v_and_b32_e32 v32, 0xf0f0f0f, v45
	v_lshrrev_b32_e32 v36, 4, v45
	v_and_b32_e32 v40, 0xf0f0f0f, v41
	v_and_b32_e32 v44, 0xf0f0f0f, v37
	v_and_b32_e32 v45, 0xf0f0f0f, v33
	v_perm_b32 v48, v40, v32, s33
	v_perm_b32 v32, v40, v32, s52
	v_perm_b32 v40, v45, v44, s33
	v_lshrrev_b32_e32 v41, 4, v41
	v_lshrrev_b32_e32 v37, 4, v37
	v_lshrrev_b32_e32 v33, 4, v33
	v_perm_b32 v44, v45, v44, s52
	v_perm_b32 v45, v40, v48, s53
	v_perm_b32 v40, v40, v48, s54
	v_and_b32_e32 v36, 0xf0f0f0f, v36
	v_and_b32_e32 v41, 0xf0f0f0f, v41
	v_and_b32_e32 v37, 0xf0f0f0f, v37
	v_and_b32_e32 v33, 0xf0f0f0f, v33
	v_dot4c_i32_i8_e32 v154, s0, v40
	v_perm_b32 v40, v44, v32, s53
	v_perm_b32 v32, v44, v32, s54
	v_dot4c_i32_i8_e32 v149, s0, v40
	v_dot4c_i32_i8_e32 v150, s0, v32
	v_perm_b32 v32, v41, v36, s33
	v_perm_b32 v40, v33, v37, s33
	v_perm_b32 v36, v41, v36, s52
	v_perm_b32 v33, v33, v37, s52
	v_perm_b32 v37, v40, v32, s53
	v_perm_b32 v32, v40, v32, s54
	v_dot4c_i32_i8_e32 v146, s0, v32
	v_perm_b32 v32, v33, v36, s53
	v_dot4c_i32_i8_e32 v155, s0, v32
	v_perm_b32 v32, v33, v36, s54
	v_dot4c_i32_i8_e32 v156, s0, v32
	v_and_b32_e32 v32, 0xf0f0f0f, v46
	v_and_b32_e32 v36, 0xf0f0f0f, v42
	v_and_b32_e32 v40, 0xf0f0f0f, v38
	v_and_b32_e32 v41, 0xf0f0f0f, v34
	v_dot4c_i32_i8_e32 v144, s0, v37
	v_lshrrev_b32_e32 v37, 4, v42
	v_perm_b32 v42, v36, v32, s33
	v_perm_b32 v32, v36, v32, s52
	v_perm_b32 v36, v41, v40, s33
	v_lshrrev_b32_e32 v33, 4, v46
	v_lshrrev_b32_e32 v38, 4, v38
	v_lshrrev_b32_e32 v34, 4, v34
	v_perm_b32 v40, v41, v40, s52
	v_perm_b32 v41, v36, v42, s53
	v_perm_b32 v36, v36, v42, s54
	v_and_b32_e32 v33, 0xf0f0f0f, v33
	v_and_b32_e32 v37, 0xf0f0f0f, v37
	v_and_b32_e32 v38, 0xf0f0f0f, v38
	v_and_b32_e32 v34, 0xf0f0f0f, v34
	v_dot4c_i32_i8_e32 v153, s0, v36
	v_perm_b32 v36, v40, v32, s53
	v_perm_b32 v32, v40, v32, s54
	v_dot4c_i32_i8_e32 v147, s0, v36
	v_dot4c_i32_i8_e32 v148, s0, v32
	v_perm_b32 v32, v37, v33, s33
	v_perm_b32 v36, v34, v38, s33
	v_perm_b32 v33, v37, v33, s52
	v_perm_b32 v34, v34, v38, s52
	v_perm_b32 v37, v36, v32, s53
	v_perm_b32 v32, v36, v32, s54
	v_dot4c_i32_i8_e32 v145, s0, v32
	v_perm_b32 v32, v34, v33, s53
	v_dot4c_i32_i8_e32 v141, s0, v32
	v_perm_b32 v32, v34, v33, s54
	v_dot4c_i32_i8_e32 v143, s0, v37
	v_dot4c_i32_i8_e32 v142, s0, v32
	v_and_b32_e32 v32, 0xf0f0f0f, v47
	v_and_b32_e32 v34, 0xf0f0f0f, v43
	v_and_b32_e32 v37, 0xf0f0f0f, v39
	v_lshrrev_b32_e32 v38, 4, v39
	v_and_b32_e32 v39, 0xf0f0f0f, v35
	v_perm_b32 v40, v34, v32, s33
	v_perm_b32 v32, v34, v32, s52
	v_perm_b32 v34, v39, v37, s33
	v_lshrrev_b32_e32 v33, 4, v47
	v_lshrrev_b32_e32 v36, 4, v43
	v_lshrrev_b32_e32 v35, 4, v35
	v_perm_b32 v37, v39, v37, s52
	v_perm_b32 v39, v34, v40, s53
	v_perm_b32 v34, v34, v40, s54
	v_and_b32_e32 v33, 0xf0f0f0f, v33
	v_and_b32_e32 v36, 0xf0f0f0f, v36
	v_and_b32_e32 v38, 0xf0f0f0f, v38
	v_and_b32_e32 v35, 0xf0f0f0f, v35
	v_dot4c_i32_i8_e32 v140, s0, v34
	v_perm_b32 v34, v37, v32, s53
	v_perm_b32 v32, v37, v32, s54
	v_dot4c_i32_i8_e32 v137, s0, v34
	v_dot4c_i32_i8_e32 v139, s0, v32
	v_perm_b32 v32, v36, v33, s33
	v_perm_b32 v34, v35, v38, s33
	v_perm_b32 v33, v36, v33, s52
	v_perm_b32 v35, v35, v38, s52
	v_perm_b32 v36, v34, v32, s53
	v_perm_b32 v32, v34, v32, s54
	v_dot4c_i32_i8_e32 v135, s0, v32
	v_perm_b32 v32, v35, v33, s53
	v_dot4c_i32_i8_e32 v123, s0, v32
	v_perm_b32 v32, v35, v33, s54
	v_dot4c_i32_i8_e32 v163, s0, v51
	v_dot4c_i32_i8_e32 v161, s0, v49
	v_dot4c_i32_i8_e32 v152, s0, v45
	v_dot4c_i32_i8_e32 v151, s0, v41
	v_dot4c_i32_i8_e32 v136, s0, v39
	v_dot4c_i32_i8_e32 v134, s0, v36
	v_dot4c_i32_i8_e32 v125, s0, v32
	v_readlane_b32 s0, v250, 6
	v_readlane_b32 s1, v250, 7
	s_waitcnt vmcnt(5)
	v_lshrrev_b32_e32 v176, 4, v15
	v_lshrrev_b32_e32 v177, 4, v11
	v_lshl_add_u64 v[32:33], v[116:117], 0, s[0:1]
	v_readlane_b32 s0, v250, 4
	v_readlane_b32 s1, v250, 5
	global_load_dwordx4 v[60:63], v[32:33], off
	v_lshrrev_b32_e32 v179, 4, v7
	v_lshl_add_u64 v[32:33], v[116:117], 0, s[0:1]
	v_readlane_b32 s0, v250, 14
	v_readlane_b32 s1, v250, 15
	global_load_dwordx4 v[56:59], v[32:33], off
	v_lshrrev_b32_e32 v180, 4, v3
	v_lshl_add_u64 v[32:33], v[116:117], 0, s[0:1]
	v_readlane_b32 s0, v250, 10
	v_readlane_b32 s1, v250, 11
	global_load_dwordx4 v[52:55], v[32:33], off
	v_lshrrev_b32_e32 v110, 4, v31
	v_lshl_add_u64 v[32:33], v[116:117], 0, s[0:1]
	v_readlane_b32 s0, v250, 12
	v_readlane_b32 s1, v250, 13
	global_load_dwordx4 v[48:51], v[32:33], off
	v_lshrrev_b32_e32 v111, 4, v27
	v_lshl_add_u64 v[32:33], v[116:117], 0, s[0:1]
	v_readlane_b32 s0, v250, 2
	v_readlane_b32 s1, v250, 3
	global_load_dwordx4 v[44:47], v[32:33], off
	s_waitcnt vmcnt(7)
; __device__ void phase_gather(const Params& p) {
;     ...
; #pragma unroll
;         for (int sub = 0; sub < GROWS / 4; ++sub) {
;           const int W4 = __builtin_amdgcn_readlane(pkv, j0 + 4 * sub);
; #pragma unroll
;           for (int m = 0; m < 4; ++m) {
;             unsigned lo[4], hi[4];
; #pragma unroll
;             for (int k = 0; k < 4; ++k) {
;               const unsigned w = rr[gi % 3][sub * 4 + k][m];
;               lo[k] = w & 0x0f0f0f0fu;
;               hi[k] = (w >> 4) & 0x0f0f0f0fu;
;             }
;             {
;               const unsigned p01l = __builtin_amdgcn_perm(lo[1], lo[0], 0x05010400u), p01h = __builtin_amdgcn_perm(lo[1], lo[0], 0x07030602u);
;               const unsigned p23l = __builtin_amdgcn_perm(lo[3], lo[2], 0x05010400u), p23h = __builtin_amdgcn_perm(lo[3], lo[2], 0x07030602u);
;               acc[m * 8 + 0] = __builtin_amdgcn_sdot4((int)__builtin_amdgcn_perm(p23l, p01l, 0x05040100u), W4, acc[m * 8 + 0], false);
;               acc[m * 8 + 1] = __builtin_amdgcn_sdot4((int)__builtin_amdgcn_perm(p23l, p01l, 0x07060302u), W4, acc[m * 8 + 1], false);
;               acc[m * 8 + 2] = __builtin_amdgcn_sdot4((int)__builtin_amdgcn_perm(p23h, p01h, 0x05040100u), W4, acc[m * 8 + 2], false);
;               acc[m * 8 + 3] = __builtin_amdgcn_sdot4((int)__builtin_amdgcn_perm(p23h, p01h, 0x07060302u), W4, acc[m * 8 + 3], false);
;             }
;             {
;               const unsigned p01l = __builtin_amdgcn_perm(hi[1], hi[0], 0x05010400u), p01h = __builtin_amdgcn_perm(hi[1], hi[0], 0x07030602u);
;               const unsigned p23l = __builtin_amdgcn_perm(hi[3], hi[2], 0x05010400u), p23h = __builtin_amdgcn_perm(hi[3], hi[2], 0x07030602u);
;               acc[m * 8 + 4] = __builtin_amdgcn_sdot4((int)__builtin_amdgcn_perm(p23l, p01l, 0x05040100u), W4, acc[m * 8 + 4], false);
;               acc[m * 8 + 5] = __builtin_amdgcn_sdot4((int)__builtin_amdgcn_perm(p23l, p01l, 0x07060302u), W4, acc[m * 8 + 5], false);
;               acc[m * 8 + 6] = __builtin_amdgcn_sdot4((int)__builtin_amdgcn_perm(p23h, p01h, 0x05040100u), W4, acc[m * 8 + 6], false);
;               acc[m * 8 + 7] = __builtin_amdgcn_sdot4((int)__builtin_amdgcn_perm(p23h, p01h, 0x07060302u), W4, acc[m * 8 + 7], false);
;             }
;           }
	v_lshrrev_b32_e32 v172, 4, v23
	v_lshl_add_u64 v[32:33], v[116:117], 0, s[0:1]
	v_readlane_b32 s0, v250, 0
	v_readlane_b32 s1, v250, 1
	global_load_dwordx4 v[40:43], v[32:33], off
	v_lshrrev_b32_e32 v173, 4, v19
	v_lshl_add_u64 v[32:33], v[116:117], 0, s[0:1]
	v_readlane_b32 s0, v250, 16
	v_and_b32_e32 v176, 0xf0f0f0f, v176
	v_and_b32_e32 v177, 0xf0f0f0f, v177
	v_and_b32_e32 v179, 0xf0f0f0f, v179
	v_and_b32_e32 v180, 0xf0f0f0f, v180
	v_readlane_b32 s1, v250, 17
	v_lshrrev_b32_e32 v103, 4, v79
	v_lshrrev_b32_e32 v104, 4, v75
	v_lshrrev_b32_e32 v106, 4, v71
	v_lshrrev_b32_e32 v107, 4, v67
	v_and_b32_e32 v110, 0xf0f0f0f, v110
	v_and_b32_e32 v111, 0xf0f0f0f, v111
	v_and_b32_e32 v172, 0xf0f0f0f, v172
	v_and_b32_e32 v173, 0xf0f0f0f, v173
	v_perm_b32 v178, v176, v177, s52
	v_perm_b32 v181, v179, v180, s52
	global_load_dwordx4 v[36:39], v[32:33], off
	v_lshl_add_u64 v[32:33], v[116:117], 0, s[0:1]
	v_readlane_b32 s0, v170, 40
	s_waitcnt vmcnt(7)
	v_lshrrev_b32_e32 v96, 4, v95
	v_lshrrev_b32_e32 v97, 4, v91
	v_lshrrev_b32_e32 v99, 4, v87
	v_lshrrev_b32_e32 v100, 4, v83
	v_and_b32_e32 v103, 0xf0f0f0f, v103
	v_and_b32_e32 v104, 0xf0f0f0f, v104
	v_and_b32_e32 v106, 0xf0f0f0f, v106
	v_and_b32_e32 v107, 0xf0f0f0f, v107
	v_perm_b32 v171, v110, v111, s52
	v_perm_b32 v174, v172, v173, s52
	v_perm_b32 v182, v178, v181, s54
	v_readlane_b32 s1, v170, 44
	v_and_b32_e32 v96, 0xf0f0f0f, v96
	v_and_b32_e32 v97, 0xf0f0f0f, v97
	v_and_b32_e32 v99, 0xf0f0f0f, v99
	v_and_b32_e32 v100, 0xf0f0f0f, v100
	v_perm_b32 v105, v103, v104, s52
	v_perm_b32 v108, v106, v107, s52
	v_perm_b32 v175, v171, v174, s54
	v_dot4c_i32_i8_e32 v125, s0, v182
	v_perm_b32 v98, v96, v97, s52
	v_perm_b32 v101, v99, v100, s52
	v_perm_b32 v109, v105, v108, s54
	v_dot4c_i32_i8_e32 v125, s1, v175
	v_perm_b32 v102, v98, v101, s54
	v_dot4c_i32_i8_e32 v125, s2, v109
	v_perm_b32 v98, v98, v101, s53
	v_perm_b32 v101, v105, v108, s53
	v_perm_b32 v105, v178, v181, s53
	v_dot4c_i32_i8_e32 v125, s3, v102
	v_perm_b32 v102, v171, v174, s53
	v_dot4c_i32_i8_e32 v123, s0, v105
	v_perm_b32 v96, v96, v97, s33
	v_perm_b32 v97, v99, v100, s33
	v_perm_b32 v100, v106, v107, s33
	v_perm_b32 v105, v176, v177, s33
	v_perm_b32 v106, v179, v180, s33
	v_dot4c_i32_i8_e32 v123, s1, v102
	v_perm_b32 v99, v103, v104, s33
	v_perm_b32 v102, v110, v111, s33
	v_perm_b32 v103, v172, v173, s33
	v_perm_b32 v107, v105, v106, s54
	v_perm_b32 v104, v102, v103, s54
	v_dot4c_i32_i8_e32 v135, s0, v107
	v_dot4c_i32_i8_e32 v123, s2, v101
	v_perm_b32 v101, v99, v100, s54
	v_dot4c_i32_i8_e32 v135, s1, v104
	v_dot4c_i32_i8_e32 v123, s3, v98
	v_perm_b32 v98, v96, v97, s54
	v_dot4c_i32_i8_e32 v135, s2, v101
	v_perm_b32 v96, v96, v97, s53
	v_perm_b32 v97, v99, v100, s53
	v_perm_b32 v99, v105, v106, s53
	v_and_b32_e32 v15, 0xf0f0f0f, v15
	v_and_b32_e32 v11, 0xf0f0f0f, v11
	v_and_b32_e32 v7, 0xf0f0f0f, v7
	v_and_b32_e32 v3, 0xf0f0f0f, v3
	v_dot4c_i32_i8_e32 v135, s3, v98
	v_perm_b32 v98, v102, v103, s53
	v_dot4c_i32_i8_e32 v134, s0, v99
	v_and_b32_e32 v31, 0xf0f0f0f, v31
	v_and_b32_e32 v27, 0xf0f0f0f, v27
	v_and_b32_e32 v23, 0xf0f0f0f, v23
	v_and_b32_e32 v19, 0xf0f0f0f, v19
	v_perm_b32 v105, v15, v11, s52
	v_perm_b32 v106, v7, v3, s52
	v_dot4c_i32_i8_e32 v134, s1, v98
	v_and_b32_e32 v79, 0xf0f0f0f, v79
	v_and_b32_e32 v75, 0xf0f0f0f, v75
	v_and_b32_e32 v71, 0xf0f0f0f, v71
	v_and_b32_e32 v67, 0xf0f0f0f, v67
	v_perm_b32 v102, v31, v27, s52
	v_perm_b32 v103, v23, v19, s52
	v_perm_b32 v107, v105, v106, s54
	v_dot4c_i32_i8_e32 v134, s2, v97
	v_and_b32_e32 v95, 0xf0f0f0f, v95
	v_and_b32_e32 v91, 0xf0f0f0f, v91
	v_and_b32_e32 v87, 0xf0f0f0f, v87
	v_and_b32_e32 v83, 0xf0f0f0f, v83
	v_perm_b32 v99, v79, v75, s52
	v_perm_b32 v100, v71, v67, s52
	v_perm_b32 v104, v102, v103, s54
	v_dot4c_i32_i8_e32 v139, s0, v107
	v_dot4c_i32_i8_e32 v134, s3, v96
	v_perm_b32 v96, v95, v91, s52
	v_perm_b32 v97, v87, v83, s52
	v_perm_b32 v101, v99, v100, s54
	v_dot4c_i32_i8_e32 v139, s1, v104
	v_perm_b32 v98, v96, v97, s54
	v_dot4c_i32_i8_e32 v139, s2, v101
	v_perm_b32 v96, v96, v97, s53
	v_perm_b32 v97, v99, v100, s53
	v_perm_b32 v99, v105, v106, s53
	v_perm_b32 v11, v15, v11, s33
	v_perm_b32 v3, v7, v3, s33
	v_dot4c_i32_i8_e32 v139, s3, v98
	v_perm_b32 v98, v102, v103, s53
	v_dot4c_i32_i8_e32 v137, s0, v99
	v_perm_b32 v27, v31, v27, s33
	v_perm_b32 v19, v23, v19, s33
	v_perm_b32 v7, v11, v3, s54
	v_perm_b32 v3, v11, v3, s53
	v_dot4c_i32_i8_e32 v137, s1, v98
	v_perm_b32 v91, v95, v91, s33
	v_perm_b32 v83, v87, v83, s33
	v_perm_b32 v75, v79, v75, s33
	v_perm_b32 v67, v71, v67, s33
	v_perm_b32 v23, v27, v19, s54
	v_perm_b32 v19, v27, v19, s53
	v_dot4c_i32_i8_e32 v136, s0, v3
	v_lshrrev_b32_e32 v101, 4, v14
	v_lshrrev_b32_e32 v102, 4, v10
	v_lshrrev_b32_e32 v104, 4, v6
	v_lshrrev_b32_e32 v105, 4, v2
	v_dot4c_i32_i8_e32 v137, s2, v97
	v_perm_b32 v87, v91, v83, s54
	v_dot4c_i32_i8_e32 v140, s0, v7
	v_perm_b32 v7, v91, v83, s53
	v_perm_b32 v15, v75, v67, s53
	v_dot4c_i32_i8_e32 v136, s1, v19
	v_lshrrev_b32_e32 v91, 4, v30
	v_lshrrev_b32_e32 v95, 4, v26
	v_lshrrev_b32_e32 v97, 4, v22
	v_lshrrev_b32_e32 v98, 4, v18
	v_and_b32_e32 v101, 0xf0f0f0f, v101
	v_and_b32_e32 v102, 0xf0f0f0f, v102
	v_and_b32_e32 v104, 0xf0f0f0f, v104
	v_and_b32_e32 v105, 0xf0f0f0f, v105
	v_perm_b32 v71, v75, v67, s54
	v_dot4c_i32_i8_e32 v136, s2, v15
	v_lshrrev_b32_e32 v31, 4, v78
	v_lshrrev_b32_e32 v67, 4, v74
	v_lshrrev_b32_e32 v75, 4, v70
	v_lshrrev_b32_e32 v79, 4, v66
	v_and_b32_e32 v91, 0xf0f0f0f, v91
	v_and_b32_e32 v95, 0xf0f0f0f, v95
	v_and_b32_e32 v97, 0xf0f0f0f, v97
	v_and_b32_e32 v98, 0xf0f0f0f, v98
	v_perm_b32 v103, v101, v102, s52
	v_perm_b32 v106, v104, v105, s52
	v_dot4c_i32_i8_e32 v137, s3, v96
; __device__ void phase_gather(const Params& p) {
;     ...
; #pragma unroll
;         for (int sub = 0; sub < GROWS / 4; ++sub) {
;           const int W4 = __builtin_amdgcn_readlane(pkv, j0 + 4 * sub);
; #pragma unroll
;           for (int m = 0; m < 4; ++m) {
;             unsigned lo[4], hi[4];
; #pragma unroll
;             for (int k = 0; k < 4; ++k) {
;               const unsigned w = rr[gi % 3][sub * 4 + k][m];
;               lo[k] = w & 0x0f0f0f0fu;
;               hi[k] = (w >> 4) & 0x0f0f0f0fu;
;             }
;             {
;               const unsigned p01l = __builtin_amdgcn_perm(lo[1], lo[0], 0x05010400u), p01h = __builtin_amdgcn_perm(lo[1], lo[0], 0x07030602u);
;               const unsigned p23l = __builtin_amdgcn_perm(lo[3], lo[2], 0x05010400u), p23h = __builtin_amdgcn_perm(lo[3], lo[2], 0x07030602u);
;               acc[m * 8 + 0] = __builtin_amdgcn_sdot4((int)__builtin_amdgcn_perm(p23l, p01l, 0x05040100u), W4, acc[m * 8 + 0], false);
;               acc[m * 8 + 1] = __builtin_amdgcn_sdot4((int)__builtin_amdgcn_perm(p23l, p01l, 0x07060302u), W4, acc[m * 8 + 1], false);
;               acc[m * 8 + 2] = __builtin_amdgcn_sdot4((int)__builtin_amdgcn_perm(p23h, p01h, 0x05040100u), W4, acc[m * 8 + 2], false);
;               acc[m * 8 + 3] = __builtin_amdgcn_sdot4((int)__builtin_amdgcn_perm(p23h, p01h, 0x07060302u), W4, acc[m * 8 + 3], false);
;             }
;             {
;               const unsigned p01l = __builtin_amdgcn_perm(hi[1], hi[0], 0x05010400u), p01h = __builtin_amdgcn_perm(hi[1], hi[0], 0x07030602u);
;               const unsigned p23l = __builtin_amdgcn_perm(hi[3], hi[2], 0x05010400u), p23h = __builtin_amdgcn_perm(hi[3], hi[2], 0x07030602u);
;               acc[m * 8 + 4] = __builtin_amdgcn_sdot4((int)__builtin_amdgcn_perm(p23l, p01l, 0x05040100u), W4, acc[m * 8 + 4], false);
;               acc[m * 8 + 5] = __builtin_amdgcn_sdot4((int)__builtin_amdgcn_perm(p23l, p01l, 0x07060302u), W4, acc[m * 8 + 5], false);
;               acc[m * 8 + 6] = __builtin_amdgcn_sdot4((int)__builtin_amdgcn_perm(p23h, p01h, 0x05040100u), W4, acc[m * 8 + 6], false);
;               acc[m * 8 + 7] = __builtin_amdgcn_sdot4((int)__builtin_amdgcn_perm(p23h, p01h, 0x07060302u), W4, acc[m * 8 + 7], false);
;             }
;           }
	v_dot4c_i32_i8_e32 v140, s1, v23
	v_dot4c_i32_i8_e32 v136, s3, v7
	v_lshrrev_b32_e32 v3, 4, v94
	v_lshrrev_b32_e32 v7, 4, v90
	v_lshrrev_b32_e32 v15, 4, v86
	v_lshrrev_b32_e32 v19, 4, v82
	v_and_b32_e32 v31, 0xf0f0f0f, v31
	v_and_b32_e32 v67, 0xf0f0f0f, v67
	v_and_b32_e32 v75, 0xf0f0f0f, v75
	v_and_b32_e32 v79, 0xf0f0f0f, v79
	v_perm_b32 v96, v91, v95, s52
	v_perm_b32 v99, v97, v98, s52
	v_perm_b32 v107, v103, v106, s54
	v_dot4c_i32_i8_e32 v140, s2, v71
	v_and_b32_e32 v3, 0xf0f0f0f, v3
	v_and_b32_e32 v7, 0xf0f0f0f, v7
	v_and_b32_e32 v15, 0xf0f0f0f, v15
	v_and_b32_e32 v19, 0xf0f0f0f, v19
	v_perm_b32 v71, v31, v67, s52
	v_perm_b32 v83, v75, v79, s52
	v_perm_b32 v100, v96, v99, s54
	v_dot4c_i32_i8_e32 v142, s0, v107
	v_dot4c_i32_i8_e32 v140, s3, v87
	v_perm_b32 v11, v3, v7, s52
	v_perm_b32 v23, v15, v19, s52
	v_perm_b32 v87, v71, v83, s54
	v_dot4c_i32_i8_e32 v142, s1, v100
	v_perm_b32 v27, v11, v23, s54
	v_dot4c_i32_i8_e32 v142, s2, v87
	v_perm_b32 v11, v11, v23, s53
	v_perm_b32 v23, v71, v83, s53
	v_perm_b32 v71, v103, v106, s53
	v_dot4c_i32_i8_e32 v142, s3, v27
	v_perm_b32 v27, v96, v99, s53
	v_dot4c_i32_i8_e32 v141, s0, v71
	v_perm_b32 v3, v3, v7, s33
	v_perm_b32 v7, v15, v19, s33
	v_perm_b32 v19, v75, v79, s33
	v_perm_b32 v71, v101, v102, s33
	v_perm_b32 v75, v104, v105, s33
	v_dot4c_i32_i8_e32 v141, s1, v27
	v_perm_b32 v15, v31, v67, s33
	v_perm_b32 v27, v91, v95, s33
	v_perm_b32 v31, v97, v98, s33
	v_perm_b32 v79, v71, v75, s54
	v_perm_b32 v67, v27, v31, s54
	v_dot4c_i32_i8_e32 v145, s0, v79
	v_dot4c_i32_i8_e32 v141, s2, v23
	v_perm_b32 v23, v15, v19, s54
	v_dot4c_i32_i8_e32 v145, s1, v67
	v_dot4c_i32_i8_e32 v141, s3, v11
	v_perm_b32 v11, v3, v7, s54
	v_dot4c_i32_i8_e32 v145, s2, v23
	v_perm_b32 v3, v3, v7, s53
	v_perm_b32 v7, v15, v19, s53
	v_perm_b32 v15, v71, v75, s53
	v_dot4c_i32_i8_e32 v145, s3, v11
	v_perm_b32 v11, v27, v31, s53
	v_dot4c_i32_i8_e32 v143, s0, v15
	v_and_b32_e32 v14, 0xf0f0f0f, v14
	v_and_b32_e32 v10, 0xf0f0f0f, v10
	v_and_b32_e32 v6, 0xf0f0f0f, v6
	v_and_b32_e32 v2, 0xf0f0f0f, v2
	v_dot4c_i32_i8_e32 v143, s1, v11
	v_and_b32_e32 v15, 0xf0f0f0f, v86
	v_and_b32_e32 v30, 0xf0f0f0f, v30
	v_and_b32_e32 v26, 0xf0f0f0f, v26
	v_and_b32_e32 v22, 0xf0f0f0f, v22
	v_and_b32_e32 v18, 0xf0f0f0f, v18
	v_perm_b32 v83, v14, v10, s52
	v_perm_b32 v86, v6, v2, s52
	v_dot4c_i32_i8_e32 v143, s2, v7
	v_and_b32_e32 v31, 0xf0f0f0f, v78
	v_and_b32_e32 v67, 0xf0f0f0f, v74
	v_and_b32_e32 v70, 0xf0f0f0f, v70
	v_and_b32_e32 v66, 0xf0f0f0f, v66
	v_perm_b32 v78, v30, v26, s52
	v_perm_b32 v79, v22, v18, s52
	v_perm_b32 v87, v83, v86, s54
	v_dot4c_i32_i8_e32 v143, s3, v3
	v_and_b32_e32 v3, 0xf0f0f0f, v94
	v_and_b32_e32 v7, 0xf0f0f0f, v90
	v_and_b32_e32 v19, 0xf0f0f0f, v82
	v_perm_b32 v71, v31, v67, s52
	v_perm_b32 v74, v70, v66, s52
	v_perm_b32 v82, v78, v79, s54
	v_dot4c_i32_i8_e32 v148, s0, v87
	v_perm_b32 v11, v3, v7, s52
	v_perm_b32 v23, v15, v19, s52
	v_perm_b32 v75, v71, v74, s54
	v_dot4c_i32_i8_e32 v148, s1, v82
	v_perm_b32 v27, v11, v23, s54
	v_dot4c_i32_i8_e32 v148, s2, v75
	v_perm_b32 v11, v11, v23, s53
	v_perm_b32 v23, v71, v74, s53
	v_perm_b32 v71, v83, v86, s53
	global_load_dwordx4 v[32:35], v[32:33], off
	v_dot4c_i32_i8_e32 v148, s3, v27
	v_perm_b32 v27, v78, v79, s53
	v_dot4c_i32_i8_e32 v147, s0, v71
	v_dot4c_i32_i8_e32 v147, s1, v27
	v_perm_b32 v10, v14, v10, s33
	v_perm_b32 v2, v6, v2, s33
	v_dot4c_i32_i8_e32 v147, s2, v23
	v_perm_b32 v3, v3, v7, s33
	v_perm_b32 v7, v15, v19, s33
	v_perm_b32 v26, v30, v26, s33
	v_perm_b32 v18, v22, v18, s33
	v_perm_b32 v6, v10, v2, s54
	v_perm_b32 v2, v10, v2, s53
	v_dot4c_i32_i8_e32 v147, s3, v11
	v_perm_b32 v11, v3, v7, s54
	v_perm_b32 v15, v31, v67, s33
	v_perm_b32 v19, v70, v66, s33
	v_perm_b32 v22, v26, v18, s54
	v_dot4c_i32_i8_e32 v153, s0, v6
	v_perm_b32 v3, v3, v7, s53
	v_perm_b32 v7, v26, v18, s53
	v_dot4c_i32_i8_e32 v151, s0, v2
	v_lshrrev_b32_e32 v75, 4, v13
	v_lshrrev_b32_e32 v78, 4, v9
	v_lshrrev_b32_e32 v82, 4, v5
	v_lshrrev_b32_e32 v83, 4, v1
	v_perm_b32 v23, v15, v19, s54
	v_dot4c_i32_i8_e32 v153, s1, v22
	v_perm_b32 v6, v15, v19, s53
	v_dot4c_i32_i8_e32 v151, s1, v7
	v_lshrrev_b32_e32 v30, 4, v29
	v_lshrrev_b32_e32 v31, 4, v25
	v_lshrrev_b32_e32 v67, 4, v21
	v_lshrrev_b32_e32 v70, 4, v17
	v_and_b32_e32 v75, 0xf0f0f0f, v75
	v_and_b32_e32 v78, 0xf0f0f0f, v78
	v_and_b32_e32 v82, 0xf0f0f0f, v82
	v_and_b32_e32 v83, 0xf0f0f0f, v83
	v_dot4c_i32_i8_e32 v153, s2, v23
	v_dot4c_i32_i8_e32 v151, s2, v6
	v_lshrrev_b32_e32 v15, 4, v77
	v_lshrrev_b32_e32 v18, 4, v73
	v_lshrrev_b32_e32 v22, 4, v69
	v_lshrrev_b32_e32 v23, 4, v65
	v_and_b32_e32 v30, 0xf0f0f0f, v30
	v_and_b32_e32 v31, 0xf0f0f0f, v31
	v_and_b32_e32 v67, 0xf0f0f0f, v67
	v_and_b32_e32 v70, 0xf0f0f0f, v70
	v_perm_b32 v79, v75, v78, s52
	v_perm_b32 v86, v82, v83, s52
	v_dot4c_i32_i8_e32 v151, s3, v3
	v_lshrrev_b32_e32 v2, 4, v93
	v_lshrrev_b32_e32 v3, 4, v89
	v_lshrrev_b32_e32 v7, 4, v85
	v_lshrrev_b32_e32 v10, 4, v81
	v_and_b32_e32 v15, 0xf0f0f0f, v15
	v_and_b32_e32 v18, 0xf0f0f0f, v18
	v_and_b32_e32 v22, 0xf0f0f0f, v22
	v_and_b32_e32 v23, 0xf0f0f0f, v23
	v_perm_b32 v66, v30, v31, s52
	v_perm_b32 v71, v67, v70, s52
	v_perm_b32 v87, v79, v86, s54
	v_and_b32_e32 v2, 0xf0f0f0f, v2
	v_and_b32_e32 v3, 0xf0f0f0f, v3
	v_and_b32_e32 v7, 0xf0f0f0f, v7
	v_and_b32_e32 v10, 0xf0f0f0f, v10
	v_perm_b32 v19, v15, v18, s52
	v_perm_b32 v26, v22, v23, s52
	v_perm_b32 v74, v66, v71, s54
	v_dot4c_i32_i8_e32 v156, s0, v87
	v_dot4c_i32_i8_e32 v153, s3, v11
	v_perm_b32 v6, v2, v3, s52
	v_perm_b32 v11, v7, v10, s52
	v_perm_b32 v27, v19, v26, s54
	v_dot4c_i32_i8_e32 v156, s1, v74
	v_perm_b32 v14, v6, v11, s54
	v_dot4c_i32_i8_e32 v156, s2, v27
; __device__ void phase_gather(const Params& p) {
;     ...
; #pragma unroll
;         for (int sub = 0; sub < GROWS / 4; ++sub) {
;           const int W4 = __builtin_amdgcn_readlane(pkv, j0 + 4 * sub);
; #pragma unroll
;           for (int m = 0; m < 4; ++m) {
;             unsigned lo[4], hi[4];
; #pragma unroll
;             for (int k = 0; k < 4; ++k) {
;               const unsigned w = rr[gi % 3][sub * 4 + k][m];
;               lo[k] = w & 0x0f0f0f0fu;
;               hi[k] = (w >> 4) & 0x0f0f0f0fu;
;             }
;             {
;               const unsigned p01l = __builtin_amdgcn_perm(lo[1], lo[0], 0x05010400u), p01h = __builtin_amdgcn_perm(lo[1], lo[0], 0x07030602u);
;               const unsigned p23l = __builtin_amdgcn_perm(lo[3], lo[2], 0x05010400u), p23h = __builtin_amdgcn_perm(lo[3], lo[2], 0x07030602u);
;               acc[m * 8 + 0] = __builtin_amdgcn_sdot4((int)__builtin_amdgcn_perm(p23l, p01l, 0x05040100u), W4, acc[m * 8 + 0], false);
;               acc[m * 8 + 1] = __builtin_amdgcn_sdot4((int)__builtin_amdgcn_perm(p23l, p01l, 0x07060302u), W4, acc[m * 8 + 1], false);
;               acc[m * 8 + 2] = __builtin_amdgcn_sdot4((int)__builtin_amdgcn_perm(p23h, p01h, 0x05040100u), W4, acc[m * 8 + 2], false);
;               acc[m * 8 + 3] = __builtin_amdgcn_sdot4((int)__builtin_amdgcn_perm(p23h, p01h, 0x07060302u), W4, acc[m * 8 + 3], false);
;             }
;             {
;               const unsigned p01l = __builtin_amdgcn_perm(hi[1], hi[0], 0x05010400u), p01h = __builtin_amdgcn_perm(hi[1], hi[0], 0x07030602u);
;               const unsigned p23l = __builtin_amdgcn_perm(hi[3], hi[2], 0x05010400u), p23h = __builtin_amdgcn_perm(hi[3], hi[2], 0x07030602u);
;               acc[m * 8 + 4] = __builtin_amdgcn_sdot4((int)__builtin_amdgcn_perm(p23l, p01l, 0x05040100u), W4, acc[m * 8 + 4], false);
;               acc[m * 8 + 5] = __builtin_amdgcn_sdot4((int)__builtin_amdgcn_perm(p23l, p01l, 0x07060302u), W4, acc[m * 8 + 5], false);
;               acc[m * 8 + 6] = __builtin_amdgcn_sdot4((int)__builtin_amdgcn_perm(p23h, p01h, 0x05040100u), W4, acc[m * 8 + 6], false);
;               acc[m * 8 + 7] = __builtin_amdgcn_sdot4((int)__builtin_amdgcn_perm(p23h, p01h, 0x07060302u), W4, acc[m * 8 + 7], false);
;             }
;           }
	v_perm_b32 v6, v6, v11, s53
	v_perm_b32 v11, v19, v26, s53
	v_perm_b32 v19, v79, v86, s53
	v_dot4c_i32_i8_e32 v156, s3, v14
	v_perm_b32 v14, v66, v71, s53
	v_dot4c_i32_i8_e32 v155, s0, v19
	v_perm_b32 v2, v2, v3, s33
	v_perm_b32 v3, v7, v10, s33
	v_perm_b32 v10, v22, v23, s33
	v_perm_b32 v19, v75, v78, s33
	v_perm_b32 v22, v82, v83, s33
	v_dot4c_i32_i8_e32 v155, s1, v14
	v_perm_b32 v7, v15, v18, s33
	v_perm_b32 v14, v30, v31, s33
	v_perm_b32 v15, v67, v70, s33
	v_perm_b32 v23, v19, v22, s54
	v_perm_b32 v18, v14, v15, s54
	v_dot4c_i32_i8_e32 v146, s0, v23
	v_dot4c_i32_i8_e32 v155, s2, v11
	v_perm_b32 v11, v7, v10, s54
	v_dot4c_i32_i8_e32 v146, s1, v18
	v_dot4c_i32_i8_e32 v155, s3, v6
	v_perm_b32 v6, v2, v3, s54
	v_dot4c_i32_i8_e32 v146, s2, v11
	v_perm_b32 v2, v2, v3, s53
	v_perm_b32 v3, v7, v10, s53
	v_perm_b32 v7, v19, v22, s53
	v_dot4c_i32_i8_e32 v146, s3, v6
	v_perm_b32 v6, v14, v15, s53
	v_dot4c_i32_i8_e32 v144, s0, v7
	v_and_b32_e32 v13, 0xf0f0f0f, v13
	v_and_b32_e32 v9, 0xf0f0f0f, v9
	v_and_b32_e32 v5, 0xf0f0f0f, v5
	v_and_b32_e32 v1, 0xf0f0f0f, v1
	v_dot4c_i32_i8_e32 v144, s1, v6
	v_and_b32_e32 v29, 0xf0f0f0f, v29
	v_and_b32_e32 v25, 0xf0f0f0f, v25
	v_and_b32_e32 v21, 0xf0f0f0f, v21
	v_and_b32_e32 v17, 0xf0f0f0f, v17
	v_perm_b32 v66, v13, v9, s52
	v_perm_b32 v67, v5, v1, s52
	v_dot4c_i32_i8_e32 v144, s2, v3
	v_and_b32_e32 v15, 0xf0f0f0f, v77
	v_and_b32_e32 v18, 0xf0f0f0f, v73
	v_and_b32_e32 v22, 0xf0f0f0f, v69
	v_and_b32_e32 v23, 0xf0f0f0f, v65
	v_perm_b32 v30, v29, v25, s52
	v_perm_b32 v31, v21, v17, s52
	v_perm_b32 v69, v66, v67, s54
	v_dot4c_i32_i8_e32 v144, s3, v2
	v_and_b32_e32 v2, 0xf0f0f0f, v93
	v_and_b32_e32 v3, 0xf0f0f0f, v89
	v_and_b32_e32 v7, 0xf0f0f0f, v85
	v_and_b32_e32 v10, 0xf0f0f0f, v81
	v_perm_b32 v19, v15, v18, s52
	v_perm_b32 v26, v22, v23, s52
	v_perm_b32 v65, v30, v31, s54
	v_dot4c_i32_i8_e32 v150, s0, v69
	v_perm_b32 v6, v2, v3, s52
	v_perm_b32 v11, v7, v10, s52
	v_perm_b32 v27, v19, v26, s54
	v_dot4c_i32_i8_e32 v150, s1, v65
	v_perm_b32 v14, v6, v11, s54
	v_dot4c_i32_i8_e32 v150, s2, v27
	v_perm_b32 v6, v6, v11, s53
	v_perm_b32 v11, v19, v26, s53
	v_perm_b32 v19, v66, v67, s53
	v_dot4c_i32_i8_e32 v150, s3, v14
	v_perm_b32 v14, v30, v31, s53
	v_dot4c_i32_i8_e32 v149, s0, v19
	v_perm_b32 v9, v13, v9, s33
	v_perm_b32 v1, v5, v1, s33
	v_dot4c_i32_i8_e32 v149, s1, v14
	v_perm_b32 v2, v2, v3, s33
	v_perm_b32 v3, v7, v10, s33
	v_perm_b32 v7, v15, v18, s33
	v_perm_b32 v14, v29, v25, s33
	v_perm_b32 v15, v21, v17, s33
	v_perm_b32 v5, v9, v1, s54
	v_perm_b32 v1, v9, v1, s53
	v_dot4c_i32_i8_e32 v149, s2, v11
	v_perm_b32 v10, v22, v23, s33
	v_perm_b32 v17, v14, v15, s54
	v_dot4c_i32_i8_e32 v154, s0, v5
	v_perm_b32 v5, v14, v15, s53
	v_dot4c_i32_i8_e32 v152, s0, v1
	v_lshrrev_b32_e32 v29, 4, v12
	v_lshrrev_b32_e32 v30, 4, v8
	v_lshrrev_b32_e32 v65, 4, v4
	v_lshrrev_b32_e32 v66, 4, v0
	v_dot4c_i32_i8_e32 v149, s3, v6
	v_perm_b32 v6, v2, v3, s54
	v_perm_b32 v11, v7, v10, s54
	v_dot4c_i32_i8_e32 v154, s1, v17
	v_perm_b32 v2, v2, v3, s53
	v_perm_b32 v3, v7, v10, s53
	v_dot4c_i32_i8_e32 v152, s1, v5
	v_lshrrev_b32_e32 v19, 4, v28
	v_lshrrev_b32_e32 v21, 4, v24
	v_lshrrev_b32_e32 v23, 4, v20
	v_lshrrev_b32_e32 v25, 4, v16
	v_and_b32_e32 v29, 0xf0f0f0f, v29
	v_and_b32_e32 v30, 0xf0f0f0f, v30
	v_and_b32_e32 v65, 0xf0f0f0f, v65
	v_and_b32_e32 v66, 0xf0f0f0f, v66
	v_dot4c_i32_i8_e32 v154, s2, v11
	v_dot4c_i32_i8_e32 v152, s2, v3
	v_lshrrev_b32_e32 v10, 4, v76
	v_lshrrev_b32_e32 v11, 4, v72
	v_lshrrev_b32_e32 v14, 4, v68
	v_lshrrev_b32_e32 v15, 4, v64
	v_and_b32_e32 v19, 0xf0f0f0f, v19
	v_and_b32_e32 v21, 0xf0f0f0f, v21
	v_and_b32_e32 v23, 0xf0f0f0f, v23
	v_and_b32_e32 v25, 0xf0f0f0f, v25
	v_perm_b32 v31, v29, v30, s52
	v_perm_b32 v67, v65, v66, s52
	v_dot4c_i32_i8_e32 v154, s3, v6
	v_dot4c_i32_i8_e32 v152, s3, v2
	v_lshrrev_b32_e32 v1, 4, v92
	v_lshrrev_b32_e32 v2, 4, v88
	v_lshrrev_b32_e32 v5, 4, v84
	v_lshrrev_b32_e32 v6, 4, v80
	v_and_b32_e32 v10, 0xf0f0f0f, v10
	v_and_b32_e32 v11, 0xf0f0f0f, v11
	v_and_b32_e32 v14, 0xf0f0f0f, v14
	v_and_b32_e32 v15, 0xf0f0f0f, v15
	v_perm_b32 v22, v19, v21, s52
	v_perm_b32 v26, v23, v25, s52
	v_perm_b32 v69, v31, v67, s54
	v_and_b32_e32 v1, 0xf0f0f0f, v1
	v_and_b32_e32 v2, 0xf0f0f0f, v2
	v_and_b32_e32 v5, 0xf0f0f0f, v5
	v_and_b32_e32 v6, 0xf0f0f0f, v6
	v_perm_b32 v13, v10, v11, s52
	v_perm_b32 v17, v14, v15, s52
	v_perm_b32 v27, v22, v26, s54
	v_dot4c_i32_i8_e32 v158, s0, v69
	v_perm_b32 v3, v1, v2, s52
	v_perm_b32 v7, v5, v6, s52
	v_perm_b32 v18, v13, v17, s54
	v_dot4c_i32_i8_e32 v158, s1, v27
	v_perm_b32 v9, v3, v7, s54
	v_dot4c_i32_i8_e32 v158, s2, v18
	v_perm_b32 v3, v3, v7, s53
	v_perm_b32 v7, v13, v17, s53
	v_perm_b32 v13, v31, v67, s53
	v_dot4c_i32_i8_e32 v158, s3, v9
	v_perm_b32 v9, v22, v26, s53
	v_dot4c_i32_i8_e32 v157, s0, v13
	v_perm_b32 v1, v1, v2, s33
	v_perm_b32 v2, v5, v6, s33
	v_perm_b32 v6, v14, v15, s33
	v_perm_b32 v13, v29, v30, s33
	v_perm_b32 v14, v65, v66, s33
	v_dot4c_i32_i8_e32 v157, s1, v9
	v_perm_b32 v5, v10, v11, s33
	v_perm_b32 v9, v19, v21, s33
	v_perm_b32 v10, v23, v25, s33
	v_perm_b32 v15, v13, v14, s54
	v_perm_b32 v11, v9, v10, s54
	v_dot4c_i32_i8_e32 v160, s0, v15
	v_dot4c_i32_i8_e32 v157, s2, v7
	v_perm_b32 v7, v5, v6, s54
	v_dot4c_i32_i8_e32 v160, s1, v11
	v_dot4c_i32_i8_e32 v157, s3, v3
	v_perm_b32 v3, v1, v2, s54
	v_dot4c_i32_i8_e32 v160, s2, v7
	v_perm_b32 v1, v1, v2, s53
	v_perm_b32 v2, v5, v6, s53
	v_perm_b32 v5, v13, v14, s53
	v_dot4c_i32_i8_e32 v160, s3, v3
	v_perm_b32 v3, v9, v10, s53
	v_dot4c_i32_i8_e32 v159, s0, v5
	v_and_b32_e32 v12, 0xf0f0f0f, v12
	v_and_b32_e32 v8, 0xf0f0f0f, v8
	v_and_b32_e32 v4, 0xf0f0f0f, v4
	v_and_b32_e32 v0, 0xf0f0f0f, v0
; __device__ void phase_gather(const Params& p) {
;     ...
; #pragma unroll
;         for (int sub = 0; sub < GROWS / 4; ++sub) {
;           const int W4 = __builtin_amdgcn_readlane(pkv, j0 + 4 * sub);
; #pragma unroll
;           for (int m = 0; m < 4; ++m) {
;             unsigned lo[4], hi[4];
; #pragma unroll
;             for (int k = 0; k < 4; ++k) {
;               const unsigned w = rr[gi % 3][sub * 4 + k][m];
;               lo[k] = w & 0x0f0f0f0fu;
;               hi[k] = (w >> 4) & 0x0f0f0f0fu;
;             }
;             {
;               const unsigned p01l = __builtin_amdgcn_perm(lo[1], lo[0], 0x05010400u), p01h = __builtin_amdgcn_perm(lo[1], lo[0], 0x07030602u);
;               const unsigned p23l = __builtin_amdgcn_perm(lo[3], lo[2], 0x05010400u), p23h = __builtin_amdgcn_perm(lo[3], lo[2], 0x07030602u);
;               acc[m * 8 + 0] = __builtin_amdgcn_sdot4((int)__builtin_amdgcn_perm(p23l, p01l, 0x05040100u), W4, acc[m * 8 + 0], false);
;               acc[m * 8 + 1] = __builtin_amdgcn_sdot4((int)__builtin_amdgcn_perm(p23l, p01l, 0x07060302u), W4, acc[m * 8 + 1], false);
;               acc[m * 8 + 2] = __builtin_amdgcn_sdot4((int)__builtin_amdgcn_perm(p23h, p01h, 0x05040100u), W4, acc[m * 8 + 2], false);
;               acc[m * 8 + 3] = __builtin_amdgcn_sdot4((int)__builtin_amdgcn_perm(p23h, p01h, 0x07060302u), W4, acc[m * 8 + 3], false);
;             }
;             {
;               const unsigned p01l = __builtin_amdgcn_perm(hi[1], hi[0], 0x05010400u), p01h = __builtin_amdgcn_perm(hi[1], hi[0], 0x07030602u);
;               const unsigned p23l = __builtin_amdgcn_perm(hi[3], hi[2], 0x05010400u), p23h = __builtin_amdgcn_perm(hi[3], hi[2], 0x07030602u);
;               acc[m * 8 + 4] = __builtin_amdgcn_sdot4((int)__builtin_amdgcn_perm(p23l, p01l, 0x05040100u), W4, acc[m * 8 + 4], false);
;               acc[m * 8 + 5] = __builtin_amdgcn_sdot4((int)__builtin_amdgcn_perm(p23l, p01l, 0x07060302u), W4, acc[m * 8 + 5], false);
;               acc[m * 8 + 6] = __builtin_amdgcn_sdot4((int)__builtin_amdgcn_perm(p23h, p01h, 0x05040100u), W4, acc[m * 8 + 6], false);
;               acc[m * 8 + 7] = __builtin_amdgcn_sdot4((int)__builtin_amdgcn_perm(p23h, p01h, 0x07060302u), W4, acc[m * 8 + 7], false);
;             }
;           }
	v_dot4c_i32_i8_e32 v159, s1, v3
	v_and_b32_e32 v19, 0xf0f0f0f, v28
	v_and_b32_e32 v21, 0xf0f0f0f, v24
	v_and_b32_e32 v20, 0xf0f0f0f, v20
	v_and_b32_e32 v16, 0xf0f0f0f, v16
	v_perm_b32 v25, v12, v8, s52
	v_perm_b32 v26, v4, v0, s52
	v_dot4c_i32_i8_e32 v159, s2, v2
	v_and_b32_e32 v10, 0xf0f0f0f, v76
	v_and_b32_e32 v11, 0xf0f0f0f, v72
	v_and_b32_e32 v14, 0xf0f0f0f, v68
	v_and_b32_e32 v15, 0xf0f0f0f, v64
	v_perm_b32 v22, v19, v21, s52
	v_perm_b32 v23, v20, v16, s52
	v_perm_b32 v27, v25, v26, s54
	v_dot4c_i32_i8_e32 v159, s3, v1
	v_and_b32_e32 v1, 0xf0f0f0f, v92
	v_and_b32_e32 v2, 0xf0f0f0f, v88
	v_and_b32_e32 v5, 0xf0f0f0f, v84
	v_and_b32_e32 v6, 0xf0f0f0f, v80
	v_perm_b32 v13, v10, v11, s52
	v_perm_b32 v17, v14, v15, s52
	v_perm_b32 v24, v22, v23, s54
	v_dot4c_i32_i8_e32 v162, s0, v27
	v_perm_b32 v3, v1, v2, s52
	v_perm_b32 v7, v5, v6, s52
	v_perm_b32 v18, v13, v17, s54
	v_dot4c_i32_i8_e32 v162, s1, v24
	v_perm_b32 v9, v3, v7, s54
	v_dot4c_i32_i8_e32 v162, s2, v18
	v_perm_b32 v3, v3, v7, s53
	v_perm_b32 v7, v13, v17, s53
	v_perm_b32 v13, v25, v26, s53
	v_dot4c_i32_i8_e32 v162, s3, v9
	v_perm_b32 v9, v22, v23, s53
	v_dot4c_i32_i8_e32 v161, s0, v13
	v_perm_b32 v8, v12, v8, s33
	v_perm_b32 v0, v4, v0, s33
	v_dot4c_i32_i8_e32 v161, s1, v9
	v_perm_b32 v1, v1, v2, s33
	v_perm_b32 v2, v5, v6, s33
	v_perm_b32 v5, v10, v11, s33
	v_perm_b32 v9, v19, v21, s33
	v_perm_b32 v10, v20, v16, s33
	v_perm_b32 v4, v8, v0, s54
	v_perm_b32 v6, v14, v15, s33
	v_perm_b32 v11, v9, v10, s54
	v_dot4c_i32_i8_e32 v164, s0, v4
	v_dot4c_i32_i8_e32 v161, s2, v7
	v_perm_b32 v7, v5, v6, s54
	v_dot4c_i32_i8_e32 v164, s1, v11
	v_dot4c_i32_i8_e32 v161, s3, v3
	v_perm_b32 v3, v1, v2, s54
	v_dot4c_i32_i8_e32 v164, s2, v7
	v_perm_b32 v0, v8, v0, s53
	v_dot4c_i32_i8_e32 v164, s3, v3
	v_perm_b32 v3, v9, v10, s53
	v_dot4c_i32_i8_e32 v163, s0, v0
	v_perm_b32 v1, v1, v2, s53
	v_perm_b32 v2, v5, v6, s53
	v_dot4c_i32_i8_e32 v163, s1, v3
	v_dot4c_i32_i8_e32 v163, s2, v2
	s_waitcnt vmcnt(7)
	v_and_b32_e32 v0, 0xf0f0f0f, v60
	s_waitcnt vmcnt(6)
	v_and_b32_e32 v2, 0xf0f0f0f, v56
	s_waitcnt vmcnt(5)
	v_and_b32_e32 v4, 0xf0f0f0f, v52
	s_waitcnt vmcnt(4)
	v_and_b32_e32 v6, 0xf0f0f0f, v48
	v_perm_b32 v8, v2, v0, s33
	v_perm_b32 v0, v2, v0, s52
	v_perm_b32 v2, v6, v4, s33
	v_dot4c_i32_i8_e32 v163, s3, v1
	v_readlane_b32 s0, v170, 56
	v_lshrrev_b32_e32 v1, 4, v60
	v_lshrrev_b32_e32 v3, 4, v56
	v_lshrrev_b32_e32 v5, 4, v52
	v_lshrrev_b32_e32 v7, 4, v48
	v_perm_b32 v4, v6, v4, s52
	v_perm_b32 v6, v2, v8, s53
	v_perm_b32 v2, v2, v8, s54
	v_and_b32_e32 v1, 0xf0f0f0f, v1
	v_and_b32_e32 v3, 0xf0f0f0f, v3
	v_and_b32_e32 v5, 0xf0f0f0f, v5
	v_and_b32_e32 v7, 0xf0f0f0f, v7
	v_dot4c_i32_i8_e32 v164, s0, v2
	v_perm_b32 v2, v4, v0, s53
	v_perm_b32 v0, v4, v0, s54
	v_dot4c_i32_i8_e32 v161, s0, v2
	v_dot4c_i32_i8_e32 v162, s0, v0
	v_perm_b32 v0, v3, v1, s33
	v_perm_b32 v2, v7, v5, s33
	v_perm_b32 v1, v3, v1, s52
	v_perm_b32 v3, v7, v5, s52
	v_perm_b32 v4, v2, v0, s53
	v_perm_b32 v0, v2, v0, s54
	v_dot4c_i32_i8_e32 v160, s0, v0
	v_perm_b32 v0, v3, v1, s53
	v_dot4c_i32_i8_e32 v157, s0, v0
	v_perm_b32 v0, v3, v1, s54
	v_dot4c_i32_i8_e32 v163, s0, v6
	v_dot4c_i32_i8_e32 v159, s0, v4
	v_dot4c_i32_i8_e32 v158, s0, v0
	v_and_b32_e32 v0, 0xf0f0f0f, v61
	v_and_b32_e32 v2, 0xf0f0f0f, v57
	v_and_b32_e32 v4, 0xf0f0f0f, v53
	v_and_b32_e32 v6, 0xf0f0f0f, v49
	v_perm_b32 v8, v2, v0, s33
	v_perm_b32 v0, v2, v0, s52
	v_perm_b32 v2, v6, v4, s33
	v_lshrrev_b32_e32 v1, 4, v61
	v_lshrrev_b32_e32 v3, 4, v57
	v_lshrrev_b32_e32 v5, 4, v53
	v_lshrrev_b32_e32 v7, 4, v49
	v_perm_b32 v4, v6, v4, s52
	v_perm_b32 v6, v2, v8, s53
	v_perm_b32 v2, v2, v8, s54
	v_and_b32_e32 v1, 0xf0f0f0f, v1
	v_and_b32_e32 v3, 0xf0f0f0f, v3
	v_and_b32_e32 v5, 0xf0f0f0f, v5
	v_and_b32_e32 v7, 0xf0f0f0f, v7
	v_dot4c_i32_i8_e32 v154, s0, v2
	v_perm_b32 v2, v4, v0, s53
	v_perm_b32 v0, v4, v0, s54
	v_dot4c_i32_i8_e32 v149, s0, v2
	v_dot4c_i32_i8_e32 v150, s0, v0
	v_perm_b32 v0, v3, v1, s33
	v_perm_b32 v2, v7, v5, s33
	v_perm_b32 v1, v3, v1, s52
	v_perm_b32 v3, v7, v5, s52
	v_perm_b32 v4, v2, v0, s53
	v_perm_b32 v0, v2, v0, s54
	v_dot4c_i32_i8_e32 v146, s0, v0
	v_perm_b32 v0, v3, v1, s53
	v_dot4c_i32_i8_e32 v155, s0, v0
	v_perm_b32 v0, v3, v1, s54
	v_dot4c_i32_i8_e32 v152, s0, v6
	v_dot4c_i32_i8_e32 v144, s0, v4
	v_dot4c_i32_i8_e32 v156, s0, v0
	v_and_b32_e32 v0, 0xf0f0f0f, v62
	v_and_b32_e32 v2, 0xf0f0f0f, v58
	v_and_b32_e32 v4, 0xf0f0f0f, v54
	v_and_b32_e32 v6, 0xf0f0f0f, v50
	v_perm_b32 v8, v2, v0, s33
	v_perm_b32 v0, v2, v0, s52
	v_perm_b32 v2, v6, v4, s33
	v_lshrrev_b32_e32 v1, 4, v62
	v_lshrrev_b32_e32 v3, 4, v58
	v_lshrrev_b32_e32 v5, 4, v54
	v_lshrrev_b32_e32 v7, 4, v50
	v_perm_b32 v4, v6, v4, s52
	v_perm_b32 v6, v2, v8, s53
	v_perm_b32 v2, v2, v8, s54
	v_and_b32_e32 v1, 0xf0f0f0f, v1
	v_and_b32_e32 v3, 0xf0f0f0f, v3
	v_and_b32_e32 v5, 0xf0f0f0f, v5
	v_and_b32_e32 v7, 0xf0f0f0f, v7
	v_dot4c_i32_i8_e32 v153, s0, v2
	v_perm_b32 v2, v4, v0, s53
	v_perm_b32 v0, v4, v0, s54
	v_dot4c_i32_i8_e32 v147, s0, v2
	v_dot4c_i32_i8_e32 v148, s0, v0
	v_perm_b32 v0, v3, v1, s33
	v_perm_b32 v2, v7, v5, s33
	v_perm_b32 v1, v3, v1, s52
	v_perm_b32 v3, v7, v5, s52
	v_perm_b32 v4, v2, v0, s53
	v_perm_b32 v0, v2, v0, s54
	v_dot4c_i32_i8_e32 v145, s0, v0
	v_perm_b32 v0, v3, v1, s53
	v_dot4c_i32_i8_e32 v141, s0, v0
	v_perm_b32 v0, v3, v1, s54
	v_dot4c_i32_i8_e32 v151, s0, v6
	v_dot4c_i32_i8_e32 v143, s0, v4
	v_dot4c_i32_i8_e32 v142, s0, v0
	v_and_b32_e32 v0, 0xf0f0f0f, v63
	v_and_b32_e32 v2, 0xf0f0f0f, v59
	v_and_b32_e32 v4, 0xf0f0f0f, v55
	v_and_b32_e32 v6, 0xf0f0f0f, v51
	v_perm_b32 v8, v2, v0, s33
	v_perm_b32 v0, v2, v0, s52
	v_perm_b32 v2, v6, v4, s33
	v_lshrrev_b32_e32 v1, 4, v63
	v_lshrrev_b32_e32 v3, 4, v59
	v_lshrrev_b32_e32 v5, 4, v55
	v_lshrrev_b32_e32 v7, 4, v51
	v_perm_b32 v4, v6, v4, s52
	v_perm_b32 v6, v2, v8, s53
	v_perm_b32 v2, v2, v8, s54
	v_and_b32_e32 v1, 0xf0f0f0f, v1
	v_and_b32_e32 v3, 0xf0f0f0f, v3
	v_and_b32_e32 v5, 0xf0f0f0f, v5
	v_and_b32_e32 v7, 0xf0f0f0f, v7
	v_dot4c_i32_i8_e32 v140, s0, v2
	v_perm_b32 v2, v4, v0, s53
	v_perm_b32 v0, v4, v0, s54
	v_dot4c_i32_i8_e32 v137, s0, v2
	v_dot4c_i32_i8_e32 v139, s0, v0
	v_perm_b32 v0, v3, v1, s33
	v_perm_b32 v2, v7, v5, s33
	v_perm_b32 v1, v3, v1, s52
	v_perm_b32 v3, v7, v5, s52
	v_perm_b32 v4, v2, v0, s53
	v_perm_b32 v0, v2, v0, s54
	v_dot4c_i32_i8_e32 v135, s0, v0
	v_perm_b32 v0, v3, v1, s53
	v_dot4c_i32_i8_e32 v123, s0, v0
	v_perm_b32 v0, v3, v1, s54
	v_dot4c_i32_i8_e32 v136, s0, v6
	v_dot4c_i32_i8_e32 v134, s0, v4
	v_dot4c_i32_i8_e32 v125, s0, v0
	s_waitcnt vmcnt(3)
; __device__ void phase_gather(const Params& p) {
;     ...
; #pragma unroll
;         for (int sub = 0; sub < GROWS / 4; ++sub) {
;           const int W4 = __builtin_amdgcn_readlane(pkv, j0 + 4 * sub);
; #pragma unroll
;           for (int m = 0; m < 4; ++m) {
;             unsigned lo[4], hi[4];
; #pragma unroll
;             for (int k = 0; k < 4; ++k) {
;               const unsigned w = rr[gi % 3][sub * 4 + k][m];
;               lo[k] = w & 0x0f0f0f0fu;
;               hi[k] = (w >> 4) & 0x0f0f0f0fu;
;             }
;             {
;               const unsigned p01l = __builtin_amdgcn_perm(lo[1], lo[0], 0x05010400u), p01h = __builtin_amdgcn_perm(lo[1], lo[0], 0x07030602u);
;               const unsigned p23l = __builtin_amdgcn_perm(lo[3], lo[2], 0x05010400u), p23h = __builtin_amdgcn_perm(lo[3], lo[2], 0x07030602u);
;               acc[m * 8 + 0] = __builtin_amdgcn_sdot4((int)__builtin_amdgcn_perm(p23l, p01l, 0x05040100u), W4, acc[m * 8 + 0], false);
;               acc[m * 8 + 1] = __builtin_amdgcn_sdot4((int)__builtin_amdgcn_perm(p23l, p01l, 0x07060302u), W4, acc[m * 8 + 1], false);
;               acc[m * 8 + 2] = __builtin_amdgcn_sdot4((int)__builtin_amdgcn_perm(p23h, p01h, 0x05040100u), W4, acc[m * 8 + 2], false);
;               acc[m * 8 + 3] = __builtin_amdgcn_sdot4((int)__builtin_amdgcn_perm(p23h, p01h, 0x07060302u), W4, acc[m * 8 + 3], false);
;             }
;             {
;               const unsigned p01l = __builtin_amdgcn_perm(hi[1], hi[0], 0x05010400u), p01h = __builtin_amdgcn_perm(hi[1], hi[0], 0x07030602u);
;               const unsigned p23l = __builtin_amdgcn_perm(hi[3], hi[2], 0x05010400u), p23h = __builtin_amdgcn_perm(hi[3], hi[2], 0x07030602u);
;               acc[m * 8 + 4] = __builtin_amdgcn_sdot4((int)__builtin_amdgcn_perm(p23l, p01l, 0x05040100u), W4, acc[m * 8 + 4], false);
;               acc[m * 8 + 5] = __builtin_amdgcn_sdot4((int)__builtin_amdgcn_perm(p23l, p01l, 0x07060302u), W4, acc[m * 8 + 5], false);
;               acc[m * 8 + 6] = __builtin_amdgcn_sdot4((int)__builtin_amdgcn_perm(p23h, p01h, 0x05040100u), W4, acc[m * 8 + 6], false);
;               acc[m * 8 + 7] = __builtin_amdgcn_sdot4((int)__builtin_amdgcn_perm(p23h, p01h, 0x07060302u), W4, acc[m * 8 + 7], false);
;             }
;           }
;         }
;       }
	v_and_b32_e32 v0, 0xf0f0f0f, v44
	s_waitcnt vmcnt(2)
	v_and_b32_e32 v2, 0xf0f0f0f, v40
	s_waitcnt vmcnt(1)
	v_and_b32_e32 v4, 0xf0f0f0f, v36
	s_waitcnt vmcnt(0)
	v_and_b32_e32 v6, 0xf0f0f0f, v32
	v_perm_b32 v8, v2, v0, s33
	v_perm_b32 v0, v2, v0, s52
	v_perm_b32 v2, v6, v4, s33
	v_readlane_b32 s0, v170, 60
	v_lshrrev_b32_e32 v1, 4, v44
	v_lshrrev_b32_e32 v3, 4, v40
	v_lshrrev_b32_e32 v5, 4, v36
	v_lshrrev_b32_e32 v7, 4, v32
	v_perm_b32 v4, v6, v4, s52
	v_perm_b32 v6, v2, v8, s53
	v_perm_b32 v2, v2, v8, s54
	v_and_b32_e32 v1, 0xf0f0f0f, v1
	v_and_b32_e32 v3, 0xf0f0f0f, v3
	v_and_b32_e32 v5, 0xf0f0f0f, v5
	v_and_b32_e32 v7, 0xf0f0f0f, v7
	v_dot4c_i32_i8_e32 v164, s0, v2
	v_perm_b32 v2, v4, v0, s53
	v_perm_b32 v0, v4, v0, s54
	v_dot4c_i32_i8_e32 v161, s0, v2
	v_dot4c_i32_i8_e32 v162, s0, v0
	v_perm_b32 v0, v3, v1, s33
	v_perm_b32 v2, v7, v5, s33
	v_perm_b32 v1, v3, v1, s52
	v_perm_b32 v3, v7, v5, s52
	v_perm_b32 v4, v2, v0, s53
	v_perm_b32 v0, v2, v0, s54
	v_dot4c_i32_i8_e32 v160, s0, v0
	v_perm_b32 v0, v3, v1, s53
	v_dot4c_i32_i8_e32 v157, s0, v0
	v_perm_b32 v0, v3, v1, s54
	v_dot4c_i32_i8_e32 v163, s0, v6
	v_dot4c_i32_i8_e32 v159, s0, v4
	v_dot4c_i32_i8_e32 v158, s0, v0
	v_and_b32_e32 v0, 0xf0f0f0f, v45
	v_and_b32_e32 v2, 0xf0f0f0f, v41
	v_and_b32_e32 v4, 0xf0f0f0f, v37
	v_and_b32_e32 v6, 0xf0f0f0f, v33
	v_perm_b32 v8, v2, v0, s33
	v_perm_b32 v0, v2, v0, s52
	v_perm_b32 v2, v6, v4, s33
	v_lshrrev_b32_e32 v1, 4, v45
	v_lshrrev_b32_e32 v3, 4, v41
	v_lshrrev_b32_e32 v5, 4, v37
	v_lshrrev_b32_e32 v7, 4, v33
	v_perm_b32 v4, v6, v4, s52
	v_perm_b32 v6, v2, v8, s53
	v_perm_b32 v2, v2, v8, s54
	v_and_b32_e32 v1, 0xf0f0f0f, v1
	v_and_b32_e32 v3, 0xf0f0f0f, v3
	v_and_b32_e32 v5, 0xf0f0f0f, v5
	v_and_b32_e32 v7, 0xf0f0f0f, v7
	v_dot4c_i32_i8_e32 v154, s0, v2
	v_perm_b32 v2, v4, v0, s53
	v_perm_b32 v0, v4, v0, s54
	v_dot4c_i32_i8_e32 v149, s0, v2
	v_dot4c_i32_i8_e32 v150, s0, v0
	v_perm_b32 v0, v3, v1, s33
	v_perm_b32 v2, v7, v5, s33
	v_perm_b32 v1, v3, v1, s52
	v_perm_b32 v3, v7, v5, s52
	v_perm_b32 v4, v2, v0, s53
	v_perm_b32 v0, v2, v0, s54
	v_dot4c_i32_i8_e32 v146, s0, v0
	v_perm_b32 v0, v3, v1, s53
	v_dot4c_i32_i8_e32 v155, s0, v0
	v_perm_b32 v0, v3, v1, s54
	v_dot4c_i32_i8_e32 v152, s0, v6
	v_dot4c_i32_i8_e32 v144, s0, v4
	v_dot4c_i32_i8_e32 v156, s0, v0
	v_and_b32_e32 v0, 0xf0f0f0f, v46
	v_and_b32_e32 v2, 0xf0f0f0f, v42
	v_and_b32_e32 v4, 0xf0f0f0f, v38
	v_and_b32_e32 v6, 0xf0f0f0f, v34
	v_perm_b32 v8, v2, v0, s33
	v_perm_b32 v0, v2, v0, s52
	v_perm_b32 v2, v6, v4, s33
	v_lshrrev_b32_e32 v1, 4, v46
	v_lshrrev_b32_e32 v3, 4, v42
	v_lshrrev_b32_e32 v5, 4, v38
	v_lshrrev_b32_e32 v7, 4, v34
	v_perm_b32 v4, v6, v4, s52
	v_perm_b32 v6, v2, v8, s53
	v_perm_b32 v2, v2, v8, s54
	v_and_b32_e32 v1, 0xf0f0f0f, v1
	v_and_b32_e32 v3, 0xf0f0f0f, v3
	v_and_b32_e32 v5, 0xf0f0f0f, v5
	v_and_b32_e32 v7, 0xf0f0f0f, v7
	v_dot4c_i32_i8_e32 v153, s0, v2
	v_perm_b32 v2, v4, v0, s53
	v_perm_b32 v0, v4, v0, s54
	v_dot4c_i32_i8_e32 v147, s0, v2
	v_dot4c_i32_i8_e32 v148, s0, v0
	v_perm_b32 v0, v3, v1, s33
	v_perm_b32 v2, v7, v5, s33
	v_perm_b32 v1, v3, v1, s52
	v_perm_b32 v3, v7, v5, s52
	v_perm_b32 v4, v2, v0, s53
	v_perm_b32 v0, v2, v0, s54
	v_dot4c_i32_i8_e32 v145, s0, v0
	v_perm_b32 v0, v3, v1, s53
	v_dot4c_i32_i8_e32 v141, s0, v0
	v_perm_b32 v0, v3, v1, s54
	v_dot4c_i32_i8_e32 v151, s0, v6
	v_dot4c_i32_i8_e32 v142, s0, v0
	v_and_b32_e32 v0, 0xf0f0f0f, v47
	v_lshrrev_b32_e32 v1, 4, v47
	v_and_b32_e32 v5, 0xf0f0f0f, v43
	v_and_b32_e32 v6, 0xf0f0f0f, v39
	v_and_b32_e32 v7, 0xf0f0f0f, v35
	v_and_b32_e32 v2, 0xf0f0f0f, v1
	v_lshrrev_b32_e32 v1, 4, v43
	v_perm_b32 v8, v5, v0, s33
	v_perm_b32 v0, v5, v0, s52
	v_perm_b32 v5, v7, v6, s33
	v_dot4c_i32_i8_e32 v143, s0, v4
	v_and_b32_e32 v4, 0xf0f0f0f, v1
	v_lshrrev_b32_e32 v1, 4, v39
	v_lshrrev_b32_e32 v3, 4, v35
	v_perm_b32 v6, v7, v6, s52
	v_perm_b32 v7, v5, v8, s53
	v_perm_b32 v5, v5, v8, s54
	v_and_b32_e32 v1, 0xf0f0f0f, v1
	v_and_b32_e32 v3, 0xf0f0f0f, v3
	v_dot4c_i32_i8_e32 v140, s0, v5
	v_perm_b32 v5, v6, v0, s53
	v_perm_b32 v0, v6, v0, s54
	v_dot4c_i32_i8_e32 v139, s0, v0
	v_perm_b32 v0, v4, v2, s33
	v_perm_b32 v2, v4, v2, s52
	v_perm_b32 v4, v3, v1, s33
	v_perm_b32 v1, v3, v1, s52
	v_perm_b32 v3, v4, v0, s53
	v_perm_b32 v0, v4, v0, s54
	v_dot4c_i32_i8_e32 v135, s0, v0
	v_perm_b32 v0, v1, v2, s53
	v_dot4c_i32_i8_e32 v123, s0, v0
	v_perm_b32 v0, v1, v2, s54
	v_dot4c_i32_i8_e32 v136, s0, v7
	v_dot4c_i32_i8_e32 v137, s0, v5
	v_dot4c_i32_i8_e32 v134, s0, v3
	v_dot4c_i32_i8_e32 v125, s0, v0
	s_mov_b64 s[0:1], 0
	s_cbranch_vccz .LBB0_1321
; __device__ void phase_gather(const Params& p) {
;     ...
;     float val[32];
;     float ss = 0.f;
;     const int off8 = 8 * wsumq;
; #pragma unroll
;     for (int q = 0; q < 8; ++q) {
;       f32x4 v = *(const f32x4*)(orow + q * 4);
; #pragma unroll
;       for (int k = 0; k < 4; ++k) {
;         val[q * 4 + k] = sw * (float)(acc[q * 4 + k] - off8) + v[k];
;         ss += val[q * 4 + k] * val[q * 4 + k];
;       }
;     }
	v_lshlrev_b64 v[0:1], 13, v[112:113]
	v_lshl_add_u64 v[4:5], v[118:119], 0, v[0:1]
	global_load_dwordx4 v[6:9], v[4:5], off
	global_load_dwordx4 v[10:13], v[4:5], off offset:16
	global_load_dwordx4 v[14:17], v[4:5], off offset:32
	global_load_dwordx4 v[18:21], v[4:5], off offset:48
	global_load_dwordx4 v[22:25], v[4:5], off offset:64
	global_load_dwordx4 v[26:29], v[4:5], off offset:80
	global_load_dwordx4 v[0:3], v[120:121], off
	global_load_dwordx4 v[30:33], v[4:5], off offset:112
	global_load_dwordx4 v[34:37], v[4:5], off offset:96
	s_waitcnt lgkmcnt(0)
	v_add_lshl_u32 v39, v166, v167, 3
	v_sub_u32_e32 v40, v163, v39
	v_sub_u32_e32 v41, v164, v39
	v_sub_u32_e32 v42, v161, v39
	v_sub_u32_e32 v43, v162, v39
	v_cvt_f32_i32_e32 v41, v41
	v_cvt_f32_i32_e32 v40, v40
	v_cvt_f32_i32_e32 v43, v43
	v_cvt_f32_i32_e32 v42, v42
	v_sub_u32_e32 v44, v159, v39
	v_sub_u32_e32 v45, v160, v39
	v_mul_f32_e32 v38, 0x3c010204, v165
	v_cvt_f32_i32_e32 v45, v45
	v_cvt_f32_i32_e32 v44, v44
	v_sub_u32_e32 v46, v157, v39
	v_sub_u32_e32 v47, v158, v39
	v_cvt_f32_i32_e32 v47, v47
	v_cvt_f32_i32_e32 v46, v46
	v_sub_u32_e32 v48, v152, v39
	v_sub_u32_e32 v49, v154, v39
	v_cvt_f32_i32_e32 v49, v49
	v_cvt_f32_i32_e32 v48, v48
	v_sub_u32_e32 v50, v149, v39
	v_sub_u32_e32 v51, v150, v39
	v_cvt_f32_i32_e32 v51, v51
	v_cvt_f32_i32_e32 v50, v50
	v_sub_u32_e32 v52, v144, v39
	v_sub_u32_e32 v53, v146, v39
	v_cvt_f32_i32_e32 v53, v53
	v_cvt_f32_i32_e32 v52, v52
	v_sub_u32_e32 v54, v155, v39
	v_sub_u32_e32 v55, v156, v39
	v_cvt_f32_i32_e32 v55, v55
	v_cvt_f32_i32_e32 v54, v54
	v_sub_u32_e32 v56, v151, v39
	v_sub_u32_e32 v57, v153, v39
	v_cvt_f32_i32_e32 v57, v57
	v_cvt_f32_i32_e32 v56, v56
	v_sub_u32_e32 v58, v147, v39
	v_sub_u32_e32 v59, v148, v39
	v_sub_u32_e32 v62, v141, v39
	v_sub_u32_e32 v63, v142, v39
	v_cvt_f32_i32_e32 v59, v59
	v_cvt_f32_i32_e32 v58, v58
	v_sub_u32_e32 v60, v143, v39
	v_sub_u32_e32 v61, v145, v39
	v_cvt_f32_i32_e32 v63, v63
	v_cvt_f32_i32_e32 v62, v62
	v_cvt_f32_i32_e32 v61, v61
	v_cvt_f32_i32_e32 v60, v60
	v_sub_u32_e32 v64, v137, v39
	v_sub_u32_e32 v65, v139, v39
	v_cvt_f32_i32_e32 v65, v65
	v_cvt_f32_i32_e32 v64, v64
	v_sub_u32_e32 v68, v123, v39
	v_cvt_f32_i32_e32 v68, v68
	v_readlane_b32 s68, v250, 28
	s_movk_i32 s0, 0x3fff
	v_readlane_b32 s70, v250, 30
	v_add_u32_e32 v112, s68, v112
	v_readlane_b32 s71, v250, 31
	v_readlane_b32 s69, v250, 29
	s_waitcnt vmcnt(8)
	v_pk_fma_f32 v[6:7], v[38:39], v[40:41], v[6:7] op_sel_hi:[0,1,1]
	v_pk_fma_f32 v[8:9], v[38:39], v[42:43], v[8:9] op_sel_hi:[0,1,1]
	v_pk_mul_f32 v[40:41], v[6:7], v[6:7]
	v_pk_mul_f32 v[42:43], v[8:9], v[8:9]
	v_add_f32_e32 v40, v40, v41
	s_waitcnt vmcnt(7)
	v_pk_fma_f32 v[10:11], v[38:39], v[44:45], v[10:11] op_sel_hi:[0,1,1]
	v_add_f32_e32 v40, v42, v40
	v_pk_mul_f32 v[44:45], v[10:11], v[10:11]
	v_add_f32_e32 v40, v43, v40
	v_pk_fma_f32 v[12:13], v[38:39], v[46:47], v[12:13] op_sel_hi:[0,1,1]
	v_add_f32_e32 v40, v44, v40
	v_pk_mul_f32 v[46:47], v[12:13], v[12:13]
	v_add_f32_e32 v40, v45, v40
	s_waitcnt vmcnt(6)
	v_pk_fma_f32 v[14:15], v[38:39], v[48:49], v[14:15] op_sel_hi:[0,1,1]
	v_add_f32_e32 v40, v46, v40
	v_pk_mul_f32 v[48:49], v[14:15], v[14:15]
	v_add_f32_e32 v40, v47, v40
	v_pk_fma_f32 v[16:17], v[38:39], v[50:51], v[16:17] op_sel_hi:[0,1,1]
	v_add_f32_e32 v40, v48, v40
	v_pk_mul_f32 v[50:51], v[16:17], v[16:17]
	v_add_f32_e32 v40, v49, v40
	s_waitcnt vmcnt(5)
	v_pk_fma_f32 v[18:19], v[38:39], v[52:53], v[18:19] op_sel_hi:[0,1,1]
	v_add_f32_e32 v40, v50, v40
	v_pk_mul_f32 v[52:53], v[18:19], v[18:19]
	v_add_f32_e32 v40, v51, v40
	v_pk_fma_f32 v[20:21], v[38:39], v[54:55], v[20:21] op_sel_hi:[0,1,1]
	v_add_f32_e32 v40, v52, v40
	v_pk_mul_f32 v[54:55], v[20:21], v[20:21]
	v_add_f32_e32 v40, v53, v40
	s_waitcnt vmcnt(4)
	v_pk_fma_f32 v[22:23], v[38:39], v[56:57], v[22:23] op_sel_hi:[0,1,1]
	v_add_f32_e32 v40, v54, v40
	v_pk_mul_f32 v[56:57], v[22:23], v[22:23]
	v_add_f32_e32 v40, v55, v40
	v_pk_fma_f32 v[24:25], v[38:39], v[58:59], v[24:25] op_sel_hi:[0,1,1]
	v_add_f32_e32 v40, v56, v40
	s_waitcnt vmcnt(3)
; __device__ void phase_gather(const Params& p) {
;     ...
;     ss = wave_sum(ss);
;     const float rs3 = rsqrtf(ss * (1.f / 2048.f) + EPSV);
; #pragma unroll
;     for (int q = 0; q < 8; ++q) {
;       f32x4 wf = *(const f32x4*)(p.norm_final_w + lane * 32 + q * 4);
;       f32x4 o = {val[q * 4 + 0] * rs3 * wf[0], val[q * 4 + 1] * rs3 * wf[1], val[q * 4 + 2] * rs3 * wf[2],
;                  val[q * 4 + 3] * rs3 * wf[3]};
;       *(f32x4*)(orow + q * 4) = o;
;     }
	v_pk_fma_f32 v[28:29], v[38:39], v[62:63], v[28:29] op_sel_hi:[0,1,1]
	v_pk_mul_f32 v[58:59], v[24:25], v[24:25]
	v_sub_u32_e32 v62, v136, v39
	v_sub_u32_e32 v63, v140, v39
	v_add_f32_e32 v40, v57, v40
	v_pk_fma_f32 v[26:27], v[38:39], v[60:61], v[26:27] op_sel_hi:[0,1,1]
	v_cvt_f32_i32_e32 v63, v63
	v_cvt_f32_i32_e32 v62, v62
	v_add_f32_e32 v40, v58, v40
	v_pk_mul_f32 v[60:61], v[26:27], v[26:27]
	v_add_f32_e32 v40, v59, v40
	v_add_f32_e32 v40, v60, v40
	v_pk_mul_f32 v[66:67], v[28:29], v[28:29]
	s_waitcnt vmcnt(0)
	v_pk_fma_f32 v[36:37], v[38:39], v[64:65], v[36:37] op_sel_hi:[0,1,1]
	v_sub_u32_e32 v64, v134, v39
	v_sub_u32_e32 v65, v135, v39
	v_add_f32_e32 v40, v61, v40
	v_pk_fma_f32 v[34:35], v[38:39], v[62:63], v[34:35] op_sel_hi:[0,1,1]
	v_cvt_f32_i32_e32 v65, v65
	v_cvt_f32_i32_e32 v64, v64
	v_add_f32_e32 v40, v66, v40
	v_pk_mul_f32 v[62:63], v[34:35], v[34:35]
	v_sub_u32_e32 v39, v125, v39
	v_add_f32_e32 v40, v67, v40
	v_cvt_f32_i32_e32 v69, v39
	v_add_f32_e32 v40, v62, v40
	v_pk_mul_f32 v[70:71], v[36:37], v[36:37]
	v_add_f32_e32 v40, v63, v40
	v_pk_fma_f32 v[30:31], v[38:39], v[64:65], v[30:31] op_sel_hi:[0,1,1]
	v_add_f32_e32 v40, v70, v40
	v_pk_mul_f32 v[64:65], v[30:31], v[30:31]
	v_add_f32_e32 v40, v71, v40
	v_pk_fma_f32 v[32:33], v[38:39], v[68:69], v[32:33] op_sel_hi:[0,1,1]
	v_add_f32_e32 v40, v64, v40
	v_pk_mul_f32 v[38:39], v[32:33], v[32:33]
	v_add_f32_e32 v40, v65, v40
	v_add_f32_e32 v38, v38, v40
	v_add_f32_e32 v38, v39, v38
	ds_bpermute_b32 v39, v126, v38
	s_waitcnt lgkmcnt(0)
	v_add_f32_e32 v38, v38, v39
	ds_bpermute_b32 v39, v127, v38
	s_waitcnt lgkmcnt(0)
	v_add_f32_e32 v38, v38, v39
	ds_bpermute_b32 v39, v128, v38
	s_waitcnt lgkmcnt(0)
	v_add_f32_e32 v38, v38, v39
	ds_bpermute_b32 v39, v129, v38
	s_waitcnt lgkmcnt(0)
	v_add_f32_e32 v38, v38, v39
	ds_bpermute_b32 v39, v130, v38
	s_waitcnt lgkmcnt(0)
	v_add_f32_e32 v38, v38, v39
	ds_bpermute_b32 v39, v131, v38
	s_waitcnt lgkmcnt(0)
	v_add_f32_e32 v38, v38, v39
	v_fmamk_f32 v38, v38, 0x3a000000, v133
	v_mul_f32_e32 v39, 0x4b800000, v38
	v_cmp_gt_f32_e32 vcc, s55, v38
	s_nop 1
	v_cndmask_b32_e32 v38, v38, v39, vcc
	v_rsq_f32_e32 v38, v38
	s_nop 0
	v_mul_f32_e32 v39, 0x45800000, v38
	v_cndmask_b32_e32 v38, v38, v39, vcc
	v_pk_mul_f32 v[6:7], v[6:7], v[38:39] op_sel_hi:[1,0]
	v_pk_mul_f32 v[8:9], v[8:9], v[38:39] op_sel_hi:[1,0]
	v_pk_mul_f32 v[0:1], v[0:1], v[6:7]
	v_pk_mul_f32 v[2:3], v[2:3], v[8:9]
	global_store_dwordx4 v[4:5], v[0:3], off
	v_pk_mul_f32 v[6:7], v[12:13], v[38:39] op_sel_hi:[1,0]
	v_pk_mul_f32 v[8:9], v[10:11], v[38:39] op_sel_hi:[1,0]
	v_cmp_lt_i32_e32 vcc, s0, v112
	v_readlane_b32 s0, v250, 32
	v_readlane_b32 s1, v250, 33
	s_or_b64 s[0:1], vcc, s[0:1]
	v_pk_mul_f32 v[0:1], v[188:189], v[8:9]
	v_pk_mul_f32 v[2:3], v[190:191], v[6:7]
	global_store_dwordx4 v[4:5], v[0:3], off offset:16
	v_pk_mul_f32 v[6:7], v[16:17], v[38:39] op_sel_hi:[1,0]
	v_pk_mul_f32 v[8:9], v[14:15], v[38:39] op_sel_hi:[1,0]
	v_pk_mul_f32 v[2:3], v[194:195], v[6:7]
	v_pk_mul_f32 v[0:1], v[192:193], v[8:9]
	global_store_dwordx4 v[4:5], v[0:3], off offset:32
	v_pk_mul_f32 v[6:7], v[20:21], v[38:39] op_sel_hi:[1,0]
	v_pk_mul_f32 v[8:9], v[18:19], v[38:39] op_sel_hi:[1,0]
	v_pk_mul_f32 v[2:3], v[198:199], v[6:7]
	v_pk_mul_f32 v[0:1], v[196:197], v[8:9]
	global_store_dwordx4 v[4:5], v[0:3], off offset:48
	v_pk_mul_f32 v[6:7], v[24:25], v[38:39] op_sel_hi:[1,0]
	v_pk_mul_f32 v[8:9], v[22:23], v[38:39] op_sel_hi:[1,0]
	v_pk_mul_f32 v[2:3], v[202:203], v[6:7]
	v_pk_mul_f32 v[0:1], v[200:201], v[8:9]
	global_store_dwordx4 v[4:5], v[0:3], off offset:64
	v_pk_mul_f32 v[6:7], v[28:29], v[38:39] op_sel_hi:[1,0]
	v_pk_mul_f32 v[8:9], v[26:27], v[38:39] op_sel_hi:[1,0]
	v_pk_mul_f32 v[2:3], v[206:207], v[6:7]
	v_pk_mul_f32 v[0:1], v[204:205], v[8:9]
	global_store_dwordx4 v[4:5], v[0:3], off offset:80
	v_pk_mul_f32 v[6:7], v[36:37], v[38:39] op_sel_hi:[1,0]
	v_pk_mul_f32 v[8:9], v[34:35], v[38:39] op_sel_hi:[1,0]
	v_pk_mul_f32 v[2:3], v[210:211], v[6:7]
	v_pk_mul_f32 v[0:1], v[208:209], v[8:9]
	global_store_dwordx4 v[4:5], v[0:3], off offset:96
	v_pk_mul_f32 v[6:7], v[32:33], v[38:39] op_sel_hi:[1,0]
	v_pk_mul_f32 v[8:9], v[30:31], v[38:39] op_sel_hi:[1,0]
	v_pk_mul_f32 v[2:3], v[214:215], v[6:7]
	v_pk_mul_f32 v[0:1], v[212:213], v[8:9]
	global_store_dwordx4 v[4:5], v[0:3], off offset:112
	s_andn2_b64 exec, exec, s[0:1]
	s_cbranch_execnz .LBB0_1318
